# FF2 owner epilogue pre-pass now covers all 16 row groups (last row included)
# speedup vs baseline: 1.0041x; 1.0027x over previous
.Lfq_LBB0_1423:
	v_lshlrev_b32_e32 v203, 12, v204
	v_lshl_add_u32 v203, v200, 2, v203
	v_lshlrev_b32_e32 v205, 2, v194
	s_cmp_eq_u32 s30, 1
	s_cbranch_scc1 .Lfq_np1
	s_cmp_eq_u32 s30, 2
	s_cbranch_scc1 .Lfq_np2
	s_add_u32 s42, s62, 0x0
	s_addc_u32 s43, s63, 0
	global_load_dwordx4 v[160:163], v205, s[42:43] sc0 sc1
	s_add_u32 s98, s62, 0x1000
	s_addc_u32 s99, s63, 0
	global_load_dwordx4 v[164:167], v205, s[98:99] sc0 sc1
	s_add_u32 s42, s62, 0x400
	s_addc_u32 s43, s63, 0
	global_load_dwordx4 v[168:171], v205, s[42:43] sc0 sc1
	s_add_u32 s98, s62, 0x1400
	s_addc_u32 s99, s63, 0
	global_load_dwordx4 v[172:175], v205, s[98:99] sc0 sc1
	s_add_u32 s42, s62, 0x800
	s_addc_u32 s43, s63, 0
	global_load_dwordx4 v[176:179], v205, s[42:43] sc0 sc1
	s_add_u32 s98, s62, 0x1800
	s_addc_u32 s99, s63, 0
	global_load_dwordx4 v[180:183], v205, s[98:99] sc0 sc1
	s_add_u32 s42, s62, 0xc00
	s_addc_u32 s43, s63, 0
	global_load_dwordx4 v[206:209], v205, s[42:43] sc0 sc1
	s_add_u32 s98, s62, 0x1c00
	s_addc_u32 s99, s63, 0
	global_load_dwordx4 v[210:213], v205, s[98:99] sc0 sc1
	s_add_u32 s42, s62, 0x2000
	s_addc_u32 s43, s63, 0
	global_load_dwordx4 v[236:239], v205, s[42:43] sc0 sc1
	s_waitcnt vmcnt(8)
	v_lshlrev_b32_e32 v240, 16, v160
	v_and_b32_e32 v241, 0xffff0000, v160
	v_pk_add_f32 v[124:125], v[124:125], v[240:241]
	v_lshlrev_b32_e32 v240, 16, v161
	v_and_b32_e32 v241, 0xffff0000, v161
	v_pk_add_f32 v[126:127], v[126:127], v[240:241]
	v_lshlrev_b32_e32 v240, 16, v162
	v_and_b32_e32 v241, 0xffff0000, v162
	v_pk_add_f32 v[120:121], v[120:121], v[240:241]
	v_lshlrev_b32_e32 v240, 16, v163
	v_and_b32_e32 v241, 0xffff0000, v163
	v_pk_add_f32 v[122:123], v[122:123], v[240:241]
	s_add_u32 s98, s62, 0x3000
	s_addc_u32 s99, s63, 0
	global_load_dwordx4 v[160:163], v205, s[98:99] sc0 sc1
	s_waitcnt vmcnt(8)
	v_lshlrev_b32_e32 v240, 16, v164
	v_and_b32_e32 v241, 0xffff0000, v164
	v_pk_add_f32 v[92:93], v[92:93], v[240:241]
	v_lshlrev_b32_e32 v240, 16, v165
	v_and_b32_e32 v241, 0xffff0000, v165
	v_pk_add_f32 v[94:95], v[94:95], v[240:241]
	v_lshlrev_b32_e32 v240, 16, v166
	v_and_b32_e32 v241, 0xffff0000, v166
	v_pk_add_f32 v[88:89], v[88:89], v[240:241]
	v_lshlrev_b32_e32 v240, 16, v167
	v_and_b32_e32 v241, 0xffff0000, v167
	v_pk_add_f32 v[90:91], v[90:91], v[240:241]
	s_add_u32 s42, s62, 0x2400
	s_addc_u32 s43, s63, 0
	global_load_dwordx4 v[164:167], v205, s[42:43] sc0 sc1
	s_waitcnt vmcnt(8)
	v_lshlrev_b32_e32 v240, 16, v168
	v_and_b32_e32 v241, 0xffff0000, v168
	v_pk_add_f32 v[116:117], v[116:117], v[240:241]
	v_lshlrev_b32_e32 v240, 16, v169
	v_and_b32_e32 v241, 0xffff0000, v169
	v_pk_add_f32 v[118:119], v[118:119], v[240:241]
	v_lshlrev_b32_e32 v240, 16, v170
	v_and_b32_e32 v241, 0xffff0000, v170
	v_pk_add_f32 v[112:113], v[112:113], v[240:241]
	v_lshlrev_b32_e32 v240, 16, v171
	v_and_b32_e32 v241, 0xffff0000, v171
	v_pk_add_f32 v[114:115], v[114:115], v[240:241]
	s_add_u32 s98, s62, 0x3400
	s_addc_u32 s99, s63, 0
	global_load_dwordx4 v[168:171], v205, s[98:99] sc0 sc1
	s_waitcnt vmcnt(8)
	v_lshlrev_b32_e32 v240, 16, v172
	v_and_b32_e32 v241, 0xffff0000, v172
	v_pk_add_f32 v[84:85], v[84:85], v[240:241]
	v_lshlrev_b32_e32 v240, 16, v173
	v_and_b32_e32 v241, 0xffff0000, v173
	v_pk_add_f32 v[86:87], v[86:87], v[240:241]
	v_lshlrev_b32_e32 v240, 16, v174
	v_and_b32_e32 v241, 0xffff0000, v174
	v_pk_add_f32 v[80:81], v[80:81], v[240:241]
	v_lshlrev_b32_e32 v240, 16, v175
	v_and_b32_e32 v241, 0xffff0000, v175
	v_pk_add_f32 v[82:83], v[82:83], v[240:241]
	s_add_u32 s42, s62, 0x2800
	s_addc_u32 s43, s63, 0
	global_load_dwordx4 v[172:175], v205, s[42:43] sc0 sc1
	s_waitcnt vmcnt(8)
	v_lshlrev_b32_e32 v240, 16, v176
	v_and_b32_e32 v241, 0xffff0000, v176
	v_pk_add_f32 v[108:109], v[108:109], v[240:241]
	v_lshlrev_b32_e32 v240, 16, v177
	v_and_b32_e32 v241, 0xffff0000, v177
	v_pk_add_f32 v[110:111], v[110:111], v[240:241]
	v_lshlrev_b32_e32 v240, 16, v178
	v_and_b32_e32 v241, 0xffff0000, v178
	v_pk_add_f32 v[104:105], v[104:105], v[240:241]
	v_lshlrev_b32_e32 v240, 16, v179
	v_and_b32_e32 v241, 0xffff0000, v179
	v_pk_add_f32 v[106:107], v[106:107], v[240:241]
	s_add_u32 s98, s62, 0x3800
	s_addc_u32 s99, s63, 0
	global_load_dwordx4 v[176:179], v205, s[98:99] sc0 sc1
	s_waitcnt vmcnt(8)
	v_lshlrev_b32_e32 v240, 16, v180
	v_and_b32_e32 v241, 0xffff0000, v180
	v_pk_add_f32 v[76:77], v[76:77], v[240:241]
	v_lshlrev_b32_e32 v240, 16, v181
	v_and_b32_e32 v241, 0xffff0000, v181
	v_pk_add_f32 v[78:79], v[78:79], v[240:241]
	v_lshlrev_b32_e32 v240, 16, v182
	v_and_b32_e32 v241, 0xffff0000, v182
	v_pk_add_f32 v[72:73], v[72:73], v[240:241]
	v_lshlrev_b32_e32 v240, 16, v183
	v_and_b32_e32 v241, 0xffff0000, v183
	v_pk_add_f32 v[74:75], v[74:75], v[240:241]
	s_add_u32 s42, s62, 0x2c00
	s_addc_u32 s43, s63, 0
	global_load_dwordx4 v[180:183], v205, s[42:43] sc0 sc1
	s_waitcnt vmcnt(8)
	v_lshlrev_b32_e32 v240, 16, v206
	v_and_b32_e32 v241, 0xffff0000, v206
	v_pk_add_f32 v[100:101], v[100:101], v[240:241]
	v_lshlrev_b32_e32 v240, 16, v207
	v_and_b32_e32 v241, 0xffff0000, v207
	v_pk_add_f32 v[102:103], v[102:103], v[240:241]
	v_lshlrev_b32_e32 v240, 16, v208
	v_and_b32_e32 v241, 0xffff0000, v208
	v_pk_add_f32 v[96:97], v[96:97], v[240:241]
	v_lshlrev_b32_e32 v240, 16, v209
	v_and_b32_e32 v241, 0xffff0000, v209
	v_pk_add_f32 v[98:99], v[98:99], v[240:241]
	s_add_u32 s98, s62, 0x3c00
	s_addc_u32 s99, s63, 0
	global_load_dwordx4 v[206:209], v205, s[98:99] sc0 sc1
	s_waitcnt vmcnt(8)
	v_lshlrev_b32_e32 v240, 16, v210
	v_and_b32_e32 v241, 0xffff0000, v210
	v_pk_add_f32 v[68:69], v[68:69], v[240:241]
	v_lshlrev_b32_e32 v240, 16, v211
	v_and_b32_e32 v241, 0xffff0000, v211
	v_pk_add_f32 v[70:71], v[70:71], v[240:241]
	v_lshlrev_b32_e32 v240, 16, v212
	v_and_b32_e32 v241, 0xffff0000, v212
	v_pk_add_f32 v[64:65], v[64:65], v[240:241]
	v_lshlrev_b32_e32 v240, 16, v213
	v_and_b32_e32 v241, 0xffff0000, v213
	v_pk_add_f32 v[66:67], v[66:67], v[240:241]
	s_add_u32 s42, s62, 0x20000
	s_addc_u32 s43, s63, 0
	global_load_dwordx4 v[210:213], v205, s[42:43] sc0 sc1
	s_waitcnt vmcnt(8)
	v_lshlrev_b32_e32 v240, 16, v236
	v_and_b32_e32 v241, 0xffff0000, v236
	v_pk_add_f32 v[60:61], v[60:61], v[240:241]
	v_lshlrev_b32_e32 v240, 16, v237
	v_and_b32_e32 v241, 0xffff0000, v237
	v_pk_add_f32 v[62:63], v[62:63], v[240:241]
	v_lshlrev_b32_e32 v240, 16, v238
	v_and_b32_e32 v241, 0xffff0000, v238
	v_pk_add_f32 v[56:57], v[56:57], v[240:241]
	v_lshlrev_b32_e32 v240, 16, v239
	v_and_b32_e32 v241, 0xffff0000, v239
	v_pk_add_f32 v[58:59], v[58:59], v[240:241]
	s_add_u32 s98, s62, 0x21000
	s_addc_u32 s99, s63, 0
	global_load_dwordx4 v[236:239], v205, s[98:99] sc0 sc1
	s_waitcnt vmcnt(8)
	v_lshlrev_b32_e32 v240, 16, v160
	v_and_b32_e32 v241, 0xffff0000, v160
	v_pk_add_f32 v[28:29], v[28:29], v[240:241]
	v_lshlrev_b32_e32 v240, 16, v161
	v_and_b32_e32 v241, 0xffff0000, v161
	v_pk_add_f32 v[30:31], v[30:31], v[240:241]
	v_lshlrev_b32_e32 v240, 16, v162
	v_and_b32_e32 v241, 0xffff0000, v162
	v_pk_add_f32 v[24:25], v[24:25], v[240:241]
	v_lshlrev_b32_e32 v240, 16, v163
	v_and_b32_e32 v241, 0xffff0000, v163
	v_pk_add_f32 v[26:27], v[26:27], v[240:241]
	s_add_u32 s42, s62, 0x20400
	s_addc_u32 s43, s63, 0
	global_load_dwordx4 v[160:163], v205, s[42:43] sc0 sc1
	s_waitcnt vmcnt(8)
	v_lshlrev_b32_e32 v240, 16, v164
	v_and_b32_e32 v241, 0xffff0000, v164
	v_pk_add_f32 v[52:53], v[52:53], v[240:241]
	v_lshlrev_b32_e32 v240, 16, v165
	v_and_b32_e32 v241, 0xffff0000, v165
	v_pk_add_f32 v[54:55], v[54:55], v[240:241]
	v_lshlrev_b32_e32 v240, 16, v166
	v_and_b32_e32 v241, 0xffff0000, v166
	v_pk_add_f32 v[48:49], v[48:49], v[240:241]
	v_lshlrev_b32_e32 v240, 16, v167
	v_and_b32_e32 v241, 0xffff0000, v167
	v_pk_add_f32 v[50:51], v[50:51], v[240:241]
	s_add_u32 s98, s62, 0x21400
	s_addc_u32 s99, s63, 0
	global_load_dwordx4 v[164:167], v205, s[98:99] sc0 sc1
	s_waitcnt vmcnt(8)
	v_lshlrev_b32_e32 v240, 16, v168
	v_and_b32_e32 v241, 0xffff0000, v168
	v_pk_add_f32 v[20:21], v[20:21], v[240:241]
	v_lshlrev_b32_e32 v240, 16, v169
	v_and_b32_e32 v241, 0xffff0000, v169
	v_pk_add_f32 v[22:23], v[22:23], v[240:241]
	v_lshlrev_b32_e32 v240, 16, v170
	v_and_b32_e32 v241, 0xffff0000, v170
	v_pk_add_f32 v[16:17], v[16:17], v[240:241]
	v_lshlrev_b32_e32 v240, 16, v171
	v_and_b32_e32 v241, 0xffff0000, v171
	v_pk_add_f32 v[18:19], v[18:19], v[240:241]
	s_add_u32 s42, s62, 0x20800
	s_addc_u32 s43, s63, 0
	global_load_dwordx4 v[168:171], v205, s[42:43] sc0 sc1
	s_waitcnt vmcnt(8)
	v_lshlrev_b32_e32 v240, 16, v172
	v_and_b32_e32 v241, 0xffff0000, v172
	v_pk_add_f32 v[44:45], v[44:45], v[240:241]
	v_lshlrev_b32_e32 v240, 16, v173
	v_and_b32_e32 v241, 0xffff0000, v173
	v_pk_add_f32 v[46:47], v[46:47], v[240:241]
	v_lshlrev_b32_e32 v240, 16, v174
	v_and_b32_e32 v241, 0xffff0000, v174
	v_pk_add_f32 v[40:41], v[40:41], v[240:241]
	v_lshlrev_b32_e32 v240, 16, v175
	v_and_b32_e32 v241, 0xffff0000, v175
	v_pk_add_f32 v[42:43], v[42:43], v[240:241]
	s_add_u32 s98, s62, 0x21800
	s_addc_u32 s99, s63, 0
	global_load_dwordx4 v[172:175], v205, s[98:99] sc0 sc1
	s_waitcnt vmcnt(8)
	v_lshlrev_b32_e32 v240, 16, v176
	v_and_b32_e32 v241, 0xffff0000, v176
	v_pk_add_f32 v[12:13], v[12:13], v[240:241]
	v_lshlrev_b32_e32 v240, 16, v177
	v_and_b32_e32 v241, 0xffff0000, v177
	v_pk_add_f32 v[14:15], v[14:15], v[240:241]
	v_lshlrev_b32_e32 v240, 16, v178
	v_and_b32_e32 v241, 0xffff0000, v178
	v_pk_add_f32 v[8:9], v[8:9], v[240:241]
	v_lshlrev_b32_e32 v240, 16, v179
	v_and_b32_e32 v241, 0xffff0000, v179
	v_pk_add_f32 v[10:11], v[10:11], v[240:241]
	s_add_u32 s42, s62, 0x20c00
	s_addc_u32 s43, s63, 0
	global_load_dwordx4 v[176:179], v205, s[42:43] sc0 sc1
	s_waitcnt vmcnt(8)
	v_lshlrev_b32_e32 v240, 16, v180
	v_and_b32_e32 v241, 0xffff0000, v180
	v_pk_add_f32 v[36:37], v[36:37], v[240:241]
	v_lshlrev_b32_e32 v240, 16, v181
	v_and_b32_e32 v241, 0xffff0000, v181
	v_pk_add_f32 v[38:39], v[38:39], v[240:241]
	v_lshlrev_b32_e32 v240, 16, v182
	v_and_b32_e32 v241, 0xffff0000, v182
	v_pk_add_f32 v[32:33], v[32:33], v[240:241]
	v_lshlrev_b32_e32 v240, 16, v183
	v_and_b32_e32 v241, 0xffff0000, v183
	v_pk_add_f32 v[34:35], v[34:35], v[240:241]
	s_add_u32 s98, s62, 0x21c00
	s_addc_u32 s99, s63, 0
	global_load_dwordx4 v[180:183], v205, s[98:99] sc0 sc1
	s_waitcnt vmcnt(8)
	v_lshlrev_b32_e32 v240, 16, v206
	v_and_b32_e32 v241, 0xffff0000, v206
	v_pk_add_f32 v[4:5], v[4:5], v[240:241]
	v_lshlrev_b32_e32 v240, 16, v207
	v_and_b32_e32 v241, 0xffff0000, v207
	v_pk_add_f32 v[6:7], v[6:7], v[240:241]
	v_lshlrev_b32_e32 v240, 16, v208
	v_and_b32_e32 v241, 0xffff0000, v208
	v_pk_add_f32 v[0:1], v[0:1], v[240:241]
	v_lshlrev_b32_e32 v240, 16, v209
	v_and_b32_e32 v241, 0xffff0000, v209
	v_pk_add_f32 v[2:3], v[2:3], v[240:241]
	s_add_u32 s42, s62, 0x22000
	s_addc_u32 s43, s63, 0
	global_load_dwordx4 v[206:209], v205, s[42:43] sc0 sc1
	s_waitcnt vmcnt(8)
	v_lshlrev_b32_e32 v240, 16, v210
	v_and_b32_e32 v241, 0xffff0000, v210
	v_pk_add_f32 v[124:125], v[124:125], v[240:241]
	v_lshlrev_b32_e32 v240, 16, v211
	v_and_b32_e32 v241, 0xffff0000, v211
	v_pk_add_f32 v[126:127], v[126:127], v[240:241]
	v_lshlrev_b32_e32 v240, 16, v212
	v_and_b32_e32 v241, 0xffff0000, v212
	v_pk_add_f32 v[120:121], v[120:121], v[240:241]
	v_lshlrev_b32_e32 v240, 16, v213
	v_and_b32_e32 v241, 0xffff0000, v213
	v_pk_add_f32 v[122:123], v[122:123], v[240:241]
	s_add_u32 s98, s62, 0x23000
	s_addc_u32 s99, s63, 0
	global_load_dwordx4 v[210:213], v205, s[98:99] sc0 sc1
	s_waitcnt vmcnt(8)
	v_lshlrev_b32_e32 v240, 16, v236
	v_and_b32_e32 v241, 0xffff0000, v236
	v_pk_add_f32 v[92:93], v[92:93], v[240:241]
	v_lshlrev_b32_e32 v240, 16, v237
	v_and_b32_e32 v241, 0xffff0000, v237
	v_pk_add_f32 v[94:95], v[94:95], v[240:241]
	v_lshlrev_b32_e32 v240, 16, v238
	v_and_b32_e32 v241, 0xffff0000, v238
	v_pk_add_f32 v[88:89], v[88:89], v[240:241]
	v_lshlrev_b32_e32 v240, 16, v239
	v_and_b32_e32 v241, 0xffff0000, v239
	v_pk_add_f32 v[90:91], v[90:91], v[240:241]
	s_add_u32 s42, s62, 0x22400
	s_addc_u32 s43, s63, 0
	global_load_dwordx4 v[236:239], v205, s[42:43] sc0 sc1
	s_waitcnt vmcnt(8)
	v_lshlrev_b32_e32 v240, 16, v160
	v_and_b32_e32 v241, 0xffff0000, v160
	v_pk_add_f32 v[116:117], v[116:117], v[240:241]
	v_lshlrev_b32_e32 v240, 16, v161
	v_and_b32_e32 v241, 0xffff0000, v161
	v_pk_add_f32 v[118:119], v[118:119], v[240:241]
	v_lshlrev_b32_e32 v240, 16, v162
	v_and_b32_e32 v241, 0xffff0000, v162
	v_pk_add_f32 v[112:113], v[112:113], v[240:241]
	v_lshlrev_b32_e32 v240, 16, v163
	v_and_b32_e32 v241, 0xffff0000, v163
	v_pk_add_f32 v[114:115], v[114:115], v[240:241]
	s_add_u32 s98, s62, 0x23400
	s_addc_u32 s99, s63, 0
	global_load_dwordx4 v[160:163], v205, s[98:99] sc0 sc1
	s_waitcnt vmcnt(8)
	v_lshlrev_b32_e32 v240, 16, v164
	v_and_b32_e32 v241, 0xffff0000, v164
	v_pk_add_f32 v[84:85], v[84:85], v[240:241]
	v_lshlrev_b32_e32 v240, 16, v165
	v_and_b32_e32 v241, 0xffff0000, v165
	v_pk_add_f32 v[86:87], v[86:87], v[240:241]
	v_lshlrev_b32_e32 v240, 16, v166
	v_and_b32_e32 v241, 0xffff0000, v166
	v_pk_add_f32 v[80:81], v[80:81], v[240:241]
	v_lshlrev_b32_e32 v240, 16, v167
	v_and_b32_e32 v241, 0xffff0000, v167
	v_pk_add_f32 v[82:83], v[82:83], v[240:241]
	s_add_u32 s42, s62, 0x22800
	s_addc_u32 s43, s63, 0
	global_load_dwordx4 v[164:167], v205, s[42:43] sc0 sc1
	s_waitcnt vmcnt(8)
	v_lshlrev_b32_e32 v240, 16, v168
	v_and_b32_e32 v241, 0xffff0000, v168
	v_pk_add_f32 v[108:109], v[108:109], v[240:241]
	v_lshlrev_b32_e32 v240, 16, v169
	v_and_b32_e32 v241, 0xffff0000, v169
	v_pk_add_f32 v[110:111], v[110:111], v[240:241]
	v_lshlrev_b32_e32 v240, 16, v170
	v_and_b32_e32 v241, 0xffff0000, v170
	v_pk_add_f32 v[104:105], v[104:105], v[240:241]
	v_lshlrev_b32_e32 v240, 16, v171
	v_and_b32_e32 v241, 0xffff0000, v171
	v_pk_add_f32 v[106:107], v[106:107], v[240:241]
	s_add_u32 s98, s62, 0x23800
	s_addc_u32 s99, s63, 0
	global_load_dwordx4 v[168:171], v205, s[98:99] sc0 sc1
	s_waitcnt vmcnt(8)
	v_lshlrev_b32_e32 v240, 16, v172
	v_and_b32_e32 v241, 0xffff0000, v172
	v_pk_add_f32 v[76:77], v[76:77], v[240:241]
	v_lshlrev_b32_e32 v240, 16, v173
	v_and_b32_e32 v241, 0xffff0000, v173
	v_pk_add_f32 v[78:79], v[78:79], v[240:241]
	v_lshlrev_b32_e32 v240, 16, v174
	v_and_b32_e32 v241, 0xffff0000, v174
	v_pk_add_f32 v[72:73], v[72:73], v[240:241]
	v_lshlrev_b32_e32 v240, 16, v175
	v_and_b32_e32 v241, 0xffff0000, v175
	v_pk_add_f32 v[74:75], v[74:75], v[240:241]
	s_add_u32 s42, s62, 0x22c00
	s_addc_u32 s43, s63, 0
	global_load_dwordx4 v[172:175], v205, s[42:43] sc0 sc1
	s_waitcnt vmcnt(8)
	v_lshlrev_b32_e32 v240, 16, v176
	v_and_b32_e32 v241, 0xffff0000, v176
	v_pk_add_f32 v[100:101], v[100:101], v[240:241]
	v_lshlrev_b32_e32 v240, 16, v177
	v_and_b32_e32 v241, 0xffff0000, v177
	v_pk_add_f32 v[102:103], v[102:103], v[240:241]
	v_lshlrev_b32_e32 v240, 16, v178
	v_and_b32_e32 v241, 0xffff0000, v178
	v_pk_add_f32 v[96:97], v[96:97], v[240:241]
	v_lshlrev_b32_e32 v240, 16, v179
	v_and_b32_e32 v241, 0xffff0000, v179
	v_pk_add_f32 v[98:99], v[98:99], v[240:241]
	s_add_u32 s98, s62, 0x23c00
	s_addc_u32 s99, s63, 0
	global_load_dwordx4 v[176:179], v205, s[98:99] sc0 sc1
	s_waitcnt vmcnt(8)
	v_lshlrev_b32_e32 v240, 16, v180
	v_and_b32_e32 v241, 0xffff0000, v180
	v_pk_add_f32 v[68:69], v[68:69], v[240:241]
	v_lshlrev_b32_e32 v240, 16, v181
	v_and_b32_e32 v241, 0xffff0000, v181
	v_pk_add_f32 v[70:71], v[70:71], v[240:241]
	v_lshlrev_b32_e32 v240, 16, v182
	v_and_b32_e32 v241, 0xffff0000, v182
	v_pk_add_f32 v[64:65], v[64:65], v[240:241]
	v_lshlrev_b32_e32 v240, 16, v183
	v_and_b32_e32 v241, 0xffff0000, v183
	v_pk_add_f32 v[66:67], v[66:67], v[240:241]
	s_add_u32 s42, s62, 0x40000
	s_addc_u32 s43, s63, 0
	global_load_dwordx4 v[180:183], v205, s[42:43] sc0 sc1
	s_waitcnt vmcnt(8)
	v_lshlrev_b32_e32 v240, 16, v206
	v_and_b32_e32 v241, 0xffff0000, v206
	v_pk_add_f32 v[60:61], v[60:61], v[240:241]
	v_lshlrev_b32_e32 v240, 16, v207
	v_and_b32_e32 v241, 0xffff0000, v207
	v_pk_add_f32 v[62:63], v[62:63], v[240:241]
	v_lshlrev_b32_e32 v240, 16, v208
	v_and_b32_e32 v241, 0xffff0000, v208
	v_pk_add_f32 v[56:57], v[56:57], v[240:241]
	v_lshlrev_b32_e32 v240, 16, v209
	v_and_b32_e32 v241, 0xffff0000, v209
	v_pk_add_f32 v[58:59], v[58:59], v[240:241]
	s_add_u32 s98, s62, 0x41000
	s_addc_u32 s99, s63, 0
	global_load_dwordx4 v[206:209], v205, s[98:99] sc0 sc1
	s_waitcnt vmcnt(8)
	v_lshlrev_b32_e32 v240, 16, v210
	v_and_b32_e32 v241, 0xffff0000, v210
	v_pk_add_f32 v[28:29], v[28:29], v[240:241]
	v_lshlrev_b32_e32 v240, 16, v211
	v_and_b32_e32 v241, 0xffff0000, v211
	v_pk_add_f32 v[30:31], v[30:31], v[240:241]
	v_lshlrev_b32_e32 v240, 16, v212
	v_and_b32_e32 v241, 0xffff0000, v212
	v_pk_add_f32 v[24:25], v[24:25], v[240:241]
	v_lshlrev_b32_e32 v240, 16, v213
	v_and_b32_e32 v241, 0xffff0000, v213
	v_pk_add_f32 v[26:27], v[26:27], v[240:241]
	s_add_u32 s42, s62, 0x40400
	s_addc_u32 s43, s63, 0
	global_load_dwordx4 v[210:213], v205, s[42:43] sc0 sc1
	s_waitcnt vmcnt(8)
	v_lshlrev_b32_e32 v240, 16, v236
	v_and_b32_e32 v241, 0xffff0000, v236
	v_pk_add_f32 v[52:53], v[52:53], v[240:241]
	v_lshlrev_b32_e32 v240, 16, v237
	v_and_b32_e32 v241, 0xffff0000, v237
	v_pk_add_f32 v[54:55], v[54:55], v[240:241]
	v_lshlrev_b32_e32 v240, 16, v238
	v_and_b32_e32 v241, 0xffff0000, v238
	v_pk_add_f32 v[48:49], v[48:49], v[240:241]
	v_lshlrev_b32_e32 v240, 16, v239
	v_and_b32_e32 v241, 0xffff0000, v239
	v_pk_add_f32 v[50:51], v[50:51], v[240:241]
	s_add_u32 s98, s62, 0x41400
	s_addc_u32 s99, s63, 0
	global_load_dwordx4 v[236:239], v205, s[98:99] sc0 sc1
	s_waitcnt vmcnt(8)
	v_lshlrev_b32_e32 v240, 16, v160
	v_and_b32_e32 v241, 0xffff0000, v160
	v_pk_add_f32 v[20:21], v[20:21], v[240:241]
	v_lshlrev_b32_e32 v240, 16, v161
	v_and_b32_e32 v241, 0xffff0000, v161
	v_pk_add_f32 v[22:23], v[22:23], v[240:241]
	v_lshlrev_b32_e32 v240, 16, v162
	v_and_b32_e32 v241, 0xffff0000, v162
	v_pk_add_f32 v[16:17], v[16:17], v[240:241]
	v_lshlrev_b32_e32 v240, 16, v163
	v_and_b32_e32 v241, 0xffff0000, v163
	v_pk_add_f32 v[18:19], v[18:19], v[240:241]
	s_add_u32 s42, s62, 0x40800
	s_addc_u32 s43, s63, 0
	global_load_dwordx4 v[160:163], v205, s[42:43] sc0 sc1
	s_waitcnt vmcnt(8)
	v_lshlrev_b32_e32 v240, 16, v164
	v_and_b32_e32 v241, 0xffff0000, v164
	v_pk_add_f32 v[44:45], v[44:45], v[240:241]
	v_lshlrev_b32_e32 v240, 16, v165
	v_and_b32_e32 v241, 0xffff0000, v165
	v_pk_add_f32 v[46:47], v[46:47], v[240:241]
	v_lshlrev_b32_e32 v240, 16, v166
	v_and_b32_e32 v241, 0xffff0000, v166
	v_pk_add_f32 v[40:41], v[40:41], v[240:241]
	v_lshlrev_b32_e32 v240, 16, v167
	v_and_b32_e32 v241, 0xffff0000, v167
	v_pk_add_f32 v[42:43], v[42:43], v[240:241]
	s_add_u32 s98, s62, 0x41800
	s_addc_u32 s99, s63, 0
	global_load_dwordx4 v[164:167], v205, s[98:99] sc0 sc1
	s_waitcnt vmcnt(8)
	v_lshlrev_b32_e32 v240, 16, v168
	v_and_b32_e32 v241, 0xffff0000, v168
	v_pk_add_f32 v[12:13], v[12:13], v[240:241]
	v_lshlrev_b32_e32 v240, 16, v169
	v_and_b32_e32 v241, 0xffff0000, v169
	v_pk_add_f32 v[14:15], v[14:15], v[240:241]
	v_lshlrev_b32_e32 v240, 16, v170
	v_and_b32_e32 v241, 0xffff0000, v170
	v_pk_add_f32 v[8:9], v[8:9], v[240:241]
	v_lshlrev_b32_e32 v240, 16, v171
	v_and_b32_e32 v241, 0xffff0000, v171
	v_pk_add_f32 v[10:11], v[10:11], v[240:241]
	s_add_u32 s42, s62, 0x40c00
	s_addc_u32 s43, s63, 0
	global_load_dwordx4 v[168:171], v205, s[42:43] sc0 sc1
	s_waitcnt vmcnt(8)
	v_lshlrev_b32_e32 v240, 16, v172
	v_and_b32_e32 v241, 0xffff0000, v172
	v_pk_add_f32 v[36:37], v[36:37], v[240:241]
	v_lshlrev_b32_e32 v240, 16, v173
	v_and_b32_e32 v241, 0xffff0000, v173
	v_pk_add_f32 v[38:39], v[38:39], v[240:241]
	v_lshlrev_b32_e32 v240, 16, v174
	v_and_b32_e32 v241, 0xffff0000, v174
	v_pk_add_f32 v[32:33], v[32:33], v[240:241]
	v_lshlrev_b32_e32 v240, 16, v175
	v_and_b32_e32 v241, 0xffff0000, v175
	v_pk_add_f32 v[34:35], v[34:35], v[240:241]
	s_add_u32 s98, s62, 0x41c00
	s_addc_u32 s99, s63, 0
	global_load_dwordx4 v[172:175], v205, s[98:99] sc0 sc1
	s_waitcnt vmcnt(8)
	v_lshlrev_b32_e32 v240, 16, v176
	v_and_b32_e32 v241, 0xffff0000, v176
	v_pk_add_f32 v[4:5], v[4:5], v[240:241]
	v_lshlrev_b32_e32 v240, 16, v177
	v_and_b32_e32 v241, 0xffff0000, v177
	v_pk_add_f32 v[6:7], v[6:7], v[240:241]
	v_lshlrev_b32_e32 v240, 16, v178
	v_and_b32_e32 v241, 0xffff0000, v178
	v_pk_add_f32 v[0:1], v[0:1], v[240:241]
	v_lshlrev_b32_e32 v240, 16, v179
	v_and_b32_e32 v241, 0xffff0000, v179
	v_pk_add_f32 v[2:3], v[2:3], v[240:241]
	s_add_u32 s42, s62, 0x42000
	s_addc_u32 s43, s63, 0
	global_load_dwordx4 v[176:179], v205, s[42:43] sc0 sc1
	s_waitcnt vmcnt(8)
	v_lshlrev_b32_e32 v240, 16, v180
	v_and_b32_e32 v241, 0xffff0000, v180
	v_pk_add_f32 v[124:125], v[124:125], v[240:241]
	v_lshlrev_b32_e32 v240, 16, v181
	v_and_b32_e32 v241, 0xffff0000, v181
	v_pk_add_f32 v[126:127], v[126:127], v[240:241]
	v_lshlrev_b32_e32 v240, 16, v182
	v_and_b32_e32 v241, 0xffff0000, v182
	v_pk_add_f32 v[120:121], v[120:121], v[240:241]
	v_lshlrev_b32_e32 v240, 16, v183
	v_and_b32_e32 v241, 0xffff0000, v183
	v_pk_add_f32 v[122:123], v[122:123], v[240:241]
	s_add_u32 s98, s62, 0x43000
	s_addc_u32 s99, s63, 0
	global_load_dwordx4 v[180:183], v205, s[98:99] sc0 sc1
	s_waitcnt vmcnt(8)
	v_lshlrev_b32_e32 v240, 16, v206
	v_and_b32_e32 v241, 0xffff0000, v206
	v_pk_add_f32 v[92:93], v[92:93], v[240:241]
	v_lshlrev_b32_e32 v240, 16, v207
	v_and_b32_e32 v241, 0xffff0000, v207
	v_pk_add_f32 v[94:95], v[94:95], v[240:241]
	v_lshlrev_b32_e32 v240, 16, v208
	v_and_b32_e32 v241, 0xffff0000, v208
	v_pk_add_f32 v[88:89], v[88:89], v[240:241]
	v_lshlrev_b32_e32 v240, 16, v209
	v_and_b32_e32 v241, 0xffff0000, v209
	v_pk_add_f32 v[90:91], v[90:91], v[240:241]
	s_add_u32 s42, s62, 0x42400
	s_addc_u32 s43, s63, 0
	global_load_dwordx4 v[206:209], v205, s[42:43] sc0 sc1
	s_waitcnt vmcnt(8)
	v_lshlrev_b32_e32 v240, 16, v210
	v_and_b32_e32 v241, 0xffff0000, v210
	v_pk_add_f32 v[116:117], v[116:117], v[240:241]
	v_lshlrev_b32_e32 v240, 16, v211
	v_and_b32_e32 v241, 0xffff0000, v211
	v_pk_add_f32 v[118:119], v[118:119], v[240:241]
	v_lshlrev_b32_e32 v240, 16, v212
	v_and_b32_e32 v241, 0xffff0000, v212
	v_pk_add_f32 v[112:113], v[112:113], v[240:241]
	v_lshlrev_b32_e32 v240, 16, v213
	v_and_b32_e32 v241, 0xffff0000, v213
	v_pk_add_f32 v[114:115], v[114:115], v[240:241]
	s_add_u32 s98, s62, 0x43400
	s_addc_u32 s99, s63, 0
	global_load_dwordx4 v[210:213], v205, s[98:99] sc0 sc1
	s_waitcnt vmcnt(8)
	v_lshlrev_b32_e32 v240, 16, v236
	v_and_b32_e32 v241, 0xffff0000, v236
	v_pk_add_f32 v[84:85], v[84:85], v[240:241]
	v_lshlrev_b32_e32 v240, 16, v237
	v_and_b32_e32 v241, 0xffff0000, v237
	v_pk_add_f32 v[86:87], v[86:87], v[240:241]
	v_lshlrev_b32_e32 v240, 16, v238
	v_and_b32_e32 v241, 0xffff0000, v238
	v_pk_add_f32 v[80:81], v[80:81], v[240:241]
	v_lshlrev_b32_e32 v240, 16, v239
	v_and_b32_e32 v241, 0xffff0000, v239
	v_pk_add_f32 v[82:83], v[82:83], v[240:241]
	s_add_u32 s42, s62, 0x42800
	s_addc_u32 s43, s63, 0
	global_load_dwordx4 v[236:239], v205, s[42:43] sc0 sc1
	s_waitcnt vmcnt(8)
	v_lshlrev_b32_e32 v240, 16, v160
	v_and_b32_e32 v241, 0xffff0000, v160
	v_pk_add_f32 v[108:109], v[108:109], v[240:241]
	v_lshlrev_b32_e32 v240, 16, v161
	v_and_b32_e32 v241, 0xffff0000, v161
	v_pk_add_f32 v[110:111], v[110:111], v[240:241]
	v_lshlrev_b32_e32 v240, 16, v162
	v_and_b32_e32 v241, 0xffff0000, v162
	v_pk_add_f32 v[104:105], v[104:105], v[240:241]
	v_lshlrev_b32_e32 v240, 16, v163
	v_and_b32_e32 v241, 0xffff0000, v163
	v_pk_add_f32 v[106:107], v[106:107], v[240:241]
	s_add_u32 s98, s62, 0x43800
	s_addc_u32 s99, s63, 0
	global_load_dwordx4 v[160:163], v205, s[98:99] sc0 sc1
	s_waitcnt vmcnt(8)
	v_lshlrev_b32_e32 v240, 16, v164
	v_and_b32_e32 v241, 0xffff0000, v164
	v_pk_add_f32 v[76:77], v[76:77], v[240:241]
	v_lshlrev_b32_e32 v240, 16, v165
	v_and_b32_e32 v241, 0xffff0000, v165
	v_pk_add_f32 v[78:79], v[78:79], v[240:241]
	v_lshlrev_b32_e32 v240, 16, v166
	v_and_b32_e32 v241, 0xffff0000, v166
	v_pk_add_f32 v[72:73], v[72:73], v[240:241]
	v_lshlrev_b32_e32 v240, 16, v167
	v_and_b32_e32 v241, 0xffff0000, v167
	v_pk_add_f32 v[74:75], v[74:75], v[240:241]
	s_add_u32 s42, s62, 0x42c00
	s_addc_u32 s43, s63, 0
	global_load_dwordx4 v[164:167], v205, s[42:43] sc0 sc1
	s_waitcnt vmcnt(8)
	v_lshlrev_b32_e32 v240, 16, v168
	v_and_b32_e32 v241, 0xffff0000, v168
	v_pk_add_f32 v[100:101], v[100:101], v[240:241]
	v_lshlrev_b32_e32 v240, 16, v169
	v_and_b32_e32 v241, 0xffff0000, v169
	v_pk_add_f32 v[102:103], v[102:103], v[240:241]
	v_lshlrev_b32_e32 v240, 16, v170
	v_and_b32_e32 v241, 0xffff0000, v170
	v_pk_add_f32 v[96:97], v[96:97], v[240:241]
	v_lshlrev_b32_e32 v240, 16, v171
	v_and_b32_e32 v241, 0xffff0000, v171
	v_pk_add_f32 v[98:99], v[98:99], v[240:241]
	s_add_u32 s98, s62, 0x43c00
	s_addc_u32 s99, s63, 0
	global_load_dwordx4 v[168:171], v205, s[98:99] sc0 sc1
	s_waitcnt vmcnt(8)
	v_lshlrev_b32_e32 v240, 16, v172
	v_and_b32_e32 v241, 0xffff0000, v172
	v_pk_add_f32 v[68:69], v[68:69], v[240:241]
	v_lshlrev_b32_e32 v240, 16, v173
	v_and_b32_e32 v241, 0xffff0000, v173
	v_pk_add_f32 v[70:71], v[70:71], v[240:241]
	v_lshlrev_b32_e32 v240, 16, v174
	v_and_b32_e32 v241, 0xffff0000, v174
	v_pk_add_f32 v[64:65], v[64:65], v[240:241]
	v_lshlrev_b32_e32 v240, 16, v175
	v_and_b32_e32 v241, 0xffff0000, v175
	v_pk_add_f32 v[66:67], v[66:67], v[240:241]
	s_add_u32 s42, s10, 0x0
	s_addc_u32 s43, s11, 0
	global_load_dwordx4 v[172:175], v203, s[42:43]
	s_waitcnt vmcnt(8)
	v_lshlrev_b32_e32 v240, 16, v176
	v_and_b32_e32 v241, 0xffff0000, v176
	v_pk_add_f32 v[60:61], v[60:61], v[240:241]
	v_lshlrev_b32_e32 v240, 16, v177
	v_and_b32_e32 v241, 0xffff0000, v177
	v_pk_add_f32 v[62:63], v[62:63], v[240:241]
	v_lshlrev_b32_e32 v240, 16, v178
	v_and_b32_e32 v241, 0xffff0000, v178
	v_pk_add_f32 v[56:57], v[56:57], v[240:241]
	v_lshlrev_b32_e32 v240, 16, v179
	v_and_b32_e32 v241, 0xffff0000, v179
	v_pk_add_f32 v[58:59], v[58:59], v[240:241]
	s_add_u32 s98, s10, 0x0
	s_addc_u32 s99, s11, 0
	global_load_dwordx4 v[176:179], v203, s[98:99] offset:16
	s_waitcnt vmcnt(8)
	v_lshlrev_b32_e32 v240, 16, v180
	v_and_b32_e32 v241, 0xffff0000, v180
	v_pk_add_f32 v[28:29], v[28:29], v[240:241]
	v_lshlrev_b32_e32 v240, 16, v181
	v_and_b32_e32 v241, 0xffff0000, v181
	v_pk_add_f32 v[30:31], v[30:31], v[240:241]
	v_lshlrev_b32_e32 v240, 16, v182
	v_and_b32_e32 v241, 0xffff0000, v182
	v_pk_add_f32 v[24:25], v[24:25], v[240:241]
	v_lshlrev_b32_e32 v240, 16, v183
	v_and_b32_e32 v241, 0xffff0000, v183
	v_pk_add_f32 v[26:27], v[26:27], v[240:241]
	s_add_u32 s42, s10, 0x200
	s_addc_u32 s43, s11, 0
	global_load_dwordx4 v[180:183], v203, s[42:43]
	s_waitcnt vmcnt(8)
	v_lshlrev_b32_e32 v240, 16, v206
	v_and_b32_e32 v241, 0xffff0000, v206
	v_pk_add_f32 v[52:53], v[52:53], v[240:241]
	v_lshlrev_b32_e32 v240, 16, v207
	v_and_b32_e32 v241, 0xffff0000, v207
	v_pk_add_f32 v[54:55], v[54:55], v[240:241]
	v_lshlrev_b32_e32 v240, 16, v208
	v_and_b32_e32 v241, 0xffff0000, v208
	v_pk_add_f32 v[48:49], v[48:49], v[240:241]
	v_lshlrev_b32_e32 v240, 16, v209
	v_and_b32_e32 v241, 0xffff0000, v209
	v_pk_add_f32 v[50:51], v[50:51], v[240:241]
	s_add_u32 s98, s10, 0x200
	s_addc_u32 s99, s11, 0
	global_load_dwordx4 v[206:209], v203, s[98:99] offset:16
	s_waitcnt vmcnt(8)
	v_lshlrev_b32_e32 v240, 16, v210
	v_and_b32_e32 v241, 0xffff0000, v210
	v_pk_add_f32 v[20:21], v[20:21], v[240:241]
	v_lshlrev_b32_e32 v240, 16, v211
	v_and_b32_e32 v241, 0xffff0000, v211
	v_pk_add_f32 v[22:23], v[22:23], v[240:241]
	v_lshlrev_b32_e32 v240, 16, v212
	v_and_b32_e32 v241, 0xffff0000, v212
	v_pk_add_f32 v[16:17], v[16:17], v[240:241]
	v_lshlrev_b32_e32 v240, 16, v213
	v_and_b32_e32 v241, 0xffff0000, v213
	v_pk_add_f32 v[18:19], v[18:19], v[240:241]
	s_add_u32 s42, s10, 0x10000
	s_addc_u32 s43, s11, 0
	global_load_dwordx4 v[210:213], v203, s[42:43]
	s_waitcnt vmcnt(8)
	v_lshlrev_b32_e32 v240, 16, v236
	v_and_b32_e32 v241, 0xffff0000, v236
	v_pk_add_f32 v[44:45], v[44:45], v[240:241]
	v_lshlrev_b32_e32 v240, 16, v237
	v_and_b32_e32 v241, 0xffff0000, v237
	v_pk_add_f32 v[46:47], v[46:47], v[240:241]
	v_lshlrev_b32_e32 v240, 16, v238
	v_and_b32_e32 v241, 0xffff0000, v238
	v_pk_add_f32 v[40:41], v[40:41], v[240:241]
	v_lshlrev_b32_e32 v240, 16, v239
	v_and_b32_e32 v241, 0xffff0000, v239
	v_pk_add_f32 v[42:43], v[42:43], v[240:241]
	s_add_u32 s98, s10, 0x10000
	s_addc_u32 s99, s11, 0
	global_load_dwordx4 v[236:239], v203, s[98:99] offset:16
	s_waitcnt vmcnt(8)
	v_lshlrev_b32_e32 v240, 16, v160
	v_and_b32_e32 v241, 0xffff0000, v160
	v_pk_add_f32 v[12:13], v[12:13], v[240:241]
	v_lshlrev_b32_e32 v240, 16, v161
	v_and_b32_e32 v241, 0xffff0000, v161
	v_pk_add_f32 v[14:15], v[14:15], v[240:241]
	v_lshlrev_b32_e32 v240, 16, v162
	v_and_b32_e32 v241, 0xffff0000, v162
	v_pk_add_f32 v[8:9], v[8:9], v[240:241]
	v_lshlrev_b32_e32 v240, 16, v163
	v_and_b32_e32 v241, 0xffff0000, v163
	v_pk_add_f32 v[10:11], v[10:11], v[240:241]
	s_add_u32 s42, s10, 0x10200
	s_addc_u32 s43, s11, 0
	global_load_dwordx4 v[160:163], v203, s[42:43]
	s_waitcnt vmcnt(8)
	v_lshlrev_b32_e32 v240, 16, v164
	v_and_b32_e32 v241, 0xffff0000, v164
	v_pk_add_f32 v[36:37], v[36:37], v[240:241]
	v_lshlrev_b32_e32 v240, 16, v165
	v_and_b32_e32 v241, 0xffff0000, v165
	v_pk_add_f32 v[38:39], v[38:39], v[240:241]
	v_lshlrev_b32_e32 v240, 16, v166
	v_and_b32_e32 v241, 0xffff0000, v166
	v_pk_add_f32 v[32:33], v[32:33], v[240:241]
	v_lshlrev_b32_e32 v240, 16, v167
	v_and_b32_e32 v241, 0xffff0000, v167
	v_pk_add_f32 v[34:35], v[34:35], v[240:241]
	s_add_u32 s98, s10, 0x10200
	s_addc_u32 s99, s11, 0
	global_load_dwordx4 v[164:167], v203, s[98:99] offset:16
	s_waitcnt vmcnt(8)
	v_lshlrev_b32_e32 v240, 16, v168
	v_and_b32_e32 v241, 0xffff0000, v168
	v_pk_add_f32 v[4:5], v[4:5], v[240:241]
	v_lshlrev_b32_e32 v240, 16, v169
	v_and_b32_e32 v241, 0xffff0000, v169
	v_pk_add_f32 v[6:7], v[6:7], v[240:241]
	v_lshlrev_b32_e32 v240, 16, v170
	v_and_b32_e32 v241, 0xffff0000, v170
	v_pk_add_f32 v[0:1], v[0:1], v[240:241]
	v_lshlrev_b32_e32 v240, 16, v171
	v_and_b32_e32 v241, 0xffff0000, v171
	v_pk_add_f32 v[2:3], v[2:3], v[240:241]
	s_add_u32 s42, s10, 0x20000
	s_addc_u32 s43, s11, 0
	global_load_dwordx4 v[168:171], v203, s[42:43]
	s_waitcnt vmcnt(8)
	v_pk_fma_f32 v[124:125], v[148:149], v[124:125], v[172:173]
	v_pk_fma_f32 v[126:127], v[150:151], v[126:127], v[174:175]
	s_add_u32 s98, s10, 0x0
	s_addc_u32 s99, s11, 0
	global_store_dwordx4 v203, v[124:127], s[98:99]
	s_add_u32 s42, s10, 0x20000
	s_addc_u32 s43, s11, 0
	global_load_dwordx4 v[172:175], v203, s[42:43] offset:16
	s_waitcnt vmcnt(9)
	v_pk_fma_f32 v[120:121], v[144:145], v[120:121], v[176:177]
	v_pk_fma_f32 v[122:123], v[146:147], v[122:123], v[178:179]
	s_add_u32 s98, s10, 0x0
	s_addc_u32 s99, s11, 0
	global_store_dwordx4 v203, v[120:123], s[98:99] offset:16
	s_add_u32 s42, s10, 0x20200
	s_addc_u32 s43, s11, 0
	global_load_dwordx4 v[176:179], v203, s[42:43]
	s_waitcnt vmcnt(10)
	v_pk_fma_f32 v[92:93], v[156:157], v[92:93], v[180:181]
	v_pk_fma_f32 v[94:95], v[158:159], v[94:95], v[182:183]
	s_add_u32 s98, s10, 0x200
	s_addc_u32 s99, s11, 0
	global_store_dwordx4 v203, v[92:95], s[98:99]
	s_add_u32 s42, s10, 0x20200
	s_addc_u32 s43, s11, 0
	global_load_dwordx4 v[180:183], v203, s[42:43] offset:16
	s_waitcnt vmcnt(11)
	v_pk_fma_f32 v[88:89], v[152:153], v[88:89], v[206:207]
	v_pk_fma_f32 v[90:91], v[154:155], v[90:91], v[208:209]
	s_add_u32 s98, s10, 0x200
	s_addc_u32 s99, s11, 0
	global_store_dwordx4 v203, v[88:91], s[98:99] offset:16
	s_add_u32 s42, s10, 0x30000
	s_addc_u32 s43, s11, 0
	global_load_dwordx4 v[206:209], v203, s[42:43]
	s_waitcnt vmcnt(12)
	v_pk_fma_f32 v[116:117], v[148:149], v[116:117], v[210:211]
	v_pk_fma_f32 v[118:119], v[150:151], v[118:119], v[212:213]
	s_add_u32 s98, s10, 0x10000
	s_addc_u32 s99, s11, 0
	global_store_dwordx4 v203, v[116:119], s[98:99]
	s_add_u32 s42, s10, 0x30000
	s_addc_u32 s43, s11, 0
	global_load_dwordx4 v[210:213], v203, s[42:43] offset:16
	s_waitcnt vmcnt(13)
	v_pk_fma_f32 v[112:113], v[144:145], v[112:113], v[236:237]
	v_pk_fma_f32 v[114:115], v[146:147], v[114:115], v[238:239]
	s_add_u32 s98, s10, 0x10000
	s_addc_u32 s99, s11, 0
	global_store_dwordx4 v203, v[112:115], s[98:99] offset:16
	s_add_u32 s42, s10, 0x30200
	s_addc_u32 s43, s11, 0
	global_load_dwordx4 v[236:239], v203, s[42:43]
	s_waitcnt vmcnt(14)
	v_pk_fma_f32 v[84:85], v[156:157], v[84:85], v[160:161]
	v_pk_fma_f32 v[86:87], v[158:159], v[86:87], v[162:163]
	s_add_u32 s98, s10, 0x10200
	s_addc_u32 s99, s11, 0
	global_store_dwordx4 v203, v[84:87], s[98:99]
	s_add_u32 s42, s10, 0x30200
	s_addc_u32 s43, s11, 0
	global_load_dwordx4 v[160:163], v203, s[42:43] offset:16
	s_waitcnt vmcnt(15)
	v_pk_fma_f32 v[80:81], v[152:153], v[80:81], v[164:165]
	v_pk_fma_f32 v[82:83], v[154:155], v[82:83], v[166:167]
	s_add_u32 s98, s10, 0x10200
	s_addc_u32 s99, s11, 0
	global_store_dwordx4 v203, v[80:83], s[98:99] offset:16
	s_add_u32 s42, s10, 0x80000
	s_addc_u32 s43, s11, 0
	global_load_dwordx4 v[164:167], v203, s[42:43]
	s_waitcnt vmcnt(16)
	v_pk_fma_f32 v[108:109], v[148:149], v[108:109], v[168:169]
	v_pk_fma_f32 v[110:111], v[150:151], v[110:111], v[170:171]
	s_add_u32 s98, s10, 0x20000
	s_addc_u32 s99, s11, 0
	global_store_dwordx4 v203, v[108:111], s[98:99]
	s_add_u32 s42, s10, 0x80000
	s_addc_u32 s43, s11, 0
	global_load_dwordx4 v[168:171], v203, s[42:43] offset:16
	s_waitcnt vmcnt(16)
	v_pk_fma_f32 v[104:105], v[144:145], v[104:105], v[172:173]
	v_pk_fma_f32 v[106:107], v[146:147], v[106:107], v[174:175]
	s_add_u32 s98, s10, 0x20000
	s_addc_u32 s99, s11, 0
	global_store_dwordx4 v203, v[104:107], s[98:99] offset:16
	s_add_u32 s42, s10, 0x80200
	s_addc_u32 s43, s11, 0
	global_load_dwordx4 v[172:175], v203, s[42:43]
	s_waitcnt vmcnt(16)
	v_pk_fma_f32 v[76:77], v[156:157], v[76:77], v[176:177]
	v_pk_fma_f32 v[78:79], v[158:159], v[78:79], v[178:179]
	s_add_u32 s98, s10, 0x20200
	s_addc_u32 s99, s11, 0
	global_store_dwordx4 v203, v[76:79], s[98:99]
	s_add_u32 s42, s10, 0x80200
	s_addc_u32 s43, s11, 0
	global_load_dwordx4 v[176:179], v203, s[42:43] offset:16
	s_waitcnt vmcnt(16)
	v_pk_fma_f32 v[72:73], v[152:153], v[72:73], v[180:181]
	v_pk_fma_f32 v[74:75], v[154:155], v[74:75], v[182:183]
	s_add_u32 s98, s10, 0x20200
	s_addc_u32 s99, s11, 0
	global_store_dwordx4 v203, v[72:75], s[98:99] offset:16
	s_add_u32 s42, s10, 0x90000
	s_addc_u32 s43, s11, 0
	global_load_dwordx4 v[180:183], v203, s[42:43]
	s_waitcnt vmcnt(16)
	v_pk_fma_f32 v[100:101], v[148:149], v[100:101], v[206:207]
	v_pk_fma_f32 v[102:103], v[150:151], v[102:103], v[208:209]
	s_add_u32 s98, s10, 0x30000
	s_addc_u32 s99, s11, 0
	global_store_dwordx4 v203, v[100:103], s[98:99]
	s_add_u32 s42, s10, 0x90000
	s_addc_u32 s43, s11, 0
	global_load_dwordx4 v[206:209], v203, s[42:43] offset:16
	s_waitcnt vmcnt(16)
	v_pk_fma_f32 v[96:97], v[144:145], v[96:97], v[210:211]
	v_pk_fma_f32 v[98:99], v[146:147], v[98:99], v[212:213]
	s_add_u32 s98, s10, 0x30000
	s_addc_u32 s99, s11, 0
	global_store_dwordx4 v203, v[96:99], s[98:99] offset:16
	s_add_u32 s42, s10, 0x90200
	s_addc_u32 s43, s11, 0
	global_load_dwordx4 v[210:213], v203, s[42:43]
	s_waitcnt vmcnt(16)
	v_pk_fma_f32 v[68:69], v[156:157], v[68:69], v[236:237]
	v_pk_fma_f32 v[70:71], v[158:159], v[70:71], v[238:239]
	s_add_u32 s98, s10, 0x30200
	s_addc_u32 s99, s11, 0
	global_store_dwordx4 v203, v[68:71], s[98:99]
	s_add_u32 s42, s10, 0x90200
	s_addc_u32 s43, s11, 0
	global_load_dwordx4 v[236:239], v203, s[42:43] offset:16
	s_waitcnt vmcnt(16)
	v_pk_fma_f32 v[64:65], v[152:153], v[64:65], v[160:161]
	v_pk_fma_f32 v[66:67], v[154:155], v[66:67], v[162:163]
	s_add_u32 s98, s10, 0x30200
	s_addc_u32 s99, s11, 0
	global_store_dwordx4 v203, v[64:67], s[98:99] offset:16
	s_add_u32 s42, s10, 0xa0000
	s_addc_u32 s43, s11, 0
	global_load_dwordx4 v[160:163], v203, s[42:43]
	s_waitcnt vmcnt(16)
	v_pk_fma_f32 v[60:61], v[148:149], v[60:61], v[164:165]
	v_pk_fma_f32 v[62:63], v[150:151], v[62:63], v[166:167]
	s_add_u32 s98, s10, 0x80000
	s_addc_u32 s99, s11, 0
	global_store_dwordx4 v203, v[60:63], s[98:99]
	s_add_u32 s42, s10, 0xa0000
	s_addc_u32 s43, s11, 0
	global_load_dwordx4 v[164:167], v203, s[42:43] offset:16
	s_waitcnt vmcnt(16)
	v_pk_fma_f32 v[56:57], v[144:145], v[56:57], v[168:169]
	v_pk_fma_f32 v[58:59], v[146:147], v[58:59], v[170:171]
	s_add_u32 s98, s10, 0x80000
	s_addc_u32 s99, s11, 0
	global_store_dwordx4 v203, v[56:59], s[98:99] offset:16
	s_add_u32 s42, s10, 0xa0200
	s_addc_u32 s43, s11, 0
	global_load_dwordx4 v[168:171], v203, s[42:43]
	s_waitcnt vmcnt(16)
	v_pk_fma_f32 v[28:29], v[156:157], v[28:29], v[172:173]
	v_pk_fma_f32 v[30:31], v[158:159], v[30:31], v[174:175]
	s_add_u32 s98, s10, 0x80200
	s_addc_u32 s99, s11, 0
	global_store_dwordx4 v203, v[28:31], s[98:99]
	s_add_u32 s42, s10, 0xa0200
	s_addc_u32 s43, s11, 0
	global_load_dwordx4 v[172:175], v203, s[42:43] offset:16
	s_waitcnt vmcnt(16)
	v_pk_fma_f32 v[24:25], v[152:153], v[24:25], v[176:177]
	v_pk_fma_f32 v[26:27], v[154:155], v[26:27], v[178:179]
	s_add_u32 s98, s10, 0x80200
	s_addc_u32 s99, s11, 0
	global_store_dwordx4 v203, v[24:27], s[98:99] offset:16
	s_add_u32 s42, s10, 0xb0000
	s_addc_u32 s43, s11, 0
	global_load_dwordx4 v[176:179], v203, s[42:43]
	s_waitcnt vmcnt(16)
	v_pk_fma_f32 v[52:53], v[148:149], v[52:53], v[180:181]
	v_pk_fma_f32 v[54:55], v[150:151], v[54:55], v[182:183]
	s_add_u32 s98, s10, 0x90000
	s_addc_u32 s99, s11, 0
	global_store_dwordx4 v203, v[52:55], s[98:99]
	s_add_u32 s42, s10, 0xb0000
	s_addc_u32 s43, s11, 0
	global_load_dwordx4 v[180:183], v203, s[42:43] offset:16
	s_waitcnt vmcnt(16)
	v_pk_fma_f32 v[48:49], v[144:145], v[48:49], v[206:207]
	v_pk_fma_f32 v[50:51], v[146:147], v[50:51], v[208:209]
	s_add_u32 s98, s10, 0x90000
	s_addc_u32 s99, s11, 0
	global_store_dwordx4 v203, v[48:51], s[98:99] offset:16
	s_add_u32 s42, s10, 0xb0200
	s_addc_u32 s43, s11, 0
	global_load_dwordx4 v[206:209], v203, s[42:43]
	s_waitcnt vmcnt(16)
	v_pk_fma_f32 v[20:21], v[156:157], v[20:21], v[210:211]
	v_pk_fma_f32 v[22:23], v[158:159], v[22:23], v[212:213]
	s_add_u32 s98, s10, 0x90200
	s_addc_u32 s99, s11, 0
	global_store_dwordx4 v203, v[20:23], s[98:99]
	s_add_u32 s42, s10, 0xb0200
	s_addc_u32 s43, s11, 0
	global_load_dwordx4 v[210:213], v203, s[42:43] offset:16
	s_waitcnt vmcnt(16)
	v_pk_fma_f32 v[16:17], v[152:153], v[16:17], v[236:237]
	v_pk_fma_f32 v[18:19], v[154:155], v[18:19], v[238:239]
	s_add_u32 s98, s10, 0x90200
	s_addc_u32 s99, s11, 0
	global_store_dwordx4 v203, v[16:19], s[98:99] offset:16
	s_waitcnt vmcnt(15)
	v_pk_fma_f32 v[44:45], v[148:149], v[44:45], v[160:161]
	v_pk_fma_f32 v[46:47], v[150:151], v[46:47], v[162:163]
	s_add_u32 s42, s10, 0xa0000
	s_addc_u32 s43, s11, 0
	global_store_dwordx4 v203, v[44:47], s[42:43]
	s_waitcnt vmcnt(14)
	v_pk_fma_f32 v[40:41], v[144:145], v[40:41], v[164:165]
	v_pk_fma_f32 v[42:43], v[146:147], v[42:43], v[166:167]
	s_add_u32 s98, s10, 0xa0000
	s_addc_u32 s99, s11, 0
	global_store_dwordx4 v203, v[40:43], s[98:99] offset:16
	s_waitcnt vmcnt(13)
	v_pk_fma_f32 v[12:13], v[156:157], v[12:13], v[168:169]
	v_pk_fma_f32 v[14:15], v[158:159], v[14:15], v[170:171]
	s_add_u32 s42, s10, 0xa0200
	s_addc_u32 s43, s11, 0
	global_store_dwordx4 v203, v[12:15], s[42:43]
	s_waitcnt vmcnt(12)
	v_pk_fma_f32 v[8:9], v[152:153], v[8:9], v[172:173]
	v_pk_fma_f32 v[10:11], v[154:155], v[10:11], v[174:175]
	s_add_u32 s98, s10, 0xa0200
	s_addc_u32 s99, s11, 0
	global_store_dwordx4 v203, v[8:11], s[98:99] offset:16
	s_waitcnt vmcnt(11)
	v_pk_fma_f32 v[36:37], v[148:149], v[36:37], v[176:177]
	v_pk_fma_f32 v[38:39], v[150:151], v[38:39], v[178:179]
	s_add_u32 s42, s10, 0xb0000
	s_addc_u32 s43, s11, 0
	global_store_dwordx4 v203, v[36:39], s[42:43]
	s_waitcnt vmcnt(10)
	v_pk_fma_f32 v[32:33], v[144:145], v[32:33], v[180:181]
	v_pk_fma_f32 v[34:35], v[146:147], v[34:35], v[182:183]
	s_add_u32 s98, s10, 0xb0000
	s_addc_u32 s99, s11, 0
	global_store_dwordx4 v203, v[32:35], s[98:99] offset:16
	s_waitcnt vmcnt(9)
	v_pk_fma_f32 v[4:5], v[156:157], v[4:5], v[206:207]
	v_pk_fma_f32 v[6:7], v[158:159], v[6:7], v[208:209]
	s_add_u32 s42, s10, 0xb0200
	s_addc_u32 s43, s11, 0
	global_store_dwordx4 v203, v[4:7], s[42:43]
	s_waitcnt vmcnt(8)
	v_pk_fma_f32 v[0:1], v[152:153], v[0:1], v[210:211]
	v_pk_fma_f32 v[2:3], v[154:155], v[2:3], v[212:213]
	s_add_u32 s98, s10, 0xb0200
	s_addc_u32 s99, s11, 0
	global_store_dwordx4 v203, v[0:3], s[98:99] offset:16
	s_branch .Lfq_predone
.Lfq_np2:
	s_add_u32 s42, s62, 0x0
	s_addc_u32 s43, s63, 0
	global_load_dwordx4 v[160:163], v205, s[42:43] sc0 sc1
	s_add_u32 s98, s62, 0x1000
	s_addc_u32 s99, s63, 0
	global_load_dwordx4 v[164:167], v205, s[98:99] sc0 sc1
	s_add_u32 s42, s62, 0x400
	s_addc_u32 s43, s63, 0
	global_load_dwordx4 v[168:171], v205, s[42:43] sc0 sc1
	s_add_u32 s98, s62, 0x1400
	s_addc_u32 s99, s63, 0
	global_load_dwordx4 v[172:175], v205, s[98:99] sc0 sc1
	s_add_u32 s42, s62, 0x800
	s_addc_u32 s43, s63, 0
	global_load_dwordx4 v[176:179], v205, s[42:43] sc0 sc1
	s_add_u32 s98, s62, 0x1800
	s_addc_u32 s99, s63, 0
	global_load_dwordx4 v[180:183], v205, s[98:99] sc0 sc1
	s_add_u32 s42, s62, 0xc00
	s_addc_u32 s43, s63, 0
	global_load_dwordx4 v[206:209], v205, s[42:43] sc0 sc1
	s_add_u32 s98, s62, 0x1c00
	s_addc_u32 s99, s63, 0
	global_load_dwordx4 v[210:213], v205, s[98:99] sc0 sc1
	s_add_u32 s42, s62, 0x2000
	s_addc_u32 s43, s63, 0
	global_load_dwordx4 v[236:239], v205, s[42:43] sc0 sc1
	s_waitcnt vmcnt(8)
	v_lshlrev_b32_e32 v240, 16, v160
	v_and_b32_e32 v241, 0xffff0000, v160
	v_pk_add_f32 v[124:125], v[124:125], v[240:241]
	v_lshlrev_b32_e32 v240, 16, v161
	v_and_b32_e32 v241, 0xffff0000, v161
	v_pk_add_f32 v[126:127], v[126:127], v[240:241]
	v_lshlrev_b32_e32 v240, 16, v162
	v_and_b32_e32 v241, 0xffff0000, v162
	v_pk_add_f32 v[120:121], v[120:121], v[240:241]
	v_lshlrev_b32_e32 v240, 16, v163
	v_and_b32_e32 v241, 0xffff0000, v163
	v_pk_add_f32 v[122:123], v[122:123], v[240:241]
	s_add_u32 s98, s62, 0x3000
	s_addc_u32 s99, s63, 0
	global_load_dwordx4 v[160:163], v205, s[98:99] sc0 sc1
	s_waitcnt vmcnt(8)
	v_lshlrev_b32_e32 v240, 16, v164
	v_and_b32_e32 v241, 0xffff0000, v164
	v_pk_add_f32 v[92:93], v[92:93], v[240:241]
	v_lshlrev_b32_e32 v240, 16, v165
	v_and_b32_e32 v241, 0xffff0000, v165
	v_pk_add_f32 v[94:95], v[94:95], v[240:241]
	v_lshlrev_b32_e32 v240, 16, v166
	v_and_b32_e32 v241, 0xffff0000, v166
	v_pk_add_f32 v[88:89], v[88:89], v[240:241]
	v_lshlrev_b32_e32 v240, 16, v167
	v_and_b32_e32 v241, 0xffff0000, v167
	v_pk_add_f32 v[90:91], v[90:91], v[240:241]
	s_add_u32 s42, s62, 0x2400
	s_addc_u32 s43, s63, 0
	global_load_dwordx4 v[164:167], v205, s[42:43] sc0 sc1
	s_waitcnt vmcnt(8)
	v_lshlrev_b32_e32 v240, 16, v168
	v_and_b32_e32 v241, 0xffff0000, v168
	v_pk_add_f32 v[116:117], v[116:117], v[240:241]
	v_lshlrev_b32_e32 v240, 16, v169
	v_and_b32_e32 v241, 0xffff0000, v169
	v_pk_add_f32 v[118:119], v[118:119], v[240:241]
	v_lshlrev_b32_e32 v240, 16, v170
	v_and_b32_e32 v241, 0xffff0000, v170
	v_pk_add_f32 v[112:113], v[112:113], v[240:241]
	v_lshlrev_b32_e32 v240, 16, v171
	v_and_b32_e32 v241, 0xffff0000, v171
	v_pk_add_f32 v[114:115], v[114:115], v[240:241]
	s_add_u32 s98, s62, 0x3400
	s_addc_u32 s99, s63, 0
	global_load_dwordx4 v[168:171], v205, s[98:99] sc0 sc1
	s_waitcnt vmcnt(8)
	v_lshlrev_b32_e32 v240, 16, v172
	v_and_b32_e32 v241, 0xffff0000, v172
	v_pk_add_f32 v[84:85], v[84:85], v[240:241]
	v_lshlrev_b32_e32 v240, 16, v173
	v_and_b32_e32 v241, 0xffff0000, v173
	v_pk_add_f32 v[86:87], v[86:87], v[240:241]
	v_lshlrev_b32_e32 v240, 16, v174
	v_and_b32_e32 v241, 0xffff0000, v174
	v_pk_add_f32 v[80:81], v[80:81], v[240:241]
	v_lshlrev_b32_e32 v240, 16, v175
	v_and_b32_e32 v241, 0xffff0000, v175
	v_pk_add_f32 v[82:83], v[82:83], v[240:241]
	s_add_u32 s42, s62, 0x2800
	s_addc_u32 s43, s63, 0
	global_load_dwordx4 v[172:175], v205, s[42:43] sc0 sc1
	s_waitcnt vmcnt(8)
	v_lshlrev_b32_e32 v240, 16, v176
	v_and_b32_e32 v241, 0xffff0000, v176
	v_pk_add_f32 v[108:109], v[108:109], v[240:241]
	v_lshlrev_b32_e32 v240, 16, v177
	v_and_b32_e32 v241, 0xffff0000, v177
	v_pk_add_f32 v[110:111], v[110:111], v[240:241]
	v_lshlrev_b32_e32 v240, 16, v178
	v_and_b32_e32 v241, 0xffff0000, v178
	v_pk_add_f32 v[104:105], v[104:105], v[240:241]
	v_lshlrev_b32_e32 v240, 16, v179
	v_and_b32_e32 v241, 0xffff0000, v179
	v_pk_add_f32 v[106:107], v[106:107], v[240:241]
	s_add_u32 s98, s62, 0x3800
	s_addc_u32 s99, s63, 0
	global_load_dwordx4 v[176:179], v205, s[98:99] sc0 sc1
	s_waitcnt vmcnt(8)
	v_lshlrev_b32_e32 v240, 16, v180
	v_and_b32_e32 v241, 0xffff0000, v180
	v_pk_add_f32 v[76:77], v[76:77], v[240:241]
	v_lshlrev_b32_e32 v240, 16, v181
	v_and_b32_e32 v241, 0xffff0000, v181
	v_pk_add_f32 v[78:79], v[78:79], v[240:241]
	v_lshlrev_b32_e32 v240, 16, v182
	v_and_b32_e32 v241, 0xffff0000, v182
	v_pk_add_f32 v[72:73], v[72:73], v[240:241]
	v_lshlrev_b32_e32 v240, 16, v183
	v_and_b32_e32 v241, 0xffff0000, v183
	v_pk_add_f32 v[74:75], v[74:75], v[240:241]
	s_add_u32 s42, s62, 0x2c00
	s_addc_u32 s43, s63, 0
	global_load_dwordx4 v[180:183], v205, s[42:43] sc0 sc1
	s_waitcnt vmcnt(8)
	v_lshlrev_b32_e32 v240, 16, v206
	v_and_b32_e32 v241, 0xffff0000, v206
	v_pk_add_f32 v[100:101], v[100:101], v[240:241]
	v_lshlrev_b32_e32 v240, 16, v207
	v_and_b32_e32 v241, 0xffff0000, v207
	v_pk_add_f32 v[102:103], v[102:103], v[240:241]
	v_lshlrev_b32_e32 v240, 16, v208
	v_and_b32_e32 v241, 0xffff0000, v208
	v_pk_add_f32 v[96:97], v[96:97], v[240:241]
	v_lshlrev_b32_e32 v240, 16, v209
	v_and_b32_e32 v241, 0xffff0000, v209
	v_pk_add_f32 v[98:99], v[98:99], v[240:241]
	s_add_u32 s98, s62, 0x3c00
	s_addc_u32 s99, s63, 0
	global_load_dwordx4 v[206:209], v205, s[98:99] sc0 sc1
	s_waitcnt vmcnt(8)
	v_lshlrev_b32_e32 v240, 16, v210
	v_and_b32_e32 v241, 0xffff0000, v210
	v_pk_add_f32 v[68:69], v[68:69], v[240:241]
	v_lshlrev_b32_e32 v240, 16, v211
	v_and_b32_e32 v241, 0xffff0000, v211
	v_pk_add_f32 v[70:71], v[70:71], v[240:241]
	v_lshlrev_b32_e32 v240, 16, v212
	v_and_b32_e32 v241, 0xffff0000, v212
	v_pk_add_f32 v[64:65], v[64:65], v[240:241]
	v_lshlrev_b32_e32 v240, 16, v213
	v_and_b32_e32 v241, 0xffff0000, v213
	v_pk_add_f32 v[66:67], v[66:67], v[240:241]
	s_add_u32 s42, s62, 0x20000
	s_addc_u32 s43, s63, 0
	global_load_dwordx4 v[210:213], v205, s[42:43] sc0 sc1
	s_waitcnt vmcnt(8)
	v_lshlrev_b32_e32 v240, 16, v236
	v_and_b32_e32 v241, 0xffff0000, v236
	v_pk_add_f32 v[60:61], v[60:61], v[240:241]
	v_lshlrev_b32_e32 v240, 16, v237
	v_and_b32_e32 v241, 0xffff0000, v237
	v_pk_add_f32 v[62:63], v[62:63], v[240:241]
	v_lshlrev_b32_e32 v240, 16, v238
	v_and_b32_e32 v241, 0xffff0000, v238
	v_pk_add_f32 v[56:57], v[56:57], v[240:241]
	v_lshlrev_b32_e32 v240, 16, v239
	v_and_b32_e32 v241, 0xffff0000, v239
	v_pk_add_f32 v[58:59], v[58:59], v[240:241]
	s_add_u32 s98, s62, 0x21000
	s_addc_u32 s99, s63, 0
	global_load_dwordx4 v[236:239], v205, s[98:99] sc0 sc1
	s_waitcnt vmcnt(8)
	v_lshlrev_b32_e32 v240, 16, v160
	v_and_b32_e32 v241, 0xffff0000, v160
	v_pk_add_f32 v[28:29], v[28:29], v[240:241]
	v_lshlrev_b32_e32 v240, 16, v161
	v_and_b32_e32 v241, 0xffff0000, v161
	v_pk_add_f32 v[30:31], v[30:31], v[240:241]
	v_lshlrev_b32_e32 v240, 16, v162
	v_and_b32_e32 v241, 0xffff0000, v162
	v_pk_add_f32 v[24:25], v[24:25], v[240:241]
	v_lshlrev_b32_e32 v240, 16, v163
	v_and_b32_e32 v241, 0xffff0000, v163
	v_pk_add_f32 v[26:27], v[26:27], v[240:241]
	s_add_u32 s42, s62, 0x20400
	s_addc_u32 s43, s63, 0
	global_load_dwordx4 v[160:163], v205, s[42:43] sc0 sc1
	s_waitcnt vmcnt(8)
	v_lshlrev_b32_e32 v240, 16, v164
	v_and_b32_e32 v241, 0xffff0000, v164
	v_pk_add_f32 v[52:53], v[52:53], v[240:241]
	v_lshlrev_b32_e32 v240, 16, v165
	v_and_b32_e32 v241, 0xffff0000, v165
	v_pk_add_f32 v[54:55], v[54:55], v[240:241]
	v_lshlrev_b32_e32 v240, 16, v166
	v_and_b32_e32 v241, 0xffff0000, v166
	v_pk_add_f32 v[48:49], v[48:49], v[240:241]
	v_lshlrev_b32_e32 v240, 16, v167
	v_and_b32_e32 v241, 0xffff0000, v167
	v_pk_add_f32 v[50:51], v[50:51], v[240:241]
	s_add_u32 s98, s62, 0x21400
	s_addc_u32 s99, s63, 0
	global_load_dwordx4 v[164:167], v205, s[98:99] sc0 sc1
	s_waitcnt vmcnt(8)
	v_lshlrev_b32_e32 v240, 16, v168
	v_and_b32_e32 v241, 0xffff0000, v168
	v_pk_add_f32 v[20:21], v[20:21], v[240:241]
	v_lshlrev_b32_e32 v240, 16, v169
	v_and_b32_e32 v241, 0xffff0000, v169
	v_pk_add_f32 v[22:23], v[22:23], v[240:241]
	v_lshlrev_b32_e32 v240, 16, v170
	v_and_b32_e32 v241, 0xffff0000, v170
	v_pk_add_f32 v[16:17], v[16:17], v[240:241]
	v_lshlrev_b32_e32 v240, 16, v171
	v_and_b32_e32 v241, 0xffff0000, v171
	v_pk_add_f32 v[18:19], v[18:19], v[240:241]
	s_add_u32 s42, s62, 0x20800
	s_addc_u32 s43, s63, 0
	global_load_dwordx4 v[168:171], v205, s[42:43] sc0 sc1
	s_waitcnt vmcnt(8)
	v_lshlrev_b32_e32 v240, 16, v172
	v_and_b32_e32 v241, 0xffff0000, v172
	v_pk_add_f32 v[44:45], v[44:45], v[240:241]
	v_lshlrev_b32_e32 v240, 16, v173
	v_and_b32_e32 v241, 0xffff0000, v173
	v_pk_add_f32 v[46:47], v[46:47], v[240:241]
	v_lshlrev_b32_e32 v240, 16, v174
	v_and_b32_e32 v241, 0xffff0000, v174
	v_pk_add_f32 v[40:41], v[40:41], v[240:241]
	v_lshlrev_b32_e32 v240, 16, v175
	v_and_b32_e32 v241, 0xffff0000, v175
	v_pk_add_f32 v[42:43], v[42:43], v[240:241]
	s_add_u32 s98, s62, 0x21800
	s_addc_u32 s99, s63, 0
	global_load_dwordx4 v[172:175], v205, s[98:99] sc0 sc1
	s_waitcnt vmcnt(8)
	v_lshlrev_b32_e32 v240, 16, v176
	v_and_b32_e32 v241, 0xffff0000, v176
	v_pk_add_f32 v[12:13], v[12:13], v[240:241]
	v_lshlrev_b32_e32 v240, 16, v177
	v_and_b32_e32 v241, 0xffff0000, v177
	v_pk_add_f32 v[14:15], v[14:15], v[240:241]
	v_lshlrev_b32_e32 v240, 16, v178
	v_and_b32_e32 v241, 0xffff0000, v178
	v_pk_add_f32 v[8:9], v[8:9], v[240:241]
	v_lshlrev_b32_e32 v240, 16, v179
	v_and_b32_e32 v241, 0xffff0000, v179
	v_pk_add_f32 v[10:11], v[10:11], v[240:241]
	s_add_u32 s42, s62, 0x20c00
	s_addc_u32 s43, s63, 0
	global_load_dwordx4 v[176:179], v205, s[42:43] sc0 sc1
	s_waitcnt vmcnt(8)
	v_lshlrev_b32_e32 v240, 16, v180
	v_and_b32_e32 v241, 0xffff0000, v180
	v_pk_add_f32 v[36:37], v[36:37], v[240:241]
	v_lshlrev_b32_e32 v240, 16, v181
	v_and_b32_e32 v241, 0xffff0000, v181
	v_pk_add_f32 v[38:39], v[38:39], v[240:241]
	v_lshlrev_b32_e32 v240, 16, v182
	v_and_b32_e32 v241, 0xffff0000, v182
	v_pk_add_f32 v[32:33], v[32:33], v[240:241]
	v_lshlrev_b32_e32 v240, 16, v183
	v_and_b32_e32 v241, 0xffff0000, v183
	v_pk_add_f32 v[34:35], v[34:35], v[240:241]
	s_add_u32 s98, s62, 0x21c00
	s_addc_u32 s99, s63, 0
	global_load_dwordx4 v[180:183], v205, s[98:99] sc0 sc1
	s_waitcnt vmcnt(8)
	v_lshlrev_b32_e32 v240, 16, v206
	v_and_b32_e32 v241, 0xffff0000, v206
	v_pk_add_f32 v[4:5], v[4:5], v[240:241]
	v_lshlrev_b32_e32 v240, 16, v207
	v_and_b32_e32 v241, 0xffff0000, v207
	v_pk_add_f32 v[6:7], v[6:7], v[240:241]
	v_lshlrev_b32_e32 v240, 16, v208
	v_and_b32_e32 v241, 0xffff0000, v208
	v_pk_add_f32 v[0:1], v[0:1], v[240:241]
	v_lshlrev_b32_e32 v240, 16, v209
	v_and_b32_e32 v241, 0xffff0000, v209
	v_pk_add_f32 v[2:3], v[2:3], v[240:241]
	s_add_u32 s42, s62, 0x22000
	s_addc_u32 s43, s63, 0
	global_load_dwordx4 v[206:209], v205, s[42:43] sc0 sc1
	s_waitcnt vmcnt(8)
	v_lshlrev_b32_e32 v240, 16, v210
	v_and_b32_e32 v241, 0xffff0000, v210
	v_pk_add_f32 v[124:125], v[124:125], v[240:241]
	v_lshlrev_b32_e32 v240, 16, v211
	v_and_b32_e32 v241, 0xffff0000, v211
	v_pk_add_f32 v[126:127], v[126:127], v[240:241]
	v_lshlrev_b32_e32 v240, 16, v212
	v_and_b32_e32 v241, 0xffff0000, v212
	v_pk_add_f32 v[120:121], v[120:121], v[240:241]
	v_lshlrev_b32_e32 v240, 16, v213
	v_and_b32_e32 v241, 0xffff0000, v213
	v_pk_add_f32 v[122:123], v[122:123], v[240:241]
	s_add_u32 s98, s62, 0x23000
	s_addc_u32 s99, s63, 0
	global_load_dwordx4 v[210:213], v205, s[98:99] sc0 sc1
	s_waitcnt vmcnt(8)
	v_lshlrev_b32_e32 v240, 16, v236
	v_and_b32_e32 v241, 0xffff0000, v236
	v_pk_add_f32 v[92:93], v[92:93], v[240:241]
	v_lshlrev_b32_e32 v240, 16, v237
	v_and_b32_e32 v241, 0xffff0000, v237
	v_pk_add_f32 v[94:95], v[94:95], v[240:241]
	v_lshlrev_b32_e32 v240, 16, v238
	v_and_b32_e32 v241, 0xffff0000, v238
	v_pk_add_f32 v[88:89], v[88:89], v[240:241]
	v_lshlrev_b32_e32 v240, 16, v239
	v_and_b32_e32 v241, 0xffff0000, v239
	v_pk_add_f32 v[90:91], v[90:91], v[240:241]
	s_add_u32 s42, s62, 0x22400
	s_addc_u32 s43, s63, 0
	global_load_dwordx4 v[236:239], v205, s[42:43] sc0 sc1
	s_waitcnt vmcnt(8)
	v_lshlrev_b32_e32 v240, 16, v160
	v_and_b32_e32 v241, 0xffff0000, v160
	v_pk_add_f32 v[116:117], v[116:117], v[240:241]
	v_lshlrev_b32_e32 v240, 16, v161
	v_and_b32_e32 v241, 0xffff0000, v161
	v_pk_add_f32 v[118:119], v[118:119], v[240:241]
	v_lshlrev_b32_e32 v240, 16, v162
	v_and_b32_e32 v241, 0xffff0000, v162
	v_pk_add_f32 v[112:113], v[112:113], v[240:241]
	v_lshlrev_b32_e32 v240, 16, v163
	v_and_b32_e32 v241, 0xffff0000, v163
	v_pk_add_f32 v[114:115], v[114:115], v[240:241]
	s_add_u32 s98, s62, 0x23400
	s_addc_u32 s99, s63, 0
	global_load_dwordx4 v[160:163], v205, s[98:99] sc0 sc1
	s_waitcnt vmcnt(8)
	v_lshlrev_b32_e32 v240, 16, v164
	v_and_b32_e32 v241, 0xffff0000, v164
	v_pk_add_f32 v[84:85], v[84:85], v[240:241]
	v_lshlrev_b32_e32 v240, 16, v165
	v_and_b32_e32 v241, 0xffff0000, v165
	v_pk_add_f32 v[86:87], v[86:87], v[240:241]
	v_lshlrev_b32_e32 v240, 16, v166
	v_and_b32_e32 v241, 0xffff0000, v166
	v_pk_add_f32 v[80:81], v[80:81], v[240:241]
	v_lshlrev_b32_e32 v240, 16, v167
	v_and_b32_e32 v241, 0xffff0000, v167
	v_pk_add_f32 v[82:83], v[82:83], v[240:241]
	s_add_u32 s42, s62, 0x22800
	s_addc_u32 s43, s63, 0
	global_load_dwordx4 v[164:167], v205, s[42:43] sc0 sc1
	s_waitcnt vmcnt(8)
	v_lshlrev_b32_e32 v240, 16, v168
	v_and_b32_e32 v241, 0xffff0000, v168
	v_pk_add_f32 v[108:109], v[108:109], v[240:241]
	v_lshlrev_b32_e32 v240, 16, v169
	v_and_b32_e32 v241, 0xffff0000, v169
	v_pk_add_f32 v[110:111], v[110:111], v[240:241]
	v_lshlrev_b32_e32 v240, 16, v170
	v_and_b32_e32 v241, 0xffff0000, v170
	v_pk_add_f32 v[104:105], v[104:105], v[240:241]
	v_lshlrev_b32_e32 v240, 16, v171
	v_and_b32_e32 v241, 0xffff0000, v171
	v_pk_add_f32 v[106:107], v[106:107], v[240:241]
	s_add_u32 s98, s62, 0x23800
	s_addc_u32 s99, s63, 0
	global_load_dwordx4 v[168:171], v205, s[98:99] sc0 sc1
	s_waitcnt vmcnt(8)
	v_lshlrev_b32_e32 v240, 16, v172
	v_and_b32_e32 v241, 0xffff0000, v172
	v_pk_add_f32 v[76:77], v[76:77], v[240:241]
	v_lshlrev_b32_e32 v240, 16, v173
	v_and_b32_e32 v241, 0xffff0000, v173
	v_pk_add_f32 v[78:79], v[78:79], v[240:241]
	v_lshlrev_b32_e32 v240, 16, v174
	v_and_b32_e32 v241, 0xffff0000, v174
	v_pk_add_f32 v[72:73], v[72:73], v[240:241]
	v_lshlrev_b32_e32 v240, 16, v175
	v_and_b32_e32 v241, 0xffff0000, v175
	v_pk_add_f32 v[74:75], v[74:75], v[240:241]
	s_add_u32 s42, s62, 0x22c00
	s_addc_u32 s43, s63, 0
	global_load_dwordx4 v[172:175], v205, s[42:43] sc0 sc1
	s_waitcnt vmcnt(8)
	v_lshlrev_b32_e32 v240, 16, v176
	v_and_b32_e32 v241, 0xffff0000, v176
	v_pk_add_f32 v[100:101], v[100:101], v[240:241]
	v_lshlrev_b32_e32 v240, 16, v177
	v_and_b32_e32 v241, 0xffff0000, v177
	v_pk_add_f32 v[102:103], v[102:103], v[240:241]
	v_lshlrev_b32_e32 v240, 16, v178
	v_and_b32_e32 v241, 0xffff0000, v178
	v_pk_add_f32 v[96:97], v[96:97], v[240:241]
	v_lshlrev_b32_e32 v240, 16, v179
	v_and_b32_e32 v241, 0xffff0000, v179
	v_pk_add_f32 v[98:99], v[98:99], v[240:241]
	s_add_u32 s98, s62, 0x23c00
	s_addc_u32 s99, s63, 0
	global_load_dwordx4 v[176:179], v205, s[98:99] sc0 sc1
	s_waitcnt vmcnt(8)
	v_lshlrev_b32_e32 v240, 16, v180
	v_and_b32_e32 v241, 0xffff0000, v180
	v_pk_add_f32 v[68:69], v[68:69], v[240:241]
	v_lshlrev_b32_e32 v240, 16, v181
	v_and_b32_e32 v241, 0xffff0000, v181
	v_pk_add_f32 v[70:71], v[70:71], v[240:241]
	v_lshlrev_b32_e32 v240, 16, v182
	v_and_b32_e32 v241, 0xffff0000, v182
	v_pk_add_f32 v[64:65], v[64:65], v[240:241]
	v_lshlrev_b32_e32 v240, 16, v183
	v_and_b32_e32 v241, 0xffff0000, v183
	v_pk_add_f32 v[66:67], v[66:67], v[240:241]
	s_add_u32 s42, s10, 0x0
	s_addc_u32 s43, s11, 0
	global_load_dwordx4 v[180:183], v203, s[42:43]
	s_waitcnt vmcnt(8)
	v_lshlrev_b32_e32 v240, 16, v206
	v_and_b32_e32 v241, 0xffff0000, v206
	v_pk_add_f32 v[60:61], v[60:61], v[240:241]
	v_lshlrev_b32_e32 v240, 16, v207
	v_and_b32_e32 v241, 0xffff0000, v207
	v_pk_add_f32 v[62:63], v[62:63], v[240:241]
	v_lshlrev_b32_e32 v240, 16, v208
	v_and_b32_e32 v241, 0xffff0000, v208
	v_pk_add_f32 v[56:57], v[56:57], v[240:241]
	v_lshlrev_b32_e32 v240, 16, v209
	v_and_b32_e32 v241, 0xffff0000, v209
	v_pk_add_f32 v[58:59], v[58:59], v[240:241]
	s_add_u32 s98, s10, 0x0
	s_addc_u32 s99, s11, 0
	global_load_dwordx4 v[206:209], v203, s[98:99] offset:16
	s_waitcnt vmcnt(8)
	v_lshlrev_b32_e32 v240, 16, v210
	v_and_b32_e32 v241, 0xffff0000, v210
	v_pk_add_f32 v[28:29], v[28:29], v[240:241]
	v_lshlrev_b32_e32 v240, 16, v211
	v_and_b32_e32 v241, 0xffff0000, v211
	v_pk_add_f32 v[30:31], v[30:31], v[240:241]
	v_lshlrev_b32_e32 v240, 16, v212
	v_and_b32_e32 v241, 0xffff0000, v212
	v_pk_add_f32 v[24:25], v[24:25], v[240:241]
	v_lshlrev_b32_e32 v240, 16, v213
	v_and_b32_e32 v241, 0xffff0000, v213
	v_pk_add_f32 v[26:27], v[26:27], v[240:241]
	s_add_u32 s42, s10, 0x200
	s_addc_u32 s43, s11, 0
	global_load_dwordx4 v[210:213], v203, s[42:43]
	s_waitcnt vmcnt(8)
	v_lshlrev_b32_e32 v240, 16, v236
	v_and_b32_e32 v241, 0xffff0000, v236
	v_pk_add_f32 v[52:53], v[52:53], v[240:241]
	v_lshlrev_b32_e32 v240, 16, v237
	v_and_b32_e32 v241, 0xffff0000, v237
	v_pk_add_f32 v[54:55], v[54:55], v[240:241]
	v_lshlrev_b32_e32 v240, 16, v238
	v_and_b32_e32 v241, 0xffff0000, v238
	v_pk_add_f32 v[48:49], v[48:49], v[240:241]
	v_lshlrev_b32_e32 v240, 16, v239
	v_and_b32_e32 v241, 0xffff0000, v239
	v_pk_add_f32 v[50:51], v[50:51], v[240:241]
	s_add_u32 s98, s10, 0x200
	s_addc_u32 s99, s11, 0
	global_load_dwordx4 v[236:239], v203, s[98:99] offset:16
	s_waitcnt vmcnt(8)
	v_lshlrev_b32_e32 v240, 16, v160
	v_and_b32_e32 v241, 0xffff0000, v160
	v_pk_add_f32 v[20:21], v[20:21], v[240:241]
	v_lshlrev_b32_e32 v240, 16, v161
	v_and_b32_e32 v241, 0xffff0000, v161
	v_pk_add_f32 v[22:23], v[22:23], v[240:241]
	v_lshlrev_b32_e32 v240, 16, v162
	v_and_b32_e32 v241, 0xffff0000, v162
	v_pk_add_f32 v[16:17], v[16:17], v[240:241]
	v_lshlrev_b32_e32 v240, 16, v163
	v_and_b32_e32 v241, 0xffff0000, v163
	v_pk_add_f32 v[18:19], v[18:19], v[240:241]
	s_add_u32 s42, s10, 0x10000
	s_addc_u32 s43, s11, 0
	global_load_dwordx4 v[160:163], v203, s[42:43]
	s_waitcnt vmcnt(8)
	v_lshlrev_b32_e32 v240, 16, v164
	v_and_b32_e32 v241, 0xffff0000, v164
	v_pk_add_f32 v[44:45], v[44:45], v[240:241]
	v_lshlrev_b32_e32 v240, 16, v165
	v_and_b32_e32 v241, 0xffff0000, v165
	v_pk_add_f32 v[46:47], v[46:47], v[240:241]
	v_lshlrev_b32_e32 v240, 16, v166
	v_and_b32_e32 v241, 0xffff0000, v166
	v_pk_add_f32 v[40:41], v[40:41], v[240:241]
	v_lshlrev_b32_e32 v240, 16, v167
	v_and_b32_e32 v241, 0xffff0000, v167
	v_pk_add_f32 v[42:43], v[42:43], v[240:241]
	s_add_u32 s98, s10, 0x10000
	s_addc_u32 s99, s11, 0
	global_load_dwordx4 v[164:167], v203, s[98:99] offset:16
	s_waitcnt vmcnt(8)
	v_lshlrev_b32_e32 v240, 16, v168
	v_and_b32_e32 v241, 0xffff0000, v168
	v_pk_add_f32 v[12:13], v[12:13], v[240:241]
	v_lshlrev_b32_e32 v240, 16, v169
	v_and_b32_e32 v241, 0xffff0000, v169
	v_pk_add_f32 v[14:15], v[14:15], v[240:241]
	v_lshlrev_b32_e32 v240, 16, v170
	v_and_b32_e32 v241, 0xffff0000, v170
	v_pk_add_f32 v[8:9], v[8:9], v[240:241]
	v_lshlrev_b32_e32 v240, 16, v171
	v_and_b32_e32 v241, 0xffff0000, v171
	v_pk_add_f32 v[10:11], v[10:11], v[240:241]
	s_add_u32 s42, s10, 0x10200
	s_addc_u32 s43, s11, 0
	global_load_dwordx4 v[168:171], v203, s[42:43]
	s_waitcnt vmcnt(8)
	v_lshlrev_b32_e32 v240, 16, v172
	v_and_b32_e32 v241, 0xffff0000, v172
	v_pk_add_f32 v[36:37], v[36:37], v[240:241]
	v_lshlrev_b32_e32 v240, 16, v173
	v_and_b32_e32 v241, 0xffff0000, v173
	v_pk_add_f32 v[38:39], v[38:39], v[240:241]
	v_lshlrev_b32_e32 v240, 16, v174
	v_and_b32_e32 v241, 0xffff0000, v174
	v_pk_add_f32 v[32:33], v[32:33], v[240:241]
	v_lshlrev_b32_e32 v240, 16, v175
	v_and_b32_e32 v241, 0xffff0000, v175
	v_pk_add_f32 v[34:35], v[34:35], v[240:241]
	s_add_u32 s98, s10, 0x10200
	s_addc_u32 s99, s11, 0
	global_load_dwordx4 v[172:175], v203, s[98:99] offset:16
	s_waitcnt vmcnt(8)
	v_lshlrev_b32_e32 v240, 16, v176
	v_and_b32_e32 v241, 0xffff0000, v176
	v_pk_add_f32 v[4:5], v[4:5], v[240:241]
	v_lshlrev_b32_e32 v240, 16, v177
	v_and_b32_e32 v241, 0xffff0000, v177
	v_pk_add_f32 v[6:7], v[6:7], v[240:241]
	v_lshlrev_b32_e32 v240, 16, v178
	v_and_b32_e32 v241, 0xffff0000, v178
	v_pk_add_f32 v[0:1], v[0:1], v[240:241]
	v_lshlrev_b32_e32 v240, 16, v179
	v_and_b32_e32 v241, 0xffff0000, v179
	v_pk_add_f32 v[2:3], v[2:3], v[240:241]
	s_add_u32 s42, s10, 0x20000
	s_addc_u32 s43, s11, 0
	global_load_dwordx4 v[176:179], v203, s[42:43]
	s_waitcnt vmcnt(8)
	v_pk_fma_f32 v[124:125], v[148:149], v[124:125], v[180:181]
	v_pk_fma_f32 v[126:127], v[150:151], v[126:127], v[182:183]
	s_add_u32 s98, s10, 0x0
	s_addc_u32 s99, s11, 0
	global_store_dwordx4 v203, v[124:127], s[98:99]
	s_add_u32 s42, s10, 0x20000
	s_addc_u32 s43, s11, 0
	global_load_dwordx4 v[180:183], v203, s[42:43] offset:16
	s_waitcnt vmcnt(9)
	v_pk_fma_f32 v[120:121], v[144:145], v[120:121], v[206:207]
	v_pk_fma_f32 v[122:123], v[146:147], v[122:123], v[208:209]
	s_add_u32 s98, s10, 0x0
	s_addc_u32 s99, s11, 0
	global_store_dwordx4 v203, v[120:123], s[98:99] offset:16
	s_add_u32 s42, s10, 0x20200
	s_addc_u32 s43, s11, 0
	global_load_dwordx4 v[206:209], v203, s[42:43]
	s_waitcnt vmcnt(10)
	v_pk_fma_f32 v[92:93], v[156:157], v[92:93], v[210:211]
	v_pk_fma_f32 v[94:95], v[158:159], v[94:95], v[212:213]
	s_add_u32 s98, s10, 0x200
	s_addc_u32 s99, s11, 0
	global_store_dwordx4 v203, v[92:95], s[98:99]
	s_add_u32 s42, s10, 0x20200
	s_addc_u32 s43, s11, 0
	global_load_dwordx4 v[210:213], v203, s[42:43] offset:16
	s_waitcnt vmcnt(11)
	v_pk_fma_f32 v[88:89], v[152:153], v[88:89], v[236:237]
	v_pk_fma_f32 v[90:91], v[154:155], v[90:91], v[238:239]
	s_add_u32 s98, s10, 0x200
	s_addc_u32 s99, s11, 0
	global_store_dwordx4 v203, v[88:91], s[98:99] offset:16
	s_add_u32 s42, s10, 0x30000
	s_addc_u32 s43, s11, 0
	global_load_dwordx4 v[236:239], v203, s[42:43]
	s_waitcnt vmcnt(12)
	v_pk_fma_f32 v[116:117], v[148:149], v[116:117], v[160:161]
	v_pk_fma_f32 v[118:119], v[150:151], v[118:119], v[162:163]
	s_add_u32 s98, s10, 0x10000
	s_addc_u32 s99, s11, 0
	global_store_dwordx4 v203, v[116:119], s[98:99]
	s_add_u32 s42, s10, 0x30000
	s_addc_u32 s43, s11, 0
	global_load_dwordx4 v[160:163], v203, s[42:43] offset:16
	s_waitcnt vmcnt(13)
	v_pk_fma_f32 v[112:113], v[144:145], v[112:113], v[164:165]
	v_pk_fma_f32 v[114:115], v[146:147], v[114:115], v[166:167]
	s_add_u32 s98, s10, 0x10000
	s_addc_u32 s99, s11, 0
	global_store_dwordx4 v203, v[112:115], s[98:99] offset:16
	s_add_u32 s42, s10, 0x30200
	s_addc_u32 s43, s11, 0
	global_load_dwordx4 v[164:167], v203, s[42:43]
	s_waitcnt vmcnt(14)
	v_pk_fma_f32 v[84:85], v[156:157], v[84:85], v[168:169]
	v_pk_fma_f32 v[86:87], v[158:159], v[86:87], v[170:171]
	s_add_u32 s98, s10, 0x10200
	s_addc_u32 s99, s11, 0
	global_store_dwordx4 v203, v[84:87], s[98:99]
	s_add_u32 s42, s10, 0x30200
	s_addc_u32 s43, s11, 0
	global_load_dwordx4 v[168:171], v203, s[42:43] offset:16
	s_waitcnt vmcnt(15)
	v_pk_fma_f32 v[80:81], v[152:153], v[80:81], v[172:173]
	v_pk_fma_f32 v[82:83], v[154:155], v[82:83], v[174:175]
	s_add_u32 s98, s10, 0x10200
	s_addc_u32 s99, s11, 0
	global_store_dwordx4 v203, v[80:83], s[98:99] offset:16
	s_add_u32 s42, s10, 0x80000
	s_addc_u32 s43, s11, 0
	global_load_dwordx4 v[172:175], v203, s[42:43]
	s_waitcnt vmcnt(16)
	v_pk_fma_f32 v[108:109], v[148:149], v[108:109], v[176:177]
	v_pk_fma_f32 v[110:111], v[150:151], v[110:111], v[178:179]
	s_add_u32 s98, s10, 0x20000
	s_addc_u32 s99, s11, 0
	global_store_dwordx4 v203, v[108:111], s[98:99]
	s_add_u32 s42, s10, 0x80000
	s_addc_u32 s43, s11, 0
	global_load_dwordx4 v[176:179], v203, s[42:43] offset:16
	s_waitcnt vmcnt(16)
	v_pk_fma_f32 v[104:105], v[144:145], v[104:105], v[180:181]
	v_pk_fma_f32 v[106:107], v[146:147], v[106:107], v[182:183]
	s_add_u32 s98, s10, 0x20000
	s_addc_u32 s99, s11, 0
	global_store_dwordx4 v203, v[104:107], s[98:99] offset:16
	s_add_u32 s42, s10, 0x80200
	s_addc_u32 s43, s11, 0
	global_load_dwordx4 v[180:183], v203, s[42:43]
	s_waitcnt vmcnt(16)
	v_pk_fma_f32 v[76:77], v[156:157], v[76:77], v[206:207]
	v_pk_fma_f32 v[78:79], v[158:159], v[78:79], v[208:209]
	s_add_u32 s98, s10, 0x20200
	s_addc_u32 s99, s11, 0
	global_store_dwordx4 v203, v[76:79], s[98:99]
	s_add_u32 s42, s10, 0x80200
	s_addc_u32 s43, s11, 0
	global_load_dwordx4 v[206:209], v203, s[42:43] offset:16
	s_waitcnt vmcnt(16)
	v_pk_fma_f32 v[72:73], v[152:153], v[72:73], v[210:211]
	v_pk_fma_f32 v[74:75], v[154:155], v[74:75], v[212:213]
	s_add_u32 s98, s10, 0x20200
	s_addc_u32 s99, s11, 0
	global_store_dwordx4 v203, v[72:75], s[98:99] offset:16
	s_add_u32 s42, s10, 0x90000
	s_addc_u32 s43, s11, 0
	global_load_dwordx4 v[210:213], v203, s[42:43]
	s_waitcnt vmcnt(16)
	v_pk_fma_f32 v[100:101], v[148:149], v[100:101], v[236:237]
	v_pk_fma_f32 v[102:103], v[150:151], v[102:103], v[238:239]
	s_add_u32 s98, s10, 0x30000
	s_addc_u32 s99, s11, 0
	global_store_dwordx4 v203, v[100:103], s[98:99]
	s_add_u32 s42, s10, 0x90000
	s_addc_u32 s43, s11, 0
	global_load_dwordx4 v[236:239], v203, s[42:43] offset:16
	s_waitcnt vmcnt(16)
	v_pk_fma_f32 v[96:97], v[144:145], v[96:97], v[160:161]
	v_pk_fma_f32 v[98:99], v[146:147], v[98:99], v[162:163]
	s_add_u32 s98, s10, 0x30000
	s_addc_u32 s99, s11, 0
	global_store_dwordx4 v203, v[96:99], s[98:99] offset:16
	s_add_u32 s42, s10, 0x90200
	s_addc_u32 s43, s11, 0
	global_load_dwordx4 v[160:163], v203, s[42:43]
	s_waitcnt vmcnt(16)
	v_pk_fma_f32 v[68:69], v[156:157], v[68:69], v[164:165]
	v_pk_fma_f32 v[70:71], v[158:159], v[70:71], v[166:167]
	s_add_u32 s98, s10, 0x30200
	s_addc_u32 s99, s11, 0
	global_store_dwordx4 v203, v[68:71], s[98:99]
	s_add_u32 s42, s10, 0x90200
	s_addc_u32 s43, s11, 0
	global_load_dwordx4 v[164:167], v203, s[42:43] offset:16
	s_waitcnt vmcnt(16)
	v_pk_fma_f32 v[64:65], v[152:153], v[64:65], v[168:169]
	v_pk_fma_f32 v[66:67], v[154:155], v[66:67], v[170:171]
	s_add_u32 s98, s10, 0x30200
	s_addc_u32 s99, s11, 0
	global_store_dwordx4 v203, v[64:67], s[98:99] offset:16
	s_add_u32 s42, s10, 0xa0000
	s_addc_u32 s43, s11, 0
	global_load_dwordx4 v[168:171], v203, s[42:43]
	s_waitcnt vmcnt(16)
	v_pk_fma_f32 v[60:61], v[148:149], v[60:61], v[172:173]
	v_pk_fma_f32 v[62:63], v[150:151], v[62:63], v[174:175]
	s_add_u32 s98, s10, 0x80000
	s_addc_u32 s99, s11, 0
	global_store_dwordx4 v203, v[60:63], s[98:99]
	s_add_u32 s42, s10, 0xa0000
	s_addc_u32 s43, s11, 0
	global_load_dwordx4 v[172:175], v203, s[42:43] offset:16
	s_waitcnt vmcnt(16)
	v_pk_fma_f32 v[56:57], v[144:145], v[56:57], v[176:177]
	v_pk_fma_f32 v[58:59], v[146:147], v[58:59], v[178:179]
	s_add_u32 s98, s10, 0x80000
	s_addc_u32 s99, s11, 0
	global_store_dwordx4 v203, v[56:59], s[98:99] offset:16
	s_add_u32 s42, s10, 0xa0200
	s_addc_u32 s43, s11, 0
	global_load_dwordx4 v[176:179], v203, s[42:43]
	s_waitcnt vmcnt(16)
	v_pk_fma_f32 v[28:29], v[156:157], v[28:29], v[180:181]
	v_pk_fma_f32 v[30:31], v[158:159], v[30:31], v[182:183]
	s_add_u32 s98, s10, 0x80200
	s_addc_u32 s99, s11, 0
	global_store_dwordx4 v203, v[28:31], s[98:99]
	s_add_u32 s42, s10, 0xa0200
	s_addc_u32 s43, s11, 0
	global_load_dwordx4 v[180:183], v203, s[42:43] offset:16
	s_waitcnt vmcnt(16)
	v_pk_fma_f32 v[24:25], v[152:153], v[24:25], v[206:207]
	v_pk_fma_f32 v[26:27], v[154:155], v[26:27], v[208:209]
	s_add_u32 s98, s10, 0x80200
	s_addc_u32 s99, s11, 0
	global_store_dwordx4 v203, v[24:27], s[98:99] offset:16
	s_add_u32 s42, s10, 0xb0000
	s_addc_u32 s43, s11, 0
	global_load_dwordx4 v[206:209], v203, s[42:43]
	s_waitcnt vmcnt(16)
	v_pk_fma_f32 v[52:53], v[148:149], v[52:53], v[210:211]
	v_pk_fma_f32 v[54:55], v[150:151], v[54:55], v[212:213]
	s_add_u32 s98, s10, 0x90000
	s_addc_u32 s99, s11, 0
	global_store_dwordx4 v203, v[52:55], s[98:99]
	s_add_u32 s42, s10, 0xb0000
	s_addc_u32 s43, s11, 0
	global_load_dwordx4 v[210:213], v203, s[42:43] offset:16
	s_waitcnt vmcnt(16)
	v_pk_fma_f32 v[48:49], v[144:145], v[48:49], v[236:237]
	v_pk_fma_f32 v[50:51], v[146:147], v[50:51], v[238:239]
	s_add_u32 s98, s10, 0x90000
	s_addc_u32 s99, s11, 0
	global_store_dwordx4 v203, v[48:51], s[98:99] offset:16
	s_add_u32 s42, s10, 0xb0200
	s_addc_u32 s43, s11, 0
	global_load_dwordx4 v[236:239], v203, s[42:43]
	s_waitcnt vmcnt(16)
	v_pk_fma_f32 v[20:21], v[156:157], v[20:21], v[160:161]
	v_pk_fma_f32 v[22:23], v[158:159], v[22:23], v[162:163]
	s_add_u32 s98, s10, 0x90200
	s_addc_u32 s99, s11, 0
	global_store_dwordx4 v203, v[20:23], s[98:99]
	s_add_u32 s42, s10, 0xb0200
	s_addc_u32 s43, s11, 0
	global_load_dwordx4 v[160:163], v203, s[42:43] offset:16
	s_waitcnt vmcnt(16)
	v_pk_fma_f32 v[16:17], v[152:153], v[16:17], v[164:165]
	v_pk_fma_f32 v[18:19], v[154:155], v[18:19], v[166:167]
	s_add_u32 s98, s10, 0x90200
	s_addc_u32 s99, s11, 0
	global_store_dwordx4 v203, v[16:19], s[98:99] offset:16
	s_waitcnt vmcnt(15)
	v_pk_fma_f32 v[44:45], v[148:149], v[44:45], v[168:169]
	v_pk_fma_f32 v[46:47], v[150:151], v[46:47], v[170:171]
	s_add_u32 s42, s10, 0xa0000
	s_addc_u32 s43, s11, 0
	global_store_dwordx4 v203, v[44:47], s[42:43]
	s_waitcnt vmcnt(14)
	v_pk_fma_f32 v[40:41], v[144:145], v[40:41], v[172:173]
	v_pk_fma_f32 v[42:43], v[146:147], v[42:43], v[174:175]
	s_add_u32 s98, s10, 0xa0000
	s_addc_u32 s99, s11, 0
	global_store_dwordx4 v203, v[40:43], s[98:99] offset:16
	s_waitcnt vmcnt(13)
	v_pk_fma_f32 v[12:13], v[156:157], v[12:13], v[176:177]
	v_pk_fma_f32 v[14:15], v[158:159], v[14:15], v[178:179]
	s_add_u32 s42, s10, 0xa0200
	s_addc_u32 s43, s11, 0
	global_store_dwordx4 v203, v[12:15], s[42:43]
	s_waitcnt vmcnt(12)
	v_pk_fma_f32 v[8:9], v[152:153], v[8:9], v[180:181]
	v_pk_fma_f32 v[10:11], v[154:155], v[10:11], v[182:183]
	s_add_u32 s98, s10, 0xa0200
	s_addc_u32 s99, s11, 0
	global_store_dwordx4 v203, v[8:11], s[98:99] offset:16
	s_waitcnt vmcnt(11)
	v_pk_fma_f32 v[36:37], v[148:149], v[36:37], v[206:207]
	v_pk_fma_f32 v[38:39], v[150:151], v[38:39], v[208:209]
	s_add_u32 s42, s10, 0xb0000
	s_addc_u32 s43, s11, 0
	global_store_dwordx4 v203, v[36:39], s[42:43]
	s_waitcnt vmcnt(10)
	v_pk_fma_f32 v[32:33], v[144:145], v[32:33], v[210:211]
	v_pk_fma_f32 v[34:35], v[146:147], v[34:35], v[212:213]
	s_add_u32 s98, s10, 0xb0000
	s_addc_u32 s99, s11, 0
	global_store_dwordx4 v203, v[32:35], s[98:99] offset:16
	s_waitcnt vmcnt(9)
	v_pk_fma_f32 v[4:5], v[156:157], v[4:5], v[236:237]
	v_pk_fma_f32 v[6:7], v[158:159], v[6:7], v[238:239]
	s_add_u32 s42, s10, 0xb0200
	s_addc_u32 s43, s11, 0
	global_store_dwordx4 v203, v[4:7], s[42:43]
	s_waitcnt vmcnt(8)
	v_pk_fma_f32 v[0:1], v[152:153], v[0:1], v[160:161]
	v_pk_fma_f32 v[2:3], v[154:155], v[2:3], v[162:163]
	s_add_u32 s98, s10, 0xb0200
	s_addc_u32 s99, s11, 0
	global_store_dwordx4 v203, v[0:3], s[98:99] offset:16
	s_branch .Lfq_predone
.Lfq_np1:
	s_add_u32 s42, s62, 0x0
	s_addc_u32 s43, s63, 0
	global_load_dwordx4 v[160:163], v205, s[42:43] sc0 sc1
	s_add_u32 s98, s62, 0x1000
	s_addc_u32 s99, s63, 0
	global_load_dwordx4 v[164:167], v205, s[98:99] sc0 sc1
	s_add_u32 s42, s62, 0x400
	s_addc_u32 s43, s63, 0
	global_load_dwordx4 v[168:171], v205, s[42:43] sc0 sc1
	s_add_u32 s98, s62, 0x1400
	s_addc_u32 s99, s63, 0
	global_load_dwordx4 v[172:175], v205, s[98:99] sc0 sc1
	s_add_u32 s42, s62, 0x800
	s_addc_u32 s43, s63, 0
	global_load_dwordx4 v[176:179], v205, s[42:43] sc0 sc1
	s_add_u32 s98, s62, 0x1800
	s_addc_u32 s99, s63, 0
	global_load_dwordx4 v[180:183], v205, s[98:99] sc0 sc1
	s_add_u32 s42, s62, 0xc00
	s_addc_u32 s43, s63, 0
	global_load_dwordx4 v[206:209], v205, s[42:43] sc0 sc1
	s_add_u32 s98, s62, 0x1c00
	s_addc_u32 s99, s63, 0
	global_load_dwordx4 v[210:213], v205, s[98:99] sc0 sc1
	s_add_u32 s42, s62, 0x2000
	s_addc_u32 s43, s63, 0
	global_load_dwordx4 v[236:239], v205, s[42:43] sc0 sc1
	s_waitcnt vmcnt(8)
	v_lshlrev_b32_e32 v240, 16, v160
	v_and_b32_e32 v241, 0xffff0000, v160
	v_pk_add_f32 v[124:125], v[124:125], v[240:241]
	v_lshlrev_b32_e32 v240, 16, v161
	v_and_b32_e32 v241, 0xffff0000, v161
	v_pk_add_f32 v[126:127], v[126:127], v[240:241]
	v_lshlrev_b32_e32 v240, 16, v162
	v_and_b32_e32 v241, 0xffff0000, v162
	v_pk_add_f32 v[120:121], v[120:121], v[240:241]
	v_lshlrev_b32_e32 v240, 16, v163
	v_and_b32_e32 v241, 0xffff0000, v163
	v_pk_add_f32 v[122:123], v[122:123], v[240:241]
	s_add_u32 s98, s62, 0x3000
	s_addc_u32 s99, s63, 0
	global_load_dwordx4 v[160:163], v205, s[98:99] sc0 sc1
	s_waitcnt vmcnt(8)
	v_lshlrev_b32_e32 v240, 16, v164
	v_and_b32_e32 v241, 0xffff0000, v164
	v_pk_add_f32 v[92:93], v[92:93], v[240:241]
	v_lshlrev_b32_e32 v240, 16, v165
	v_and_b32_e32 v241, 0xffff0000, v165
	v_pk_add_f32 v[94:95], v[94:95], v[240:241]
	v_lshlrev_b32_e32 v240, 16, v166
	v_and_b32_e32 v241, 0xffff0000, v166
	v_pk_add_f32 v[88:89], v[88:89], v[240:241]
	v_lshlrev_b32_e32 v240, 16, v167
	v_and_b32_e32 v241, 0xffff0000, v167
	v_pk_add_f32 v[90:91], v[90:91], v[240:241]
	s_add_u32 s42, s62, 0x2400
	s_addc_u32 s43, s63, 0
	global_load_dwordx4 v[164:167], v205, s[42:43] sc0 sc1
	s_waitcnt vmcnt(8)
	v_lshlrev_b32_e32 v240, 16, v168
	v_and_b32_e32 v241, 0xffff0000, v168
	v_pk_add_f32 v[116:117], v[116:117], v[240:241]
	v_lshlrev_b32_e32 v240, 16, v169
	v_and_b32_e32 v241, 0xffff0000, v169
	v_pk_add_f32 v[118:119], v[118:119], v[240:241]
	v_lshlrev_b32_e32 v240, 16, v170
	v_and_b32_e32 v241, 0xffff0000, v170
	v_pk_add_f32 v[112:113], v[112:113], v[240:241]
	v_lshlrev_b32_e32 v240, 16, v171
	v_and_b32_e32 v241, 0xffff0000, v171
	v_pk_add_f32 v[114:115], v[114:115], v[240:241]
	s_add_u32 s98, s62, 0x3400
	s_addc_u32 s99, s63, 0
	global_load_dwordx4 v[168:171], v205, s[98:99] sc0 sc1
	s_waitcnt vmcnt(8)
	v_lshlrev_b32_e32 v240, 16, v172
	v_and_b32_e32 v241, 0xffff0000, v172
	v_pk_add_f32 v[84:85], v[84:85], v[240:241]
	v_lshlrev_b32_e32 v240, 16, v173
	v_and_b32_e32 v241, 0xffff0000, v173
	v_pk_add_f32 v[86:87], v[86:87], v[240:241]
	v_lshlrev_b32_e32 v240, 16, v174
	v_and_b32_e32 v241, 0xffff0000, v174
	v_pk_add_f32 v[80:81], v[80:81], v[240:241]
	v_lshlrev_b32_e32 v240, 16, v175
	v_and_b32_e32 v241, 0xffff0000, v175
	v_pk_add_f32 v[82:83], v[82:83], v[240:241]
	s_add_u32 s42, s62, 0x2800
	s_addc_u32 s43, s63, 0
	global_load_dwordx4 v[172:175], v205, s[42:43] sc0 sc1
	s_waitcnt vmcnt(8)
	v_lshlrev_b32_e32 v240, 16, v176
	v_and_b32_e32 v241, 0xffff0000, v176
	v_pk_add_f32 v[108:109], v[108:109], v[240:241]
	v_lshlrev_b32_e32 v240, 16, v177
	v_and_b32_e32 v241, 0xffff0000, v177
	v_pk_add_f32 v[110:111], v[110:111], v[240:241]
	v_lshlrev_b32_e32 v240, 16, v178
	v_and_b32_e32 v241, 0xffff0000, v178
	v_pk_add_f32 v[104:105], v[104:105], v[240:241]
	v_lshlrev_b32_e32 v240, 16, v179
	v_and_b32_e32 v241, 0xffff0000, v179
	v_pk_add_f32 v[106:107], v[106:107], v[240:241]
	s_add_u32 s98, s62, 0x3800
	s_addc_u32 s99, s63, 0
	global_load_dwordx4 v[176:179], v205, s[98:99] sc0 sc1
	s_waitcnt vmcnt(8)
	v_lshlrev_b32_e32 v240, 16, v180
	v_and_b32_e32 v241, 0xffff0000, v180
	v_pk_add_f32 v[76:77], v[76:77], v[240:241]
	v_lshlrev_b32_e32 v240, 16, v181
	v_and_b32_e32 v241, 0xffff0000, v181
	v_pk_add_f32 v[78:79], v[78:79], v[240:241]
	v_lshlrev_b32_e32 v240, 16, v182
	v_and_b32_e32 v241, 0xffff0000, v182
	v_pk_add_f32 v[72:73], v[72:73], v[240:241]
	v_lshlrev_b32_e32 v240, 16, v183
	v_and_b32_e32 v241, 0xffff0000, v183
	v_pk_add_f32 v[74:75], v[74:75], v[240:241]
	s_add_u32 s42, s62, 0x2c00
	s_addc_u32 s43, s63, 0
	global_load_dwordx4 v[180:183], v205, s[42:43] sc0 sc1
	s_waitcnt vmcnt(8)
	v_lshlrev_b32_e32 v240, 16, v206
	v_and_b32_e32 v241, 0xffff0000, v206
	v_pk_add_f32 v[100:101], v[100:101], v[240:241]
	v_lshlrev_b32_e32 v240, 16, v207
	v_and_b32_e32 v241, 0xffff0000, v207
	v_pk_add_f32 v[102:103], v[102:103], v[240:241]
	v_lshlrev_b32_e32 v240, 16, v208
	v_and_b32_e32 v241, 0xffff0000, v208
	v_pk_add_f32 v[96:97], v[96:97], v[240:241]
	v_lshlrev_b32_e32 v240, 16, v209
	v_and_b32_e32 v241, 0xffff0000, v209
	v_pk_add_f32 v[98:99], v[98:99], v[240:241]
	s_add_u32 s98, s62, 0x3c00
	s_addc_u32 s99, s63, 0
	global_load_dwordx4 v[206:209], v205, s[98:99] sc0 sc1
	s_waitcnt vmcnt(8)
	v_lshlrev_b32_e32 v240, 16, v210
	v_and_b32_e32 v241, 0xffff0000, v210
	v_pk_add_f32 v[68:69], v[68:69], v[240:241]
	v_lshlrev_b32_e32 v240, 16, v211
	v_and_b32_e32 v241, 0xffff0000, v211
	v_pk_add_f32 v[70:71], v[70:71], v[240:241]
	v_lshlrev_b32_e32 v240, 16, v212
	v_and_b32_e32 v241, 0xffff0000, v212
	v_pk_add_f32 v[64:65], v[64:65], v[240:241]
	v_lshlrev_b32_e32 v240, 16, v213
	v_and_b32_e32 v241, 0xffff0000, v213
	v_pk_add_f32 v[66:67], v[66:67], v[240:241]
	s_add_u32 s42, s10, 0x0
	s_addc_u32 s43, s11, 0
	global_load_dwordx4 v[210:213], v203, s[42:43]
	s_waitcnt vmcnt(8)
	v_lshlrev_b32_e32 v240, 16, v236
	v_and_b32_e32 v241, 0xffff0000, v236
	v_pk_add_f32 v[60:61], v[60:61], v[240:241]
	v_lshlrev_b32_e32 v240, 16, v237
	v_and_b32_e32 v241, 0xffff0000, v237
	v_pk_add_f32 v[62:63], v[62:63], v[240:241]
	v_lshlrev_b32_e32 v240, 16, v238
	v_and_b32_e32 v241, 0xffff0000, v238
	v_pk_add_f32 v[56:57], v[56:57], v[240:241]
	v_lshlrev_b32_e32 v240, 16, v239
	v_and_b32_e32 v241, 0xffff0000, v239
	v_pk_add_f32 v[58:59], v[58:59], v[240:241]
	s_add_u32 s98, s10, 0x0
	s_addc_u32 s99, s11, 0
	global_load_dwordx4 v[236:239], v203, s[98:99] offset:16
	s_waitcnt vmcnt(8)
	v_lshlrev_b32_e32 v240, 16, v160
	v_and_b32_e32 v241, 0xffff0000, v160
	v_pk_add_f32 v[28:29], v[28:29], v[240:241]
	v_lshlrev_b32_e32 v240, 16, v161
	v_and_b32_e32 v241, 0xffff0000, v161
	v_pk_add_f32 v[30:31], v[30:31], v[240:241]
	v_lshlrev_b32_e32 v240, 16, v162
	v_and_b32_e32 v241, 0xffff0000, v162
	v_pk_add_f32 v[24:25], v[24:25], v[240:241]
	v_lshlrev_b32_e32 v240, 16, v163
	v_and_b32_e32 v241, 0xffff0000, v163
	v_pk_add_f32 v[26:27], v[26:27], v[240:241]
	s_add_u32 s42, s10, 0x200
	s_addc_u32 s43, s11, 0
	global_load_dwordx4 v[160:163], v203, s[42:43]
	s_waitcnt vmcnt(8)
	v_lshlrev_b32_e32 v240, 16, v164
	v_and_b32_e32 v241, 0xffff0000, v164
	v_pk_add_f32 v[52:53], v[52:53], v[240:241]
	v_lshlrev_b32_e32 v240, 16, v165
	v_and_b32_e32 v241, 0xffff0000, v165
	v_pk_add_f32 v[54:55], v[54:55], v[240:241]
	v_lshlrev_b32_e32 v240, 16, v166
	v_and_b32_e32 v241, 0xffff0000, v166
	v_pk_add_f32 v[48:49], v[48:49], v[240:241]
	v_lshlrev_b32_e32 v240, 16, v167
	v_and_b32_e32 v241, 0xffff0000, v167
	v_pk_add_f32 v[50:51], v[50:51], v[240:241]
	s_add_u32 s98, s10, 0x200
	s_addc_u32 s99, s11, 0
	global_load_dwordx4 v[164:167], v203, s[98:99] offset:16
	s_waitcnt vmcnt(8)
	v_lshlrev_b32_e32 v240, 16, v168
	v_and_b32_e32 v241, 0xffff0000, v168
	v_pk_add_f32 v[20:21], v[20:21], v[240:241]
	v_lshlrev_b32_e32 v240, 16, v169
	v_and_b32_e32 v241, 0xffff0000, v169
	v_pk_add_f32 v[22:23], v[22:23], v[240:241]
	v_lshlrev_b32_e32 v240, 16, v170
	v_and_b32_e32 v241, 0xffff0000, v170
	v_pk_add_f32 v[16:17], v[16:17], v[240:241]
	v_lshlrev_b32_e32 v240, 16, v171
	v_and_b32_e32 v241, 0xffff0000, v171
	v_pk_add_f32 v[18:19], v[18:19], v[240:241]
	s_add_u32 s42, s10, 0x10000
	s_addc_u32 s43, s11, 0
	global_load_dwordx4 v[168:171], v203, s[42:43]
	s_waitcnt vmcnt(8)
	v_lshlrev_b32_e32 v240, 16, v172
	v_and_b32_e32 v241, 0xffff0000, v172
	v_pk_add_f32 v[44:45], v[44:45], v[240:241]
	v_lshlrev_b32_e32 v240, 16, v173
	v_and_b32_e32 v241, 0xffff0000, v173
	v_pk_add_f32 v[46:47], v[46:47], v[240:241]
	v_lshlrev_b32_e32 v240, 16, v174
	v_and_b32_e32 v241, 0xffff0000, v174
	v_pk_add_f32 v[40:41], v[40:41], v[240:241]
	v_lshlrev_b32_e32 v240, 16, v175
	v_and_b32_e32 v241, 0xffff0000, v175
	v_pk_add_f32 v[42:43], v[42:43], v[240:241]
	s_add_u32 s98, s10, 0x10000
	s_addc_u32 s99, s11, 0
	global_load_dwordx4 v[172:175], v203, s[98:99] offset:16
	s_waitcnt vmcnt(8)
	v_lshlrev_b32_e32 v240, 16, v176
	v_and_b32_e32 v241, 0xffff0000, v176
	v_pk_add_f32 v[12:13], v[12:13], v[240:241]
	v_lshlrev_b32_e32 v240, 16, v177
	v_and_b32_e32 v241, 0xffff0000, v177
	v_pk_add_f32 v[14:15], v[14:15], v[240:241]
	v_lshlrev_b32_e32 v240, 16, v178
	v_and_b32_e32 v241, 0xffff0000, v178
	v_pk_add_f32 v[8:9], v[8:9], v[240:241]
	v_lshlrev_b32_e32 v240, 16, v179
	v_and_b32_e32 v241, 0xffff0000, v179
	v_pk_add_f32 v[10:11], v[10:11], v[240:241]
	s_add_u32 s42, s10, 0x10200
	s_addc_u32 s43, s11, 0
	global_load_dwordx4 v[176:179], v203, s[42:43]
	s_waitcnt vmcnt(8)
	v_lshlrev_b32_e32 v240, 16, v180
	v_and_b32_e32 v241, 0xffff0000, v180
	v_pk_add_f32 v[36:37], v[36:37], v[240:241]
	v_lshlrev_b32_e32 v240, 16, v181
	v_and_b32_e32 v241, 0xffff0000, v181
	v_pk_add_f32 v[38:39], v[38:39], v[240:241]
	v_lshlrev_b32_e32 v240, 16, v182
	v_and_b32_e32 v241, 0xffff0000, v182
	v_pk_add_f32 v[32:33], v[32:33], v[240:241]
	v_lshlrev_b32_e32 v240, 16, v183
	v_and_b32_e32 v241, 0xffff0000, v183
	v_pk_add_f32 v[34:35], v[34:35], v[240:241]
	s_add_u32 s98, s10, 0x10200
	s_addc_u32 s99, s11, 0
	global_load_dwordx4 v[180:183], v203, s[98:99] offset:16
	s_waitcnt vmcnt(8)
	v_lshlrev_b32_e32 v240, 16, v206
	v_and_b32_e32 v241, 0xffff0000, v206
	v_pk_add_f32 v[4:5], v[4:5], v[240:241]
	v_lshlrev_b32_e32 v240, 16, v207
	v_and_b32_e32 v241, 0xffff0000, v207
	v_pk_add_f32 v[6:7], v[6:7], v[240:241]
	v_lshlrev_b32_e32 v240, 16, v208
	v_and_b32_e32 v241, 0xffff0000, v208
	v_pk_add_f32 v[0:1], v[0:1], v[240:241]
	v_lshlrev_b32_e32 v240, 16, v209
	v_and_b32_e32 v241, 0xffff0000, v209
	v_pk_add_f32 v[2:3], v[2:3], v[240:241]
	s_add_u32 s42, s10, 0x20000
	s_addc_u32 s43, s11, 0
	global_load_dwordx4 v[206:209], v203, s[42:43]
	s_waitcnt vmcnt(8)
	v_pk_fma_f32 v[124:125], v[148:149], v[124:125], v[210:211]
	v_pk_fma_f32 v[126:127], v[150:151], v[126:127], v[212:213]
	s_add_u32 s98, s10, 0x0
	s_addc_u32 s99, s11, 0
	global_store_dwordx4 v203, v[124:127], s[98:99]
	s_add_u32 s42, s10, 0x20000
	s_addc_u32 s43, s11, 0
	global_load_dwordx4 v[210:213], v203, s[42:43] offset:16
	s_waitcnt vmcnt(9)
	v_pk_fma_f32 v[120:121], v[144:145], v[120:121], v[236:237]
	v_pk_fma_f32 v[122:123], v[146:147], v[122:123], v[238:239]
	s_add_u32 s98, s10, 0x0
	s_addc_u32 s99, s11, 0
	global_store_dwordx4 v203, v[120:123], s[98:99] offset:16
	s_add_u32 s42, s10, 0x20200
	s_addc_u32 s43, s11, 0
	global_load_dwordx4 v[236:239], v203, s[42:43]
	s_waitcnt vmcnt(10)
	v_pk_fma_f32 v[92:93], v[156:157], v[92:93], v[160:161]
	v_pk_fma_f32 v[94:95], v[158:159], v[94:95], v[162:163]
	s_add_u32 s98, s10, 0x200
	s_addc_u32 s99, s11, 0
	global_store_dwordx4 v203, v[92:95], s[98:99]
	s_add_u32 s42, s10, 0x20200
	s_addc_u32 s43, s11, 0
	global_load_dwordx4 v[160:163], v203, s[42:43] offset:16
	s_waitcnt vmcnt(11)
	v_pk_fma_f32 v[88:89], v[152:153], v[88:89], v[164:165]
	v_pk_fma_f32 v[90:91], v[154:155], v[90:91], v[166:167]
	s_add_u32 s98, s10, 0x200
	s_addc_u32 s99, s11, 0
	global_store_dwordx4 v203, v[88:91], s[98:99] offset:16
	s_add_u32 s42, s10, 0x30000
	s_addc_u32 s43, s11, 0
	global_load_dwordx4 v[164:167], v203, s[42:43]
	s_waitcnt vmcnt(12)
	v_pk_fma_f32 v[116:117], v[148:149], v[116:117], v[168:169]
	v_pk_fma_f32 v[118:119], v[150:151], v[118:119], v[170:171]
	s_add_u32 s98, s10, 0x10000
	s_addc_u32 s99, s11, 0
	global_store_dwordx4 v203, v[116:119], s[98:99]
	s_add_u32 s42, s10, 0x30000
	s_addc_u32 s43, s11, 0
	global_load_dwordx4 v[168:171], v203, s[42:43] offset:16
	s_waitcnt vmcnt(13)
	v_pk_fma_f32 v[112:113], v[144:145], v[112:113], v[172:173]
	v_pk_fma_f32 v[114:115], v[146:147], v[114:115], v[174:175]
	s_add_u32 s98, s10, 0x10000
	s_addc_u32 s99, s11, 0
	global_store_dwordx4 v203, v[112:115], s[98:99] offset:16
	s_add_u32 s42, s10, 0x30200
	s_addc_u32 s43, s11, 0
	global_load_dwordx4 v[172:175], v203, s[42:43]
	s_waitcnt vmcnt(14)
	v_pk_fma_f32 v[84:85], v[156:157], v[84:85], v[176:177]
	v_pk_fma_f32 v[86:87], v[158:159], v[86:87], v[178:179]
	s_add_u32 s98, s10, 0x10200
	s_addc_u32 s99, s11, 0
	global_store_dwordx4 v203, v[84:87], s[98:99]
	s_add_u32 s42, s10, 0x30200
	s_addc_u32 s43, s11, 0
	global_load_dwordx4 v[176:179], v203, s[42:43] offset:16
	s_waitcnt vmcnt(15)
	v_pk_fma_f32 v[80:81], v[152:153], v[80:81], v[180:181]
	v_pk_fma_f32 v[82:83], v[154:155], v[82:83], v[182:183]
	s_add_u32 s98, s10, 0x10200
	s_addc_u32 s99, s11, 0
	global_store_dwordx4 v203, v[80:83], s[98:99] offset:16
	s_add_u32 s42, s10, 0x80000
	s_addc_u32 s43, s11, 0
	global_load_dwordx4 v[180:183], v203, s[42:43]
	s_waitcnt vmcnt(16)
	v_pk_fma_f32 v[108:109], v[148:149], v[108:109], v[206:207]
	v_pk_fma_f32 v[110:111], v[150:151], v[110:111], v[208:209]
	s_add_u32 s98, s10, 0x20000
	s_addc_u32 s99, s11, 0
	global_store_dwordx4 v203, v[108:111], s[98:99]
	s_add_u32 s42, s10, 0x80000
	s_addc_u32 s43, s11, 0
	global_load_dwordx4 v[206:209], v203, s[42:43] offset:16
	s_waitcnt vmcnt(16)
	v_pk_fma_f32 v[104:105], v[144:145], v[104:105], v[210:211]
	v_pk_fma_f32 v[106:107], v[146:147], v[106:107], v[212:213]
	s_add_u32 s98, s10, 0x20000
	s_addc_u32 s99, s11, 0
	global_store_dwordx4 v203, v[104:107], s[98:99] offset:16
	s_add_u32 s42, s10, 0x80200
	s_addc_u32 s43, s11, 0
	global_load_dwordx4 v[210:213], v203, s[42:43]
	s_waitcnt vmcnt(16)
	v_pk_fma_f32 v[76:77], v[156:157], v[76:77], v[236:237]
	v_pk_fma_f32 v[78:79], v[158:159], v[78:79], v[238:239]
	s_add_u32 s98, s10, 0x20200
	s_addc_u32 s99, s11, 0
	global_store_dwordx4 v203, v[76:79], s[98:99]
	s_add_u32 s42, s10, 0x80200
	s_addc_u32 s43, s11, 0
	global_load_dwordx4 v[236:239], v203, s[42:43] offset:16
	s_waitcnt vmcnt(16)
	v_pk_fma_f32 v[72:73], v[152:153], v[72:73], v[160:161]
	v_pk_fma_f32 v[74:75], v[154:155], v[74:75], v[162:163]
	s_add_u32 s98, s10, 0x20200
	s_addc_u32 s99, s11, 0
	global_store_dwordx4 v203, v[72:75], s[98:99] offset:16
	s_add_u32 s42, s10, 0x90000
	s_addc_u32 s43, s11, 0
	global_load_dwordx4 v[160:163], v203, s[42:43]
	s_waitcnt vmcnt(16)
	v_pk_fma_f32 v[100:101], v[148:149], v[100:101], v[164:165]
	v_pk_fma_f32 v[102:103], v[150:151], v[102:103], v[166:167]
	s_add_u32 s98, s10, 0x30000
	s_addc_u32 s99, s11, 0
	global_store_dwordx4 v203, v[100:103], s[98:99]
	s_add_u32 s42, s10, 0x90000
	s_addc_u32 s43, s11, 0
	global_load_dwordx4 v[164:167], v203, s[42:43] offset:16
	s_waitcnt vmcnt(16)
	v_pk_fma_f32 v[96:97], v[144:145], v[96:97], v[168:169]
	v_pk_fma_f32 v[98:99], v[146:147], v[98:99], v[170:171]
	s_add_u32 s98, s10, 0x30000
	s_addc_u32 s99, s11, 0
	global_store_dwordx4 v203, v[96:99], s[98:99] offset:16
	s_add_u32 s42, s10, 0x90200
	s_addc_u32 s43, s11, 0
	global_load_dwordx4 v[168:171], v203, s[42:43]
	s_waitcnt vmcnt(16)
	v_pk_fma_f32 v[68:69], v[156:157], v[68:69], v[172:173]
	v_pk_fma_f32 v[70:71], v[158:159], v[70:71], v[174:175]
	s_add_u32 s98, s10, 0x30200
	s_addc_u32 s99, s11, 0
	global_store_dwordx4 v203, v[68:71], s[98:99]
	s_add_u32 s42, s10, 0x90200
	s_addc_u32 s43, s11, 0
	global_load_dwordx4 v[172:175], v203, s[42:43] offset:16
	s_waitcnt vmcnt(16)
	v_pk_fma_f32 v[64:65], v[152:153], v[64:65], v[176:177]
	v_pk_fma_f32 v[66:67], v[154:155], v[66:67], v[178:179]
	s_add_u32 s98, s10, 0x30200
	s_addc_u32 s99, s11, 0
	global_store_dwordx4 v203, v[64:67], s[98:99] offset:16
	s_add_u32 s42, s10, 0xa0000
	s_addc_u32 s43, s11, 0
	global_load_dwordx4 v[176:179], v203, s[42:43]
	s_waitcnt vmcnt(16)
	v_pk_fma_f32 v[60:61], v[148:149], v[60:61], v[180:181]
	v_pk_fma_f32 v[62:63], v[150:151], v[62:63], v[182:183]
	s_add_u32 s98, s10, 0x80000
	s_addc_u32 s99, s11, 0
	global_store_dwordx4 v203, v[60:63], s[98:99]
	s_add_u32 s42, s10, 0xa0000
	s_addc_u32 s43, s11, 0
	global_load_dwordx4 v[180:183], v203, s[42:43] offset:16
	s_waitcnt vmcnt(16)
	v_pk_fma_f32 v[56:57], v[144:145], v[56:57], v[206:207]
	v_pk_fma_f32 v[58:59], v[146:147], v[58:59], v[208:209]
	s_add_u32 s98, s10, 0x80000
	s_addc_u32 s99, s11, 0
	global_store_dwordx4 v203, v[56:59], s[98:99] offset:16
	s_add_u32 s42, s10, 0xa0200
	s_addc_u32 s43, s11, 0
	global_load_dwordx4 v[206:209], v203, s[42:43]
	s_waitcnt vmcnt(16)
	v_pk_fma_f32 v[28:29], v[156:157], v[28:29], v[210:211]
	v_pk_fma_f32 v[30:31], v[158:159], v[30:31], v[212:213]
	s_add_u32 s98, s10, 0x80200
	s_addc_u32 s99, s11, 0
	global_store_dwordx4 v203, v[28:31], s[98:99]
	s_add_u32 s42, s10, 0xa0200
	s_addc_u32 s43, s11, 0
	global_load_dwordx4 v[210:213], v203, s[42:43] offset:16
	s_waitcnt vmcnt(16)
	v_pk_fma_f32 v[24:25], v[152:153], v[24:25], v[236:237]
	v_pk_fma_f32 v[26:27], v[154:155], v[26:27], v[238:239]
	s_add_u32 s98, s10, 0x80200
	s_addc_u32 s99, s11, 0
	global_store_dwordx4 v203, v[24:27], s[98:99] offset:16
	s_add_u32 s42, s10, 0xb0000
	s_addc_u32 s43, s11, 0
	global_load_dwordx4 v[236:239], v203, s[42:43]
	s_waitcnt vmcnt(16)
	v_pk_fma_f32 v[52:53], v[148:149], v[52:53], v[160:161]
	v_pk_fma_f32 v[54:55], v[150:151], v[54:55], v[162:163]
	s_add_u32 s98, s10, 0x90000
	s_addc_u32 s99, s11, 0
	global_store_dwordx4 v203, v[52:55], s[98:99]
	s_add_u32 s42, s10, 0xb0000
	s_addc_u32 s43, s11, 0
	global_load_dwordx4 v[160:163], v203, s[42:43] offset:16
	s_waitcnt vmcnt(16)
	v_pk_fma_f32 v[48:49], v[144:145], v[48:49], v[164:165]
	v_pk_fma_f32 v[50:51], v[146:147], v[50:51], v[166:167]
	s_add_u32 s98, s10, 0x90000
	s_addc_u32 s99, s11, 0
	global_store_dwordx4 v203, v[48:51], s[98:99] offset:16
	s_add_u32 s42, s10, 0xb0200
	s_addc_u32 s43, s11, 0
	global_load_dwordx4 v[164:167], v203, s[42:43]
	s_waitcnt vmcnt(16)
	v_pk_fma_f32 v[20:21], v[156:157], v[20:21], v[168:169]
	v_pk_fma_f32 v[22:23], v[158:159], v[22:23], v[170:171]
	s_add_u32 s98, s10, 0x90200
	s_addc_u32 s99, s11, 0
	global_store_dwordx4 v203, v[20:23], s[98:99]
	s_add_u32 s42, s10, 0xb0200
	s_addc_u32 s43, s11, 0
	global_load_dwordx4 v[168:171], v203, s[42:43] offset:16
	s_waitcnt vmcnt(16)
	v_pk_fma_f32 v[16:17], v[152:153], v[16:17], v[172:173]
	v_pk_fma_f32 v[18:19], v[154:155], v[18:19], v[174:175]
	s_add_u32 s98, s10, 0x90200
	s_addc_u32 s99, s11, 0
	global_store_dwordx4 v203, v[16:19], s[98:99] offset:16
	s_waitcnt vmcnt(15)
	v_pk_fma_f32 v[44:45], v[148:149], v[44:45], v[176:177]
	v_pk_fma_f32 v[46:47], v[150:151], v[46:47], v[178:179]
	s_add_u32 s42, s10, 0xa0000
	s_addc_u32 s43, s11, 0
	global_store_dwordx4 v203, v[44:47], s[42:43]
	s_waitcnt vmcnt(14)
	v_pk_fma_f32 v[40:41], v[144:145], v[40:41], v[180:181]
	v_pk_fma_f32 v[42:43], v[146:147], v[42:43], v[182:183]
	s_add_u32 s98, s10, 0xa0000
	s_addc_u32 s99, s11, 0
	global_store_dwordx4 v203, v[40:43], s[98:99] offset:16
	s_waitcnt vmcnt(13)
	v_pk_fma_f32 v[12:13], v[156:157], v[12:13], v[206:207]
	v_pk_fma_f32 v[14:15], v[158:159], v[14:15], v[208:209]
	s_add_u32 s42, s10, 0xa0200
	s_addc_u32 s43, s11, 0
	global_store_dwordx4 v203, v[12:15], s[42:43]
	s_waitcnt vmcnt(12)
	v_pk_fma_f32 v[8:9], v[152:153], v[8:9], v[210:211]
	v_pk_fma_f32 v[10:11], v[154:155], v[10:11], v[212:213]
	s_add_u32 s98, s10, 0xa0200
	s_addc_u32 s99, s11, 0
	global_store_dwordx4 v203, v[8:11], s[98:99] offset:16
	s_waitcnt vmcnt(11)
	v_pk_fma_f32 v[36:37], v[148:149], v[36:37], v[236:237]
	v_pk_fma_f32 v[38:39], v[150:151], v[38:39], v[238:239]
	s_add_u32 s42, s10, 0xb0000
	s_addc_u32 s43, s11, 0
	global_store_dwordx4 v203, v[36:39], s[42:43]
	s_waitcnt vmcnt(10)
	v_pk_fma_f32 v[32:33], v[144:145], v[32:33], v[160:161]
	v_pk_fma_f32 v[34:35], v[146:147], v[34:35], v[162:163]
	s_add_u32 s98, s10, 0xb0000
	s_addc_u32 s99, s11, 0
	global_store_dwordx4 v203, v[32:35], s[98:99] offset:16
	s_waitcnt vmcnt(9)
	v_pk_fma_f32 v[4:5], v[156:157], v[4:5], v[164:165]
	v_pk_fma_f32 v[6:7], v[158:159], v[6:7], v[166:167]
	s_add_u32 s42, s10, 0xb0200
	s_addc_u32 s43, s11, 0
	global_store_dwordx4 v203, v[4:7], s[42:43]
	s_waitcnt vmcnt(8)
	v_pk_fma_f32 v[0:1], v[152:153], v[0:1], v[168:169]
	v_pk_fma_f32 v[2:3], v[154:155], v[2:3], v[170:171]
	s_add_u32 s98, s10, 0xb0200
	s_addc_u32 s99, s11, 0
	global_store_dwordx4 v203, v[0:3], s[98:99] offset:16

.Lfq_LBB0_1556:
	v_ashrrev_i32_e32 v179, 31, v178
	v_lshlrev_b64 v[160:161], 12, v[178:179]
	v_lshl_add_u64 v[182:183], s[10:11], 0, v[160:161]
	v_lshl_add_u64 v[202:203], v[200:201], 2, v[182:183]
	v_mov_b64_e32 v[174:175], v[38:39]
	v_mov_b64_e32 v[170:171], v[34:35]
	s_and_b64 vcc, exec, s[84:85]
	v_mov_b64_e32 v[172:173], v[36:37]
	v_mov_b64_e32 v[168:169], v[32:33]
	s_cbranch_vccnz .Lfq_LBB0_1561
	v_readlane_b32 s82, v242, 42
	v_readlane_b32 s83, v242, 43
	v_lshlrev_b32_e32 v180, 2, v194
	v_mov_b32_e32 v181, v185
	s_cmp_lt_i32 s30, 2
	v_lshl_add_u64 v[204:205], s[82:83], 0, v[180:181]
	flat_load_dwordx4 v[168:171], v[204:205]
	s_waitcnt vmcnt(0) lgkmcnt(0)
	v_lshlrev_b32_e32 v172, 16, v168
	v_and_b32_e32 v173, 0xffff0000, v168
	v_lshlrev_b32_e32 v168, 16, v169
	v_and_b32_e32 v169, 0xffff0000, v169
	v_lshlrev_b32_e32 v206, 16, v170
	v_and_b32_e32 v207, 0xffff0000, v170
	v_lshlrev_b32_e32 v170, 16, v171
	v_and_b32_e32 v171, 0xffff0000, v171
	v_pk_add_f32 v[174:175], v[38:39], v[168:169]
	v_pk_add_f32 v[172:173], v[36:37], v[172:173]
	v_pk_add_f32 v[170:171], v[34:35], v[170:171]
	v_pk_add_f32 v[168:169], v[32:33], v[206:207]
	s_cbranch_scc1 .Lfq_LBB0_1559
	v_add_co_u32_e32 v204, vcc, 0x20000, v204
	s_nop 1
	v_addc_co_u32_e32 v205, vcc, 0, v205, vcc
	flat_load_dwordx4 v[204:207], v[204:205]
	s_waitcnt vmcnt(0) lgkmcnt(0)
	v_lshlrev_b32_e32 v208, 16, v204
	v_and_b32_e32 v209, 0xffff0000, v204
	v_lshlrev_b32_e32 v204, 16, v205
	v_and_b32_e32 v205, 0xffff0000, v205
	v_pk_add_f32 v[174:175], v[174:175], v[204:205]
	v_lshlrev_b32_e32 v204, 16, v206
	v_and_b32_e32 v205, 0xffff0000, v206
	v_lshlrev_b32_e32 v206, 16, v207
	v_and_b32_e32 v207, 0xffff0000, v207
	v_pk_add_f32 v[172:173], v[172:173], v[208:209]
	v_pk_add_f32 v[170:171], v[170:171], v[206:207]
	v_pk_add_f32 v[168:169], v[168:169], v[204:205]

.Lfq_LBB0_1561:
	v_ashrrev_i32_e32 v177, 31, v176
	v_lshlrev_b64 v[180:181], 10, v[176:177]
	v_mov_b64_e32 v[150:151], v[38:39]
	v_mov_b64_e32 v[148:149], v[36:37]
	v_mov_b64_e32 v[146:147], v[34:35]
	v_mov_b64_e32 v[144:145], v[32:33]
	s_and_b64 vcc, exec, s[80:81]
	s_cbranch_vccnz .Lfq_LBB0_1563
	v_mul_f32_e32 v160, v140, v148
	v_mul_f32_e32 v161, v141, v149
	v_mul_f32_e32 v164, v136, v144
	v_mul_f32_e32 v165, v137, v145
	v_mov_b32_e32 v136, v185
	v_mov_b32_e32 v137, v185
	v_cvt_pk_fp8_f32 v136, v160, v161
	v_cvt_pk_fp8_f32 v137, v164, v165
	v_mul_f32_e32 v162, v142, v150
	v_mul_f32_e32 v163, v143, v151
	v_mul_f32_e32 v166, v138, v146
	v_mul_f32_e32 v167, v139, v147
	v_lshl_add_u64 v[138:139], v[180:181], 1, s[18:19]
	v_cvt_pk_fp8_f32 v136, v162, v163 op_sel:[0,0,1]
	v_cvt_pk_fp8_f32 v137, v166, v167 op_sel:[0,0,1]
	v_lshl_add_u64 v[138:139], v[200:201], 1, v[138:139]
	v_cvt_pk_bf16_f32 v140, v160, v161
	v_cvt_pk_bf16_f32 v141, v162, v163
	v_cvt_pk_bf16_f32 v142, v164, v165
	v_cvt_pk_bf16_f32 v143, v166, v167
	global_store_dwordx4 v[138:139], v[140:143], off
	v_lshl_add_u64 v[138:139], s[70:71], 0, v[180:181]
	v_lshl_add_u64 v[138:139], v[138:139], 0, v[200:201]
	global_store_dwordx2 v[138:139], v[136:137], off
.Lfq_LBB0_1563:
	v_lshl_add_u64 v[168:169], v[200:201], 2, v[182:183]
	v_mov_b64_e32 v[136:137], v[0:1]
	v_mov_b64_e32 v[138:139], v[2:3]
	v_mov_b64_e32 v[140:141], v[4:5]
	v_mov_b64_e32 v[142:143], v[6:7]
	v_mov_b64_e32 v[166:167], v[6:7]
	v_mov_b64_e32 v[162:163], v[2:3]
	s_and_b64 vcc, exec, s[84:85]
	v_mov_b64_e32 v[164:165], v[4:5]
	v_mov_b64_e32 v[160:161], v[0:1]
	s_mov_b32 s84, s40
	s_cbranch_vccnz .Lfq_LBB0_1568
	v_readlane_b32 s82, v242, 44
	v_readlane_b32 s83, v242, 45
	v_lshlrev_b32_e32 v170, 2, v194
	v_mov_b32_e32 v171, v185
	s_cmp_lt_i32 s30, 2
	v_lshl_add_u64 v[172:173], s[82:83], 0, v[170:171]
	flat_load_dwordx4 v[160:163], v[172:173]
	s_waitcnt vmcnt(0) lgkmcnt(0)
	v_lshlrev_b32_e32 v164, 16, v160
	v_and_b32_e32 v165, 0xffff0000, v160
	v_lshlrev_b32_e32 v160, 16, v161
	v_and_b32_e32 v161, 0xffff0000, v161
	v_lshlrev_b32_e32 v174, 16, v162
	v_and_b32_e32 v175, 0xffff0000, v162
	v_lshlrev_b32_e32 v162, 16, v163
	v_and_b32_e32 v163, 0xffff0000, v163
	v_pk_add_f32 v[166:167], v[6:7], v[160:161]
	v_pk_add_f32 v[164:165], v[4:5], v[164:165]
	v_pk_add_f32 v[162:163], v[2:3], v[162:163]
	v_pk_add_f32 v[160:161], v[0:1], v[174:175]
	s_cbranch_scc1 .Lfq_LBB0_1566
	v_add_co_u32_e32 v172, vcc, 0x20000, v172
	s_nop 1
	v_addc_co_u32_e32 v173, vcc, 0, v173, vcc
	flat_load_dwordx4 v[172:175], v[172:173]
	s_waitcnt vmcnt(0) lgkmcnt(0)
	v_lshlrev_b32_e32 v182, 16, v172
	v_and_b32_e32 v183, 0xffff0000, v172
	v_lshlrev_b32_e32 v172, 16, v173
	v_and_b32_e32 v173, 0xffff0000, v173
	v_pk_add_f32 v[166:167], v[166:167], v[172:173]
	v_lshlrev_b32_e32 v172, 16, v174
	v_and_b32_e32 v173, 0xffff0000, v174
	v_lshlrev_b32_e32 v174, 16, v175
	v_and_b32_e32 v175, 0xffff0000, v175
	v_pk_add_f32 v[164:165], v[164:165], v[182:183]
	v_pk_add_f32 v[162:163], v[162:163], v[174:175]
	v_pk_add_f32 v[160:161], v[160:161], v[172:173]

.Lfq_LBB0_1568:
	s_and_b64 vcc, exec, s[80:81]
	s_cbranch_vccnz .Lfq_LBB0_1570
	v_mul_f32_e32 v152, v132, v140
	v_mul_f32_e32 v153, v133, v141
	v_mul_f32_e32 v156, v128, v136
	v_mul_f32_e32 v157, v129, v137
	v_mov_b32_e32 v128, v185
	v_mov_b32_e32 v129, v185
	v_cvt_pk_fp8_f32 v128, v152, v153
	v_cvt_pk_fp8_f32 v129, v156, v157
	v_mul_f32_e32 v154, v134, v142
	v_mul_f32_e32 v155, v135, v143
	v_mul_f32_e32 v158, v130, v138
	v_mul_f32_e32 v159, v131, v139
	v_lshl_add_u64 v[130:131], v[180:181], 1, s[18:19]
	v_cvt_pk_fp8_f32 v128, v154, v155 op_sel:[0,0,1]
	v_cvt_pk_fp8_f32 v129, v158, v159 op_sel:[0,0,1]
	v_lshl_add_u64 v[130:131], v[200:201], 1, v[130:131]
	v_cvt_pk_bf16_f32 v132, v152, v153
	v_cvt_pk_bf16_f32 v133, v154, v155
	v_cvt_pk_bf16_f32 v134, v156, v157
	v_cvt_pk_bf16_f32 v135, v158, v159
	global_store_dwordx4 v[130:131], v[132:135], off offset:256
	v_lshl_add_u64 v[130:131], s[70:71], 0, v[180:181]
	v_lshl_add_u64 v[130:131], v[130:131], 0, v[200:201]
	global_store_dwordx2 v[130:131], v[128:129], off offset:128

.Lfs_LBB0_1420:
	s_lshl_b32 s31, s31, 8
	v_add_u32_e32 v202, s31, v224
	v_mov_b32_e32 v160, s92
	v_mov_b32_e32 v161, s93
	v_cmp_gt_i32_e32 vcc, s33, v202
	s_nop 1
	v_cndmask_b32_e32 v160, v160, v161, vcc
	v_cndmask_b32_e64 v161, 0, 1, s[84:85]
	v_cmp_ne_u32_e64 s[82:83], 1, v161
	v_add_u32_e32 v204, v202, v160
	v_lshlrev_b32_e32 v203, 12, v204
	v_lshl_add_u32 v203, v200, 2, v203
	v_lshlrev_b32_e32 v205, 2, v194
	v_add_u32_e32 v235, 0xffffc000, v204
	v_lshrrev_b32_e32 v235, 3, v235
	v_add_u32_e32 v235, 8, v235
	v_mul_u32_u24_e32 v235, 0xc000, v235
	v_lshl_add_u32 v235, v200, 2, v235
	s_cmp_eq_u32 s30, 1
	s_cbranch_scc1 .Lfs_np1
	s_cmp_eq_u32 s30, 2
	s_cbranch_scc1 .Lfs_np2
	s_add_u32 s42, s62, 0x0
	s_addc_u32 s43, s63, 0
	global_load_dwordx4 v[128:131], v205, s[42:43] sc0 sc1
	s_add_u32 s98, s62, 0x1000
	s_addc_u32 s99, s63, 0
	global_load_dwordx4 v[132:135], v205, s[98:99] sc0 sc1
	s_add_u32 s42, s62, 0x400
	s_addc_u32 s43, s63, 0
	global_load_dwordx4 v[136:139], v205, s[42:43] sc0 sc1
	s_add_u32 s98, s62, 0x1400
	s_addc_u32 s99, s63, 0
	global_load_dwordx4 v[140:143], v205, s[98:99] sc0 sc1
	s_add_u32 s42, s62, 0x800
	s_addc_u32 s43, s63, 0
	global_load_dwordx4 v[144:147], v205, s[42:43] sc0 sc1
	s_add_u32 s98, s62, 0x1800
	s_addc_u32 s99, s63, 0
	global_load_dwordx4 v[148:151], v205, s[98:99] sc0 sc1
	s_add_u32 s42, s62, 0xc00
	s_addc_u32 s43, s63, 0
	global_load_dwordx4 v[152:155], v205, s[42:43] sc0 sc1
	s_add_u32 s98, s62, 0x1c00
	s_addc_u32 s99, s63, 0
	global_load_dwordx4 v[156:159], v205, s[98:99] sc0 sc1
	s_add_u32 s42, s62, 0x2000
	s_addc_u32 s43, s63, 0
	global_load_dwordx4 v[160:163], v205, s[42:43] sc0 sc1
	s_add_u32 s98, s62, 0x3000
	s_addc_u32 s99, s63, 0
	global_load_dwordx4 v[164:167], v205, s[98:99] sc0 sc1
	s_add_u32 s42, s62, 0x2400
	s_addc_u32 s43, s63, 0
	global_load_dwordx4 v[168:171], v205, s[42:43] sc0 sc1
	s_add_u32 s98, s62, 0x3400
	s_addc_u32 s99, s63, 0
	global_load_dwordx4 v[172:175], v205, s[98:99] sc0 sc1
	s_add_u32 s42, s62, 0x2800
	s_addc_u32 s43, s63, 0
	global_load_dwordx4 v[176:179], v205, s[42:43] sc0 sc1
	s_add_u32 s98, s62, 0x3800
	s_addc_u32 s99, s63, 0
	global_load_dwordx4 v[180:183], v205, s[98:99] sc0 sc1
	s_add_u32 s42, s62, 0x2c00
	s_addc_u32 s43, s63, 0
	global_load_dwordx4 v[206:209], v205, s[42:43] sc0 sc1
	s_add_u32 s98, s62, 0x3c00
	s_addc_u32 s99, s63, 0
	global_load_dwordx4 v[210:213], v205, s[98:99] sc0 sc1
	s_add_u32 s42, s62, 0x20000
	s_addc_u32 s43, s63, 0
	global_load_dwordx4 v[236:239], v205, s[42:43] sc0 sc1
	s_waitcnt vmcnt(16)
	v_lshlrev_b32_e32 v240, 16, v128
	v_and_b32_e32 v241, 0xffff0000, v128
	v_pk_add_f32 v[124:125], v[124:125], v[240:241]
	v_lshlrev_b32_e32 v240, 16, v129
	v_and_b32_e32 v241, 0xffff0000, v129
	v_pk_add_f32 v[126:127], v[126:127], v[240:241]
	v_lshlrev_b32_e32 v240, 16, v130
	v_and_b32_e32 v241, 0xffff0000, v130
	v_pk_add_f32 v[120:121], v[120:121], v[240:241]
	v_lshlrev_b32_e32 v240, 16, v131
	v_and_b32_e32 v241, 0xffff0000, v131
	v_pk_add_f32 v[122:123], v[122:123], v[240:241]
	s_add_u32 s98, s62, 0x21000
	s_addc_u32 s99, s63, 0
	global_load_dwordx4 v[128:131], v205, s[98:99] sc0 sc1
	s_waitcnt vmcnt(16)
	v_lshlrev_b32_e32 v240, 16, v132
	v_and_b32_e32 v241, 0xffff0000, v132
	v_pk_add_f32 v[92:93], v[92:93], v[240:241]
	v_lshlrev_b32_e32 v240, 16, v133
	v_and_b32_e32 v241, 0xffff0000, v133
	v_pk_add_f32 v[94:95], v[94:95], v[240:241]
	v_lshlrev_b32_e32 v240, 16, v134
	v_and_b32_e32 v241, 0xffff0000, v134
	v_pk_add_f32 v[88:89], v[88:89], v[240:241]
	v_lshlrev_b32_e32 v240, 16, v135
	v_and_b32_e32 v241, 0xffff0000, v135
	v_pk_add_f32 v[90:91], v[90:91], v[240:241]
	s_add_u32 s42, s62, 0x20400
	s_addc_u32 s43, s63, 0
	global_load_dwordx4 v[132:135], v205, s[42:43] sc0 sc1
	s_waitcnt vmcnt(16)
	v_lshlrev_b32_e32 v240, 16, v136
	v_and_b32_e32 v241, 0xffff0000, v136
	v_pk_add_f32 v[116:117], v[116:117], v[240:241]
	v_lshlrev_b32_e32 v240, 16, v137
	v_and_b32_e32 v241, 0xffff0000, v137
	v_pk_add_f32 v[118:119], v[118:119], v[240:241]
	v_lshlrev_b32_e32 v240, 16, v138
	v_and_b32_e32 v241, 0xffff0000, v138
	v_pk_add_f32 v[112:113], v[112:113], v[240:241]
	v_lshlrev_b32_e32 v240, 16, v139
	v_and_b32_e32 v241, 0xffff0000, v139
	v_pk_add_f32 v[114:115], v[114:115], v[240:241]
	s_add_u32 s98, s62, 0x21400
	s_addc_u32 s99, s63, 0
	global_load_dwordx4 v[136:139], v205, s[98:99] sc0 sc1
	s_waitcnt vmcnt(16)
	v_lshlrev_b32_e32 v240, 16, v140
	v_and_b32_e32 v241, 0xffff0000, v140
	v_pk_add_f32 v[84:85], v[84:85], v[240:241]
	v_lshlrev_b32_e32 v240, 16, v141
	v_and_b32_e32 v241, 0xffff0000, v141
	v_pk_add_f32 v[86:87], v[86:87], v[240:241]
	v_lshlrev_b32_e32 v240, 16, v142
	v_and_b32_e32 v241, 0xffff0000, v142
	v_pk_add_f32 v[80:81], v[80:81], v[240:241]
	v_lshlrev_b32_e32 v240, 16, v143
	v_and_b32_e32 v241, 0xffff0000, v143
	v_pk_add_f32 v[82:83], v[82:83], v[240:241]
	s_add_u32 s42, s62, 0x20800
	s_addc_u32 s43, s63, 0
	global_load_dwordx4 v[140:143], v205, s[42:43] sc0 sc1
	s_waitcnt vmcnt(16)
	v_lshlrev_b32_e32 v240, 16, v144
	v_and_b32_e32 v241, 0xffff0000, v144
	v_pk_add_f32 v[108:109], v[108:109], v[240:241]
	v_lshlrev_b32_e32 v240, 16, v145
	v_and_b32_e32 v241, 0xffff0000, v145
	v_pk_add_f32 v[110:111], v[110:111], v[240:241]
	v_lshlrev_b32_e32 v240, 16, v146
	v_and_b32_e32 v241, 0xffff0000, v146
	v_pk_add_f32 v[104:105], v[104:105], v[240:241]
	v_lshlrev_b32_e32 v240, 16, v147
	v_and_b32_e32 v241, 0xffff0000, v147
	v_pk_add_f32 v[106:107], v[106:107], v[240:241]
	s_add_u32 s98, s62, 0x21800
	s_addc_u32 s99, s63, 0
	global_load_dwordx4 v[144:147], v205, s[98:99] sc0 sc1
	s_waitcnt vmcnt(16)
	v_lshlrev_b32_e32 v240, 16, v148
	v_and_b32_e32 v241, 0xffff0000, v148
	v_pk_add_f32 v[76:77], v[76:77], v[240:241]
	v_lshlrev_b32_e32 v240, 16, v149
	v_and_b32_e32 v241, 0xffff0000, v149
	v_pk_add_f32 v[78:79], v[78:79], v[240:241]
	v_lshlrev_b32_e32 v240, 16, v150
	v_and_b32_e32 v241, 0xffff0000, v150
	v_pk_add_f32 v[72:73], v[72:73], v[240:241]
	v_lshlrev_b32_e32 v240, 16, v151
	v_and_b32_e32 v241, 0xffff0000, v151
	v_pk_add_f32 v[74:75], v[74:75], v[240:241]
	s_add_u32 s42, s62, 0x20c00
	s_addc_u32 s43, s63, 0
	global_load_dwordx4 v[148:151], v205, s[42:43] sc0 sc1
	s_waitcnt vmcnt(16)
	v_lshlrev_b32_e32 v240, 16, v152
	v_and_b32_e32 v241, 0xffff0000, v152
	v_pk_add_f32 v[100:101], v[100:101], v[240:241]
	v_lshlrev_b32_e32 v240, 16, v153
	v_and_b32_e32 v241, 0xffff0000, v153
	v_pk_add_f32 v[102:103], v[102:103], v[240:241]
	v_lshlrev_b32_e32 v240, 16, v154
	v_and_b32_e32 v241, 0xffff0000, v154
	v_pk_add_f32 v[96:97], v[96:97], v[240:241]
	v_lshlrev_b32_e32 v240, 16, v155
	v_and_b32_e32 v241, 0xffff0000, v155
	v_pk_add_f32 v[98:99], v[98:99], v[240:241]
	s_add_u32 s98, s62, 0x21c00
	s_addc_u32 s99, s63, 0
	global_load_dwordx4 v[152:155], v205, s[98:99] sc0 sc1
	s_waitcnt vmcnt(16)
	v_lshlrev_b32_e32 v240, 16, v156
	v_and_b32_e32 v241, 0xffff0000, v156
	v_pk_add_f32 v[68:69], v[68:69], v[240:241]
	v_lshlrev_b32_e32 v240, 16, v157
	v_and_b32_e32 v241, 0xffff0000, v157
	v_pk_add_f32 v[70:71], v[70:71], v[240:241]
	v_lshlrev_b32_e32 v240, 16, v158
	v_and_b32_e32 v241, 0xffff0000, v158
	v_pk_add_f32 v[64:65], v[64:65], v[240:241]
	v_lshlrev_b32_e32 v240, 16, v159
	v_and_b32_e32 v241, 0xffff0000, v159
	v_pk_add_f32 v[66:67], v[66:67], v[240:241]
	s_add_u32 s42, s62, 0x22000
	s_addc_u32 s43, s63, 0
	global_load_dwordx4 v[156:159], v205, s[42:43] sc0 sc1
	s_waitcnt vmcnt(16)
	v_lshlrev_b32_e32 v240, 16, v160
	v_and_b32_e32 v241, 0xffff0000, v160
	v_pk_add_f32 v[60:61], v[60:61], v[240:241]
	v_lshlrev_b32_e32 v240, 16, v161
	v_and_b32_e32 v241, 0xffff0000, v161
	v_pk_add_f32 v[62:63], v[62:63], v[240:241]
	v_lshlrev_b32_e32 v240, 16, v162
	v_and_b32_e32 v241, 0xffff0000, v162
	v_pk_add_f32 v[56:57], v[56:57], v[240:241]
	v_lshlrev_b32_e32 v240, 16, v163
	v_and_b32_e32 v241, 0xffff0000, v163
	v_pk_add_f32 v[58:59], v[58:59], v[240:241]
	s_add_u32 s98, s62, 0x23000
	s_addc_u32 s99, s63, 0
	global_load_dwordx4 v[160:163], v205, s[98:99] sc0 sc1
	s_waitcnt vmcnt(16)
	v_lshlrev_b32_e32 v240, 16, v164
	v_and_b32_e32 v241, 0xffff0000, v164
	v_pk_add_f32 v[28:29], v[28:29], v[240:241]
	v_lshlrev_b32_e32 v240, 16, v165
	v_and_b32_e32 v241, 0xffff0000, v165
	v_pk_add_f32 v[30:31], v[30:31], v[240:241]
	v_lshlrev_b32_e32 v240, 16, v166
	v_and_b32_e32 v241, 0xffff0000, v166
	v_pk_add_f32 v[24:25], v[24:25], v[240:241]
	v_lshlrev_b32_e32 v240, 16, v167
	v_and_b32_e32 v241, 0xffff0000, v167
	v_pk_add_f32 v[26:27], v[26:27], v[240:241]
	s_add_u32 s42, s62, 0x22400
	s_addc_u32 s43, s63, 0
	global_load_dwordx4 v[164:167], v205, s[42:43] sc0 sc1
	s_waitcnt vmcnt(16)
	v_lshlrev_b32_e32 v240, 16, v168
	v_and_b32_e32 v241, 0xffff0000, v168
	v_pk_add_f32 v[52:53], v[52:53], v[240:241]
	v_lshlrev_b32_e32 v240, 16, v169
	v_and_b32_e32 v241, 0xffff0000, v169
	v_pk_add_f32 v[54:55], v[54:55], v[240:241]
	v_lshlrev_b32_e32 v240, 16, v170
	v_and_b32_e32 v241, 0xffff0000, v170
	v_pk_add_f32 v[48:49], v[48:49], v[240:241]
	v_lshlrev_b32_e32 v240, 16, v171
	v_and_b32_e32 v241, 0xffff0000, v171
	v_pk_add_f32 v[50:51], v[50:51], v[240:241]
	s_add_u32 s98, s62, 0x23400
	s_addc_u32 s99, s63, 0
	global_load_dwordx4 v[168:171], v205, s[98:99] sc0 sc1
	s_waitcnt vmcnt(16)
	v_lshlrev_b32_e32 v240, 16, v172
	v_and_b32_e32 v241, 0xffff0000, v172
	v_pk_add_f32 v[20:21], v[20:21], v[240:241]
	v_lshlrev_b32_e32 v240, 16, v173
	v_and_b32_e32 v241, 0xffff0000, v173
	v_pk_add_f32 v[22:23], v[22:23], v[240:241]
	v_lshlrev_b32_e32 v240, 16, v174
	v_and_b32_e32 v241, 0xffff0000, v174
	v_pk_add_f32 v[16:17], v[16:17], v[240:241]
	v_lshlrev_b32_e32 v240, 16, v175
	v_and_b32_e32 v241, 0xffff0000, v175
	v_pk_add_f32 v[18:19], v[18:19], v[240:241]
	s_add_u32 s42, s62, 0x22800
	s_addc_u32 s43, s63, 0
	global_load_dwordx4 v[172:175], v205, s[42:43] sc0 sc1
	s_waitcnt vmcnt(16)
	v_lshlrev_b32_e32 v240, 16, v176
	v_and_b32_e32 v241, 0xffff0000, v176
	v_pk_add_f32 v[44:45], v[44:45], v[240:241]
	v_lshlrev_b32_e32 v240, 16, v177
	v_and_b32_e32 v241, 0xffff0000, v177
	v_pk_add_f32 v[46:47], v[46:47], v[240:241]
	v_lshlrev_b32_e32 v240, 16, v178
	v_and_b32_e32 v241, 0xffff0000, v178
	v_pk_add_f32 v[40:41], v[40:41], v[240:241]
	v_lshlrev_b32_e32 v240, 16, v179
	v_and_b32_e32 v241, 0xffff0000, v179
	v_pk_add_f32 v[42:43], v[42:43], v[240:241]
	s_add_u32 s98, s62, 0x23800
	s_addc_u32 s99, s63, 0
	global_load_dwordx4 v[176:179], v205, s[98:99] sc0 sc1
	s_waitcnt vmcnt(16)
	v_lshlrev_b32_e32 v240, 16, v180
	v_and_b32_e32 v241, 0xffff0000, v180
	v_pk_add_f32 v[12:13], v[12:13], v[240:241]
	v_lshlrev_b32_e32 v240, 16, v181
	v_and_b32_e32 v241, 0xffff0000, v181
	v_pk_add_f32 v[14:15], v[14:15], v[240:241]
	v_lshlrev_b32_e32 v240, 16, v182
	v_and_b32_e32 v241, 0xffff0000, v182
	v_pk_add_f32 v[8:9], v[8:9], v[240:241]
	v_lshlrev_b32_e32 v240, 16, v183
	v_and_b32_e32 v241, 0xffff0000, v183
	v_pk_add_f32 v[10:11], v[10:11], v[240:241]
	s_add_u32 s42, s62, 0x22c00
	s_addc_u32 s43, s63, 0
	global_load_dwordx4 v[180:183], v205, s[42:43] sc0 sc1
	s_waitcnt vmcnt(16)
	v_lshlrev_b32_e32 v240, 16, v206
	v_and_b32_e32 v241, 0xffff0000, v206
	v_pk_add_f32 v[36:37], v[36:37], v[240:241]
	v_lshlrev_b32_e32 v240, 16, v207
	v_and_b32_e32 v241, 0xffff0000, v207
	v_pk_add_f32 v[38:39], v[38:39], v[240:241]
	v_lshlrev_b32_e32 v240, 16, v208
	v_and_b32_e32 v241, 0xffff0000, v208
	v_pk_add_f32 v[32:33], v[32:33], v[240:241]
	v_lshlrev_b32_e32 v240, 16, v209
	v_and_b32_e32 v241, 0xffff0000, v209
	v_pk_add_f32 v[34:35], v[34:35], v[240:241]
	s_add_u32 s98, s62, 0x23c00
	s_addc_u32 s99, s63, 0
	global_load_dwordx4 v[206:209], v205, s[98:99] sc0 sc1
	s_waitcnt vmcnt(16)
	v_lshlrev_b32_e32 v240, 16, v210
	v_and_b32_e32 v241, 0xffff0000, v210
	v_pk_add_f32 v[4:5], v[4:5], v[240:241]
	v_lshlrev_b32_e32 v240, 16, v211
	v_and_b32_e32 v241, 0xffff0000, v211
	v_pk_add_f32 v[6:7], v[6:7], v[240:241]
	v_lshlrev_b32_e32 v240, 16, v212
	v_and_b32_e32 v241, 0xffff0000, v212
	v_pk_add_f32 v[0:1], v[0:1], v[240:241]
	v_lshlrev_b32_e32 v240, 16, v213
	v_and_b32_e32 v241, 0xffff0000, v213
	v_pk_add_f32 v[2:3], v[2:3], v[240:241]
	s_add_u32 s42, s62, 0x40000
	s_addc_u32 s43, s63, 0
	global_load_dwordx4 v[210:213], v205, s[42:43] sc0 sc1
	s_waitcnt vmcnt(16)
	v_lshlrev_b32_e32 v240, 16, v236
	v_and_b32_e32 v241, 0xffff0000, v236
	v_pk_add_f32 v[124:125], v[124:125], v[240:241]
	v_lshlrev_b32_e32 v240, 16, v237
	v_and_b32_e32 v241, 0xffff0000, v237
	v_pk_add_f32 v[126:127], v[126:127], v[240:241]
	v_lshlrev_b32_e32 v240, 16, v238
	v_and_b32_e32 v241, 0xffff0000, v238
	v_pk_add_f32 v[120:121], v[120:121], v[240:241]
	v_lshlrev_b32_e32 v240, 16, v239
	v_and_b32_e32 v241, 0xffff0000, v239
	v_pk_add_f32 v[122:123], v[122:123], v[240:241]
	s_add_u32 s98, s62, 0x41000
	s_addc_u32 s99, s63, 0
	global_load_dwordx4 v[236:239], v205, s[98:99] sc0 sc1
	s_waitcnt vmcnt(16)
	v_lshlrev_b32_e32 v240, 16, v128
	v_and_b32_e32 v241, 0xffff0000, v128
	v_pk_add_f32 v[92:93], v[92:93], v[240:241]
	v_lshlrev_b32_e32 v240, 16, v129
	v_and_b32_e32 v241, 0xffff0000, v129
	v_pk_add_f32 v[94:95], v[94:95], v[240:241]
	v_lshlrev_b32_e32 v240, 16, v130
	v_and_b32_e32 v241, 0xffff0000, v130
	v_pk_add_f32 v[88:89], v[88:89], v[240:241]
	v_lshlrev_b32_e32 v240, 16, v131
	v_and_b32_e32 v241, 0xffff0000, v131
	v_pk_add_f32 v[90:91], v[90:91], v[240:241]
	s_add_u32 s42, s62, 0x40400
	s_addc_u32 s43, s63, 0
	global_load_dwordx4 v[128:131], v205, s[42:43] sc0 sc1
	s_waitcnt vmcnt(16)
	v_lshlrev_b32_e32 v240, 16, v132
	v_and_b32_e32 v241, 0xffff0000, v132
	v_pk_add_f32 v[116:117], v[116:117], v[240:241]
	v_lshlrev_b32_e32 v240, 16, v133
	v_and_b32_e32 v241, 0xffff0000, v133
	v_pk_add_f32 v[118:119], v[118:119], v[240:241]
	v_lshlrev_b32_e32 v240, 16, v134
	v_and_b32_e32 v241, 0xffff0000, v134
	v_pk_add_f32 v[112:113], v[112:113], v[240:241]
	v_lshlrev_b32_e32 v240, 16, v135
	v_and_b32_e32 v241, 0xffff0000, v135
	v_pk_add_f32 v[114:115], v[114:115], v[240:241]
	s_add_u32 s98, s62, 0x41400
	s_addc_u32 s99, s63, 0
	global_load_dwordx4 v[132:135], v205, s[98:99] sc0 sc1
	s_waitcnt vmcnt(16)
	v_lshlrev_b32_e32 v240, 16, v136
	v_and_b32_e32 v241, 0xffff0000, v136
	v_pk_add_f32 v[84:85], v[84:85], v[240:241]
	v_lshlrev_b32_e32 v240, 16, v137
	v_and_b32_e32 v241, 0xffff0000, v137
	v_pk_add_f32 v[86:87], v[86:87], v[240:241]
	v_lshlrev_b32_e32 v240, 16, v138
	v_and_b32_e32 v241, 0xffff0000, v138
	v_pk_add_f32 v[80:81], v[80:81], v[240:241]
	v_lshlrev_b32_e32 v240, 16, v139
	v_and_b32_e32 v241, 0xffff0000, v139
	v_pk_add_f32 v[82:83], v[82:83], v[240:241]
	s_add_u32 s42, s62, 0x40800
	s_addc_u32 s43, s63, 0
	global_load_dwordx4 v[136:139], v205, s[42:43] sc0 sc1
	s_waitcnt vmcnt(16)
	v_lshlrev_b32_e32 v240, 16, v140
	v_and_b32_e32 v241, 0xffff0000, v140
	v_pk_add_f32 v[108:109], v[108:109], v[240:241]
	v_lshlrev_b32_e32 v240, 16, v141
	v_and_b32_e32 v241, 0xffff0000, v141
	v_pk_add_f32 v[110:111], v[110:111], v[240:241]
	v_lshlrev_b32_e32 v240, 16, v142
	v_and_b32_e32 v241, 0xffff0000, v142
	v_pk_add_f32 v[104:105], v[104:105], v[240:241]
	v_lshlrev_b32_e32 v240, 16, v143
	v_and_b32_e32 v241, 0xffff0000, v143
	v_pk_add_f32 v[106:107], v[106:107], v[240:241]
	s_add_u32 s98, s62, 0x41800
	s_addc_u32 s99, s63, 0
	global_load_dwordx4 v[140:143], v205, s[98:99] sc0 sc1
	s_waitcnt vmcnt(16)
	v_lshlrev_b32_e32 v240, 16, v144
	v_and_b32_e32 v241, 0xffff0000, v144
	v_pk_add_f32 v[76:77], v[76:77], v[240:241]
	v_lshlrev_b32_e32 v240, 16, v145
	v_and_b32_e32 v241, 0xffff0000, v145
	v_pk_add_f32 v[78:79], v[78:79], v[240:241]
	v_lshlrev_b32_e32 v240, 16, v146
	v_and_b32_e32 v241, 0xffff0000, v146
	v_pk_add_f32 v[72:73], v[72:73], v[240:241]
	v_lshlrev_b32_e32 v240, 16, v147
	v_and_b32_e32 v241, 0xffff0000, v147
	v_pk_add_f32 v[74:75], v[74:75], v[240:241]
	s_add_u32 s42, s62, 0x40c00
	s_addc_u32 s43, s63, 0
	global_load_dwordx4 v[144:147], v205, s[42:43] sc0 sc1
	s_waitcnt vmcnt(16)
	v_lshlrev_b32_e32 v240, 16, v148
	v_and_b32_e32 v241, 0xffff0000, v148
	v_pk_add_f32 v[100:101], v[100:101], v[240:241]
	v_lshlrev_b32_e32 v240, 16, v149
	v_and_b32_e32 v241, 0xffff0000, v149
	v_pk_add_f32 v[102:103], v[102:103], v[240:241]
	v_lshlrev_b32_e32 v240, 16, v150
	v_and_b32_e32 v241, 0xffff0000, v150
	v_pk_add_f32 v[96:97], v[96:97], v[240:241]
	v_lshlrev_b32_e32 v240, 16, v151
	v_and_b32_e32 v241, 0xffff0000, v151
	v_pk_add_f32 v[98:99], v[98:99], v[240:241]
	s_add_u32 s98, s62, 0x41c00
	s_addc_u32 s99, s63, 0
	global_load_dwordx4 v[148:151], v205, s[98:99] sc0 sc1
	s_waitcnt vmcnt(16)
	v_lshlrev_b32_e32 v240, 16, v152
	v_and_b32_e32 v241, 0xffff0000, v152
	v_pk_add_f32 v[68:69], v[68:69], v[240:241]
	v_lshlrev_b32_e32 v240, 16, v153
	v_and_b32_e32 v241, 0xffff0000, v153
	v_pk_add_f32 v[70:71], v[70:71], v[240:241]
	v_lshlrev_b32_e32 v240, 16, v154
	v_and_b32_e32 v241, 0xffff0000, v154
	v_pk_add_f32 v[64:65], v[64:65], v[240:241]
	v_lshlrev_b32_e32 v240, 16, v155
	v_and_b32_e32 v241, 0xffff0000, v155
	v_pk_add_f32 v[66:67], v[66:67], v[240:241]
	s_add_u32 s42, s62, 0x42000
	s_addc_u32 s43, s63, 0
	global_load_dwordx4 v[152:155], v205, s[42:43] sc0 sc1
	s_waitcnt vmcnt(16)
	v_lshlrev_b32_e32 v240, 16, v156
	v_and_b32_e32 v241, 0xffff0000, v156
	v_pk_add_f32 v[60:61], v[60:61], v[240:241]
	v_lshlrev_b32_e32 v240, 16, v157
	v_and_b32_e32 v241, 0xffff0000, v157
	v_pk_add_f32 v[62:63], v[62:63], v[240:241]
	v_lshlrev_b32_e32 v240, 16, v158
	v_and_b32_e32 v241, 0xffff0000, v158
	v_pk_add_f32 v[56:57], v[56:57], v[240:241]
	v_lshlrev_b32_e32 v240, 16, v159
	v_and_b32_e32 v241, 0xffff0000, v159
	v_pk_add_f32 v[58:59], v[58:59], v[240:241]
	s_add_u32 s98, s62, 0x43000
	s_addc_u32 s99, s63, 0
	global_load_dwordx4 v[156:159], v205, s[98:99] sc0 sc1
	s_waitcnt vmcnt(16)
	v_lshlrev_b32_e32 v240, 16, v160
	v_and_b32_e32 v241, 0xffff0000, v160
	v_pk_add_f32 v[28:29], v[28:29], v[240:241]
	v_lshlrev_b32_e32 v240, 16, v161
	v_and_b32_e32 v241, 0xffff0000, v161
	v_pk_add_f32 v[30:31], v[30:31], v[240:241]
	v_lshlrev_b32_e32 v240, 16, v162
	v_and_b32_e32 v241, 0xffff0000, v162
	v_pk_add_f32 v[24:25], v[24:25], v[240:241]
	v_lshlrev_b32_e32 v240, 16, v163
	v_and_b32_e32 v241, 0xffff0000, v163
	v_pk_add_f32 v[26:27], v[26:27], v[240:241]
	s_add_u32 s42, s62, 0x42400
	s_addc_u32 s43, s63, 0
	global_load_dwordx4 v[160:163], v205, s[42:43] sc0 sc1
	s_waitcnt vmcnt(16)
	v_lshlrev_b32_e32 v240, 16, v164
	v_and_b32_e32 v241, 0xffff0000, v164
	v_pk_add_f32 v[52:53], v[52:53], v[240:241]
	v_lshlrev_b32_e32 v240, 16, v165
	v_and_b32_e32 v241, 0xffff0000, v165
	v_pk_add_f32 v[54:55], v[54:55], v[240:241]
	v_lshlrev_b32_e32 v240, 16, v166
	v_and_b32_e32 v241, 0xffff0000, v166
	v_pk_add_f32 v[48:49], v[48:49], v[240:241]
	v_lshlrev_b32_e32 v240, 16, v167
	v_and_b32_e32 v241, 0xffff0000, v167
	v_pk_add_f32 v[50:51], v[50:51], v[240:241]
	s_add_u32 s98, s62, 0x43400
	s_addc_u32 s99, s63, 0
	global_load_dwordx4 v[164:167], v205, s[98:99] sc0 sc1
	s_waitcnt vmcnt(16)
	v_lshlrev_b32_e32 v240, 16, v168
	v_and_b32_e32 v241, 0xffff0000, v168
	v_pk_add_f32 v[20:21], v[20:21], v[240:241]
	v_lshlrev_b32_e32 v240, 16, v169
	v_and_b32_e32 v241, 0xffff0000, v169
	v_pk_add_f32 v[22:23], v[22:23], v[240:241]
	v_lshlrev_b32_e32 v240, 16, v170
	v_and_b32_e32 v241, 0xffff0000, v170
	v_pk_add_f32 v[16:17], v[16:17], v[240:241]
	v_lshlrev_b32_e32 v240, 16, v171
	v_and_b32_e32 v241, 0xffff0000, v171
	v_pk_add_f32 v[18:19], v[18:19], v[240:241]
	s_add_u32 s42, s62, 0x42800
	s_addc_u32 s43, s63, 0
	global_load_dwordx4 v[168:171], v205, s[42:43] sc0 sc1
	s_waitcnt vmcnt(16)
	v_lshlrev_b32_e32 v240, 16, v172
	v_and_b32_e32 v241, 0xffff0000, v172
	v_pk_add_f32 v[44:45], v[44:45], v[240:241]
	v_lshlrev_b32_e32 v240, 16, v173
	v_and_b32_e32 v241, 0xffff0000, v173
	v_pk_add_f32 v[46:47], v[46:47], v[240:241]
	v_lshlrev_b32_e32 v240, 16, v174
	v_and_b32_e32 v241, 0xffff0000, v174
	v_pk_add_f32 v[40:41], v[40:41], v[240:241]
	v_lshlrev_b32_e32 v240, 16, v175
	v_and_b32_e32 v241, 0xffff0000, v175
	v_pk_add_f32 v[42:43], v[42:43], v[240:241]
	s_add_u32 s98, s62, 0x43800
	s_addc_u32 s99, s63, 0
	global_load_dwordx4 v[172:175], v205, s[98:99] sc0 sc1
	s_waitcnt vmcnt(16)
	v_lshlrev_b32_e32 v240, 16, v176
	v_and_b32_e32 v241, 0xffff0000, v176
	v_pk_add_f32 v[12:13], v[12:13], v[240:241]
	v_lshlrev_b32_e32 v240, 16, v177
	v_and_b32_e32 v241, 0xffff0000, v177
	v_pk_add_f32 v[14:15], v[14:15], v[240:241]
	v_lshlrev_b32_e32 v240, 16, v178
	v_and_b32_e32 v241, 0xffff0000, v178
	v_pk_add_f32 v[8:9], v[8:9], v[240:241]
	v_lshlrev_b32_e32 v240, 16, v179
	v_and_b32_e32 v241, 0xffff0000, v179
	v_pk_add_f32 v[10:11], v[10:11], v[240:241]
	s_add_u32 s42, s62, 0x42c00
	s_addc_u32 s43, s63, 0
	global_load_dwordx4 v[176:179], v205, s[42:43] sc0 sc1
	s_waitcnt vmcnt(16)
	v_lshlrev_b32_e32 v240, 16, v180
	v_and_b32_e32 v241, 0xffff0000, v180
	v_pk_add_f32 v[36:37], v[36:37], v[240:241]
	v_lshlrev_b32_e32 v240, 16, v181
	v_and_b32_e32 v241, 0xffff0000, v181
	v_pk_add_f32 v[38:39], v[38:39], v[240:241]
	v_lshlrev_b32_e32 v240, 16, v182
	v_and_b32_e32 v241, 0xffff0000, v182
	v_pk_add_f32 v[32:33], v[32:33], v[240:241]
	v_lshlrev_b32_e32 v240, 16, v183
	v_and_b32_e32 v241, 0xffff0000, v183
	v_pk_add_f32 v[34:35], v[34:35], v[240:241]
	s_add_u32 s98, s62, 0x43c00
	s_addc_u32 s99, s63, 0
	global_load_dwordx4 v[180:183], v205, s[98:99] sc0 sc1
	s_waitcnt vmcnt(16)
	v_lshlrev_b32_e32 v240, 16, v206
	v_and_b32_e32 v241, 0xffff0000, v206
	v_pk_add_f32 v[4:5], v[4:5], v[240:241]
	v_lshlrev_b32_e32 v240, 16, v207
	v_and_b32_e32 v241, 0xffff0000, v207
	v_pk_add_f32 v[6:7], v[6:7], v[240:241]
	v_lshlrev_b32_e32 v240, 16, v208
	v_and_b32_e32 v241, 0xffff0000, v208
	v_pk_add_f32 v[0:1], v[0:1], v[240:241]
	v_lshlrev_b32_e32 v240, 16, v209
	v_and_b32_e32 v241, 0xffff0000, v209
	v_pk_add_f32 v[2:3], v[2:3], v[240:241]
	s_add_u32 s42, s14, 0x0
	s_addc_u32 s43, s15, 0
	global_load_dwordx4 v[206:209], v235, s[42:43]
	s_waitcnt vmcnt(16)
	v_lshlrev_b32_e32 v240, 16, v210
	v_and_b32_e32 v241, 0xffff0000, v210
	v_pk_add_f32 v[124:125], v[124:125], v[240:241]
	v_lshlrev_b32_e32 v240, 16, v211
	v_and_b32_e32 v241, 0xffff0000, v211
	v_pk_add_f32 v[126:127], v[126:127], v[240:241]
	v_lshlrev_b32_e32 v240, 16, v212
	v_and_b32_e32 v241, 0xffff0000, v212
	v_pk_add_f32 v[120:121], v[120:121], v[240:241]
	v_lshlrev_b32_e32 v240, 16, v213
	v_and_b32_e32 v241, 0xffff0000, v213
	v_pk_add_f32 v[122:123], v[122:123], v[240:241]
	s_add_u32 s98, s10, 0x0
	s_addc_u32 s99, s11, 0
	global_load_dwordx4 v[210:213], v203, s[98:99]
	s_waitcnt vmcnt(16)
	v_lshlrev_b32_e32 v240, 16, v236
	v_and_b32_e32 v241, 0xffff0000, v236
	v_pk_add_f32 v[92:93], v[92:93], v[240:241]
	v_lshlrev_b32_e32 v240, 16, v237
	v_and_b32_e32 v241, 0xffff0000, v237
	v_pk_add_f32 v[94:95], v[94:95], v[240:241]
	v_lshlrev_b32_e32 v240, 16, v238
	v_and_b32_e32 v241, 0xffff0000, v238
	v_pk_add_f32 v[88:89], v[88:89], v[240:241]
	v_lshlrev_b32_e32 v240, 16, v239
	v_and_b32_e32 v241, 0xffff0000, v239
	v_pk_add_f32 v[90:91], v[90:91], v[240:241]
	s_add_u32 s42, s14, 0x0
	s_addc_u32 s43, s15, 0
	global_load_dwordx4 v[236:239], v235, s[42:43] offset:16
	s_waitcnt vmcnt(16)
	v_lshlrev_b32_e32 v240, 16, v128
	v_and_b32_e32 v241, 0xffff0000, v128
	v_pk_add_f32 v[116:117], v[116:117], v[240:241]
	v_lshlrev_b32_e32 v240, 16, v129
	v_and_b32_e32 v241, 0xffff0000, v129
	v_pk_add_f32 v[118:119], v[118:119], v[240:241]
	v_lshlrev_b32_e32 v240, 16, v130
	v_and_b32_e32 v241, 0xffff0000, v130
	v_pk_add_f32 v[112:113], v[112:113], v[240:241]
	v_lshlrev_b32_e32 v240, 16, v131
	v_and_b32_e32 v241, 0xffff0000, v131
	v_pk_add_f32 v[114:115], v[114:115], v[240:241]
	s_add_u32 s98, s10, 0x0
	s_addc_u32 s99, s11, 0
	global_load_dwordx4 v[128:131], v203, s[98:99] offset:16
	s_waitcnt vmcnt(16)
	v_lshlrev_b32_e32 v240, 16, v132
	v_and_b32_e32 v241, 0xffff0000, v132
	v_pk_add_f32 v[84:85], v[84:85], v[240:241]
	v_lshlrev_b32_e32 v240, 16, v133
	v_and_b32_e32 v241, 0xffff0000, v133
	v_pk_add_f32 v[86:87], v[86:87], v[240:241]
	v_lshlrev_b32_e32 v240, 16, v134
	v_and_b32_e32 v241, 0xffff0000, v134
	v_pk_add_f32 v[80:81], v[80:81], v[240:241]
	v_lshlrev_b32_e32 v240, 16, v135
	v_and_b32_e32 v241, 0xffff0000, v135
	v_pk_add_f32 v[82:83], v[82:83], v[240:241]
	s_add_u32 s42, s14, 0x200
	s_addc_u32 s43, s15, 0
	global_load_dwordx4 v[132:135], v235, s[42:43]
	s_waitcnt vmcnt(16)
	v_lshlrev_b32_e32 v240, 16, v136
	v_and_b32_e32 v241, 0xffff0000, v136
	v_pk_add_f32 v[108:109], v[108:109], v[240:241]
	v_lshlrev_b32_e32 v240, 16, v137
	v_and_b32_e32 v241, 0xffff0000, v137
	v_pk_add_f32 v[110:111], v[110:111], v[240:241]
	v_lshlrev_b32_e32 v240, 16, v138
	v_and_b32_e32 v241, 0xffff0000, v138
	v_pk_add_f32 v[104:105], v[104:105], v[240:241]
	v_lshlrev_b32_e32 v240, 16, v139
	v_and_b32_e32 v241, 0xffff0000, v139
	v_pk_add_f32 v[106:107], v[106:107], v[240:241]
	s_add_u32 s98, s10, 0x200
	s_addc_u32 s99, s11, 0
	global_load_dwordx4 v[136:139], v203, s[98:99]
	s_waitcnt vmcnt(16)
	v_lshlrev_b32_e32 v240, 16, v140
	v_and_b32_e32 v241, 0xffff0000, v140
	v_pk_add_f32 v[76:77], v[76:77], v[240:241]
	v_lshlrev_b32_e32 v240, 16, v141
	v_and_b32_e32 v241, 0xffff0000, v141
	v_pk_add_f32 v[78:79], v[78:79], v[240:241]
	v_lshlrev_b32_e32 v240, 16, v142
	v_and_b32_e32 v241, 0xffff0000, v142
	v_pk_add_f32 v[72:73], v[72:73], v[240:241]
	v_lshlrev_b32_e32 v240, 16, v143
	v_and_b32_e32 v241, 0xffff0000, v143
	v_pk_add_f32 v[74:75], v[74:75], v[240:241]
	s_add_u32 s42, s14, 0x200
	s_addc_u32 s43, s15, 0
	global_load_dwordx4 v[140:143], v235, s[42:43] offset:16
	s_waitcnt vmcnt(16)
	v_lshlrev_b32_e32 v240, 16, v144
	v_and_b32_e32 v241, 0xffff0000, v144
	v_pk_add_f32 v[100:101], v[100:101], v[240:241]
	v_lshlrev_b32_e32 v240, 16, v145
	v_and_b32_e32 v241, 0xffff0000, v145
	v_pk_add_f32 v[102:103], v[102:103], v[240:241]
	v_lshlrev_b32_e32 v240, 16, v146
	v_and_b32_e32 v241, 0xffff0000, v146
	v_pk_add_f32 v[96:97], v[96:97], v[240:241]
	v_lshlrev_b32_e32 v240, 16, v147
	v_and_b32_e32 v241, 0xffff0000, v147
	v_pk_add_f32 v[98:99], v[98:99], v[240:241]
	s_add_u32 s98, s10, 0x200
	s_addc_u32 s99, s11, 0
	global_load_dwordx4 v[144:147], v203, s[98:99] offset:16
	s_waitcnt vmcnt(16)
	v_lshlrev_b32_e32 v240, 16, v148
	v_and_b32_e32 v241, 0xffff0000, v148
	v_pk_add_f32 v[68:69], v[68:69], v[240:241]
	v_lshlrev_b32_e32 v240, 16, v149
	v_and_b32_e32 v241, 0xffff0000, v149
	v_pk_add_f32 v[70:71], v[70:71], v[240:241]
	v_lshlrev_b32_e32 v240, 16, v150
	v_and_b32_e32 v241, 0xffff0000, v150
	v_pk_add_f32 v[64:65], v[64:65], v[240:241]
	v_lshlrev_b32_e32 v240, 16, v151
	v_and_b32_e32 v241, 0xffff0000, v151
	v_pk_add_f32 v[66:67], v[66:67], v[240:241]
	s_add_u32 s42, s14, 0x18000
	s_addc_u32 s43, s15, 0
	global_load_dwordx4 v[148:151], v235, s[42:43]
	s_waitcnt vmcnt(16)
	v_lshlrev_b32_e32 v240, 16, v152
	v_and_b32_e32 v241, 0xffff0000, v152
	v_pk_add_f32 v[60:61], v[60:61], v[240:241]
	v_lshlrev_b32_e32 v240, 16, v153
	v_and_b32_e32 v241, 0xffff0000, v153
	v_pk_add_f32 v[62:63], v[62:63], v[240:241]
	v_lshlrev_b32_e32 v240, 16, v154
	v_and_b32_e32 v241, 0xffff0000, v154
	v_pk_add_f32 v[56:57], v[56:57], v[240:241]
	v_lshlrev_b32_e32 v240, 16, v155
	v_and_b32_e32 v241, 0xffff0000, v155
	v_pk_add_f32 v[58:59], v[58:59], v[240:241]
	s_add_u32 s98, s10, 0x10000
	s_addc_u32 s99, s11, 0
	global_load_dwordx4 v[152:155], v203, s[98:99]
	s_waitcnt vmcnt(16)
	v_lshlrev_b32_e32 v240, 16, v156
	v_and_b32_e32 v241, 0xffff0000, v156
	v_pk_add_f32 v[28:29], v[28:29], v[240:241]
	v_lshlrev_b32_e32 v240, 16, v157
	v_and_b32_e32 v241, 0xffff0000, v157
	v_pk_add_f32 v[30:31], v[30:31], v[240:241]
	v_lshlrev_b32_e32 v240, 16, v158
	v_and_b32_e32 v241, 0xffff0000, v158
	v_pk_add_f32 v[24:25], v[24:25], v[240:241]
	v_lshlrev_b32_e32 v240, 16, v159
	v_and_b32_e32 v241, 0xffff0000, v159
	v_pk_add_f32 v[26:27], v[26:27], v[240:241]
	s_add_u32 s42, s14, 0x18000
	s_addc_u32 s43, s15, 0
	global_load_dwordx4 v[156:159], v235, s[42:43] offset:16
	s_waitcnt vmcnt(16)
	v_lshlrev_b32_e32 v240, 16, v160
	v_and_b32_e32 v241, 0xffff0000, v160
	v_pk_add_f32 v[52:53], v[52:53], v[240:241]
	v_lshlrev_b32_e32 v240, 16, v161
	v_and_b32_e32 v241, 0xffff0000, v161
	v_pk_add_f32 v[54:55], v[54:55], v[240:241]
	v_lshlrev_b32_e32 v240, 16, v162
	v_and_b32_e32 v241, 0xffff0000, v162
	v_pk_add_f32 v[48:49], v[48:49], v[240:241]
	v_lshlrev_b32_e32 v240, 16, v163
	v_and_b32_e32 v241, 0xffff0000, v163
	v_pk_add_f32 v[50:51], v[50:51], v[240:241]
	s_add_u32 s98, s10, 0x10000
	s_addc_u32 s99, s11, 0
	global_load_dwordx4 v[160:163], v203, s[98:99] offset:16
	s_waitcnt vmcnt(16)
	v_lshlrev_b32_e32 v240, 16, v164
	v_and_b32_e32 v241, 0xffff0000, v164
	v_pk_add_f32 v[20:21], v[20:21], v[240:241]
	v_lshlrev_b32_e32 v240, 16, v165
	v_and_b32_e32 v241, 0xffff0000, v165
	v_pk_add_f32 v[22:23], v[22:23], v[240:241]
	v_lshlrev_b32_e32 v240, 16, v166
	v_and_b32_e32 v241, 0xffff0000, v166
	v_pk_add_f32 v[16:17], v[16:17], v[240:241]
	v_lshlrev_b32_e32 v240, 16, v167
	v_and_b32_e32 v241, 0xffff0000, v167
	v_pk_add_f32 v[18:19], v[18:19], v[240:241]
	s_add_u32 s42, s14, 0x18200
	s_addc_u32 s43, s15, 0
	global_load_dwordx4 v[164:167], v235, s[42:43]
	s_waitcnt vmcnt(16)
	v_lshlrev_b32_e32 v240, 16, v168
	v_and_b32_e32 v241, 0xffff0000, v168
	v_pk_add_f32 v[44:45], v[44:45], v[240:241]
	v_lshlrev_b32_e32 v240, 16, v169
	v_and_b32_e32 v241, 0xffff0000, v169
	v_pk_add_f32 v[46:47], v[46:47], v[240:241]
	v_lshlrev_b32_e32 v240, 16, v170
	v_and_b32_e32 v241, 0xffff0000, v170
	v_pk_add_f32 v[40:41], v[40:41], v[240:241]
	v_lshlrev_b32_e32 v240, 16, v171
	v_and_b32_e32 v241, 0xffff0000, v171
	v_pk_add_f32 v[42:43], v[42:43], v[240:241]
	s_add_u32 s98, s10, 0x10200
	s_addc_u32 s99, s11, 0
	global_load_dwordx4 v[168:171], v203, s[98:99]
	s_waitcnt vmcnt(16)
	v_lshlrev_b32_e32 v240, 16, v172
	v_and_b32_e32 v241, 0xffff0000, v172
	v_pk_add_f32 v[12:13], v[12:13], v[240:241]
	v_lshlrev_b32_e32 v240, 16, v173
	v_and_b32_e32 v241, 0xffff0000, v173
	v_pk_add_f32 v[14:15], v[14:15], v[240:241]
	v_lshlrev_b32_e32 v240, 16, v174
	v_and_b32_e32 v241, 0xffff0000, v174
	v_pk_add_f32 v[8:9], v[8:9], v[240:241]
	v_lshlrev_b32_e32 v240, 16, v175
	v_and_b32_e32 v241, 0xffff0000, v175
	v_pk_add_f32 v[10:11], v[10:11], v[240:241]
	s_add_u32 s42, s14, 0x18200
	s_addc_u32 s43, s15, 0
	global_load_dwordx4 v[172:175], v235, s[42:43] offset:16
	s_waitcnt vmcnt(16)
	v_lshlrev_b32_e32 v240, 16, v176
	v_and_b32_e32 v241, 0xffff0000, v176
	v_pk_add_f32 v[36:37], v[36:37], v[240:241]
	v_lshlrev_b32_e32 v240, 16, v177
	v_and_b32_e32 v241, 0xffff0000, v177
	v_pk_add_f32 v[38:39], v[38:39], v[240:241]
	v_lshlrev_b32_e32 v240, 16, v178
	v_and_b32_e32 v241, 0xffff0000, v178
	v_pk_add_f32 v[32:33], v[32:33], v[240:241]
	v_lshlrev_b32_e32 v240, 16, v179
	v_and_b32_e32 v241, 0xffff0000, v179
	v_pk_add_f32 v[34:35], v[34:35], v[240:241]
	s_add_u32 s98, s10, 0x10200
	s_addc_u32 s99, s11, 0
	global_load_dwordx4 v[176:179], v203, s[98:99] offset:16
	s_waitcnt vmcnt(16)
	v_lshlrev_b32_e32 v240, 16, v180
	v_and_b32_e32 v241, 0xffff0000, v180
	v_pk_add_f32 v[4:5], v[4:5], v[240:241]
	v_lshlrev_b32_e32 v240, 16, v181
	v_and_b32_e32 v241, 0xffff0000, v181
	v_pk_add_f32 v[6:7], v[6:7], v[240:241]
	v_lshlrev_b32_e32 v240, 16, v182
	v_and_b32_e32 v241, 0xffff0000, v182
	v_pk_add_f32 v[0:1], v[0:1], v[240:241]
	v_lshlrev_b32_e32 v240, 16, v183
	v_and_b32_e32 v241, 0xffff0000, v183
	v_pk_add_f32 v[2:3], v[2:3], v[240:241]
	s_add_u32 s42, s14, 0x30000
	s_addc_u32 s43, s15, 0
	global_load_dwordx4 v[180:183], v235, s[42:43]
	s_waitcnt vmcnt(15)
	v_pk_fma_f32 v[124:125], v[206:207], v[124:125], v[210:211]
	v_pk_fma_f32 v[126:127], v[208:209], v[126:127], v[212:213]
	s_add_u32 s98, s10, 0x0
	s_addc_u32 s99, s11, 0
	global_store_dwordx4 v203, v[124:127], s[98:99]
	s_add_u32 s42, s10, 0x20000
	s_addc_u32 s43, s11, 0
	global_load_dwordx4 v[206:209], v203, s[42:43]
	s_add_u32 s98, s14, 0x30000
	s_addc_u32 s99, s15, 0
	global_load_dwordx4 v[210:213], v235, s[98:99] offset:16
	s_waitcnt vmcnt(16)
	v_pk_fma_f32 v[120:121], v[236:237], v[120:121], v[128:129]
	v_pk_fma_f32 v[122:123], v[238:239], v[122:123], v[130:131]
	s_add_u32 s42, s10, 0x0
	s_addc_u32 s43, s11, 0
	global_store_dwordx4 v203, v[120:123], s[42:43] offset:16
	s_add_u32 s98, s10, 0x20000
	s_addc_u32 s99, s11, 0
	global_load_dwordx4 v[236:239], v203, s[98:99] offset:16
	s_add_u32 s42, s14, 0x30200
	s_addc_u32 s43, s15, 0
	global_load_dwordx4 v[128:131], v235, s[42:43]
	s_waitcnt vmcnt(17)
	v_pk_fma_f32 v[92:93], v[132:133], v[92:93], v[136:137]
	v_pk_fma_f32 v[94:95], v[134:135], v[94:95], v[138:139]
	s_add_u32 s98, s10, 0x200
	s_addc_u32 s99, s11, 0
	global_store_dwordx4 v203, v[92:95], s[98:99]
	s_add_u32 s42, s10, 0x20200
	s_addc_u32 s43, s11, 0
	global_load_dwordx4 v[132:135], v203, s[42:43]
	s_add_u32 s98, s14, 0x30200
	s_addc_u32 s99, s15, 0
	global_load_dwordx4 v[136:139], v235, s[98:99] offset:16
	s_waitcnt vmcnt(18)
	v_pk_fma_f32 v[88:89], v[140:141], v[88:89], v[144:145]
	v_pk_fma_f32 v[90:91], v[142:143], v[90:91], v[146:147]
	s_add_u32 s42, s10, 0x200
	s_addc_u32 s43, s11, 0
	global_store_dwordx4 v203, v[88:91], s[42:43] offset:16
	s_add_u32 s98, s10, 0x20200
	s_addc_u32 s99, s11, 0
	global_load_dwordx4 v[140:143], v203, s[98:99] offset:16
	s_add_u32 s42, s14, 0x48000
	s_addc_u32 s43, s15, 0
	global_load_dwordx4 v[144:147], v235, s[42:43]
	s_waitcnt vmcnt(19)
	v_pk_fma_f32 v[116:117], v[148:149], v[116:117], v[152:153]
	v_pk_fma_f32 v[118:119], v[150:151], v[118:119], v[154:155]
	s_add_u32 s98, s10, 0x10000
	s_addc_u32 s99, s11, 0
	global_store_dwordx4 v203, v[116:119], s[98:99]
	s_add_u32 s42, s10, 0x30000
	s_addc_u32 s43, s11, 0
	global_load_dwordx4 v[148:151], v203, s[42:43]
	s_add_u32 s98, s14, 0x48000
	s_addc_u32 s99, s15, 0
	global_load_dwordx4 v[152:155], v235, s[98:99] offset:16
	s_waitcnt vmcnt(20)
	v_pk_fma_f32 v[112:113], v[156:157], v[112:113], v[160:161]
	v_pk_fma_f32 v[114:115], v[158:159], v[114:115], v[162:163]
	s_add_u32 s42, s10, 0x10000
	s_addc_u32 s43, s11, 0
	global_store_dwordx4 v203, v[112:115], s[42:43] offset:16
	s_add_u32 s98, s10, 0x30000
	s_addc_u32 s99, s11, 0
	global_load_dwordx4 v[156:159], v203, s[98:99] offset:16
	s_add_u32 s42, s14, 0x48200
	s_addc_u32 s43, s15, 0
	global_load_dwordx4 v[160:163], v235, s[42:43]
	s_waitcnt vmcnt(21)
	v_pk_fma_f32 v[84:85], v[164:165], v[84:85], v[168:169]
	v_pk_fma_f32 v[86:87], v[166:167], v[86:87], v[170:171]
	s_add_u32 s98, s10, 0x10200
	s_addc_u32 s99, s11, 0
	global_store_dwordx4 v203, v[84:87], s[98:99]
	s_add_u32 s42, s10, 0x30200
	s_addc_u32 s43, s11, 0
	global_load_dwordx4 v[164:167], v203, s[42:43]
	s_add_u32 s98, s14, 0x48200
	s_addc_u32 s99, s15, 0
	global_load_dwordx4 v[168:171], v235, s[98:99] offset:16
	s_waitcnt vmcnt(22)
	v_pk_fma_f32 v[80:81], v[172:173], v[80:81], v[176:177]
	v_pk_fma_f32 v[82:83], v[174:175], v[82:83], v[178:179]
	s_add_u32 s42, s10, 0x10200
	s_addc_u32 s43, s11, 0
	global_store_dwordx4 v203, v[80:83], s[42:43] offset:16
	s_add_u32 s98, s10, 0x30200
	s_addc_u32 s99, s11, 0
	global_load_dwordx4 v[172:175], v203, s[98:99] offset:16
	s_add_u32 s42, s14, 0xc0000
	s_addc_u32 s43, s15, 0
	global_load_dwordx4 v[176:179], v235, s[42:43]
	s_waitcnt vmcnt(22)
	v_pk_fma_f32 v[108:109], v[180:181], v[108:109], v[206:207]
	v_pk_fma_f32 v[110:111], v[182:183], v[110:111], v[208:209]
	s_add_u32 s98, s10, 0x20000
	s_addc_u32 s99, s11, 0
	global_store_dwordx4 v203, v[108:111], s[98:99]
	s_add_u32 s42, s10, 0x80000
	s_addc_u32 s43, s11, 0
	global_load_dwordx4 v[180:183], v203, s[42:43]
	s_add_u32 s98, s14, 0xc0000
	s_addc_u32 s99, s15, 0
	global_load_dwordx4 v[206:209], v235, s[98:99] offset:16
	s_waitcnt vmcnt(22)
	v_pk_fma_f32 v[104:105], v[210:211], v[104:105], v[236:237]
	v_pk_fma_f32 v[106:107], v[212:213], v[106:107], v[238:239]
	s_add_u32 s42, s10, 0x20000
	s_addc_u32 s43, s11, 0
	global_store_dwordx4 v203, v[104:107], s[42:43] offset:16
	s_add_u32 s98, s10, 0x80000
	s_addc_u32 s99, s11, 0
	global_load_dwordx4 v[210:213], v203, s[98:99] offset:16
	s_add_u32 s42, s14, 0xc0200
	s_addc_u32 s43, s15, 0
	global_load_dwordx4 v[236:239], v235, s[42:43]
	s_waitcnt vmcnt(22)
	v_pk_fma_f32 v[76:77], v[128:129], v[76:77], v[132:133]
	v_pk_fma_f32 v[78:79], v[130:131], v[78:79], v[134:135]
	s_add_u32 s98, s10, 0x20200
	s_addc_u32 s99, s11, 0
	global_store_dwordx4 v203, v[76:79], s[98:99]
	s_add_u32 s42, s10, 0x80200
	s_addc_u32 s43, s11, 0
	global_load_dwordx4 v[128:131], v203, s[42:43]
	s_add_u32 s98, s14, 0xc0200
	s_addc_u32 s99, s15, 0
	global_load_dwordx4 v[132:135], v235, s[98:99] offset:16
	s_waitcnt vmcnt(22)
	v_pk_fma_f32 v[72:73], v[136:137], v[72:73], v[140:141]
	v_pk_fma_f32 v[74:75], v[138:139], v[74:75], v[142:143]
	s_add_u32 s42, s10, 0x20200
	s_addc_u32 s43, s11, 0
	global_store_dwordx4 v203, v[72:75], s[42:43] offset:16
	s_add_u32 s98, s10, 0x80200
	s_addc_u32 s99, s11, 0
	global_load_dwordx4 v[136:139], v203, s[98:99] offset:16
	s_add_u32 s42, s14, 0xd8000
	s_addc_u32 s43, s15, 0
	global_load_dwordx4 v[140:143], v235, s[42:43]
	s_waitcnt vmcnt(22)
	v_pk_fma_f32 v[100:101], v[144:145], v[100:101], v[148:149]
	v_pk_fma_f32 v[102:103], v[146:147], v[102:103], v[150:151]
	s_add_u32 s98, s10, 0x30000
	s_addc_u32 s99, s11, 0
	global_store_dwordx4 v203, v[100:103], s[98:99]
	s_add_u32 s42, s10, 0x90000
	s_addc_u32 s43, s11, 0
	global_load_dwordx4 v[144:147], v203, s[42:43]
	s_add_u32 s98, s14, 0xd8000
	s_addc_u32 s99, s15, 0
	global_load_dwordx4 v[148:151], v235, s[98:99] offset:16
	s_waitcnt vmcnt(22)
	v_pk_fma_f32 v[96:97], v[152:153], v[96:97], v[156:157]
	v_pk_fma_f32 v[98:99], v[154:155], v[98:99], v[158:159]
	s_add_u32 s42, s10, 0x30000
	s_addc_u32 s43, s11, 0
	global_store_dwordx4 v203, v[96:99], s[42:43] offset:16
	s_add_u32 s98, s10, 0x90000
	s_addc_u32 s99, s11, 0
	global_load_dwordx4 v[152:155], v203, s[98:99] offset:16
	s_add_u32 s42, s14, 0xd8200
	s_addc_u32 s43, s15, 0
	global_load_dwordx4 v[156:159], v235, s[42:43]
	s_waitcnt vmcnt(22)
	v_pk_fma_f32 v[68:69], v[160:161], v[68:69], v[164:165]
	v_pk_fma_f32 v[70:71], v[162:163], v[70:71], v[166:167]
	s_add_u32 s98, s10, 0x30200
	s_addc_u32 s99, s11, 0
	global_store_dwordx4 v203, v[68:71], s[98:99]
	s_add_u32 s42, s10, 0x90200
	s_addc_u32 s43, s11, 0
	global_load_dwordx4 v[160:163], v203, s[42:43]
	s_add_u32 s98, s14, 0xd8200
	s_addc_u32 s99, s15, 0
	global_load_dwordx4 v[164:167], v235, s[98:99] offset:16
	s_waitcnt vmcnt(22)
	v_pk_fma_f32 v[64:65], v[168:169], v[64:65], v[172:173]
	v_pk_fma_f32 v[66:67], v[170:171], v[66:67], v[174:175]
	s_add_u32 s42, s10, 0x30200
	s_addc_u32 s43, s11, 0
	global_store_dwordx4 v203, v[64:67], s[42:43] offset:16
	s_add_u32 s98, s10, 0x90200
	s_addc_u32 s99, s11, 0
	global_load_dwordx4 v[168:171], v203, s[98:99] offset:16
	s_add_u32 s42, s14, 0xf0000
	s_addc_u32 s43, s15, 0
	global_load_dwordx4 v[172:175], v235, s[42:43]
	s_waitcnt vmcnt(22)
	v_pk_fma_f32 v[60:61], v[176:177], v[60:61], v[180:181]
	v_pk_fma_f32 v[62:63], v[178:179], v[62:63], v[182:183]
	s_add_u32 s98, s10, 0x80000
	s_addc_u32 s99, s11, 0
	global_store_dwordx4 v203, v[60:63], s[98:99]
	s_add_u32 s42, s10, 0xa0000
	s_addc_u32 s43, s11, 0
	global_load_dwordx4 v[176:179], v203, s[42:43]
	s_add_u32 s98, s14, 0xf0000
	s_addc_u32 s99, s15, 0
	global_load_dwordx4 v[180:183], v235, s[98:99] offset:16
	s_waitcnt vmcnt(22)
	v_pk_fma_f32 v[56:57], v[206:207], v[56:57], v[210:211]
	v_pk_fma_f32 v[58:59], v[208:209], v[58:59], v[212:213]
	s_add_u32 s42, s10, 0x80000
	s_addc_u32 s43, s11, 0
	global_store_dwordx4 v203, v[56:59], s[42:43] offset:16
	s_add_u32 s98, s10, 0xa0000
	s_addc_u32 s99, s11, 0
	global_load_dwordx4 v[206:209], v203, s[98:99] offset:16
	s_add_u32 s42, s14, 0xf0200
	s_addc_u32 s43, s15, 0
	global_load_dwordx4 v[210:213], v235, s[42:43]
	s_waitcnt vmcnt(22)
	v_pk_fma_f32 v[28:29], v[236:237], v[28:29], v[128:129]
	v_pk_fma_f32 v[30:31], v[238:239], v[30:31], v[130:131]
	s_add_u32 s98, s10, 0x80200
	s_addc_u32 s99, s11, 0
	global_store_dwordx4 v203, v[28:31], s[98:99]
	s_add_u32 s42, s10, 0xa0200
	s_addc_u32 s43, s11, 0
	global_load_dwordx4 v[236:239], v203, s[42:43]
	s_add_u32 s98, s14, 0xf0200
	s_addc_u32 s99, s15, 0
	global_load_dwordx4 v[128:131], v235, s[98:99] offset:16
	s_waitcnt vmcnt(22)
	v_pk_fma_f32 v[24:25], v[132:133], v[24:25], v[136:137]
	v_pk_fma_f32 v[26:27], v[134:135], v[26:27], v[138:139]
	s_add_u32 s42, s10, 0x80200
	s_addc_u32 s43, s11, 0
	global_store_dwordx4 v203, v[24:27], s[42:43] offset:16
	s_add_u32 s98, s10, 0xa0200
	s_addc_u32 s99, s11, 0
	global_load_dwordx4 v[132:135], v203, s[98:99] offset:16
	s_add_u32 s42, s14, 0x108000
	s_addc_u32 s43, s15, 0
	global_load_dwordx4 v[136:139], v235, s[42:43]
	s_waitcnt vmcnt(22)
	v_pk_fma_f32 v[52:53], v[140:141], v[52:53], v[144:145]
	v_pk_fma_f32 v[54:55], v[142:143], v[54:55], v[146:147]
	s_add_u32 s98, s10, 0x90000
	s_addc_u32 s99, s11, 0
	global_store_dwordx4 v203, v[52:55], s[98:99]
	s_add_u32 s42, s10, 0xb0000
	s_addc_u32 s43, s11, 0
	global_load_dwordx4 v[140:143], v203, s[42:43]
	s_add_u32 s98, s14, 0x108000
	s_addc_u32 s99, s15, 0
	global_load_dwordx4 v[144:147], v235, s[98:99] offset:16
	s_waitcnt vmcnt(22)
	v_pk_fma_f32 v[48:49], v[148:149], v[48:49], v[152:153]
	v_pk_fma_f32 v[50:51], v[150:151], v[50:51], v[154:155]
	s_add_u32 s42, s10, 0x90000
	s_addc_u32 s43, s11, 0
	global_store_dwordx4 v203, v[48:51], s[42:43] offset:16
	s_add_u32 s98, s10, 0xb0000
	s_addc_u32 s99, s11, 0
	global_load_dwordx4 v[148:151], v203, s[98:99] offset:16
	s_add_u32 s42, s14, 0x108200
	s_addc_u32 s43, s15, 0
	global_load_dwordx4 v[152:155], v235, s[42:43]
	s_waitcnt vmcnt(22)
	v_pk_fma_f32 v[20:21], v[156:157], v[20:21], v[160:161]
	v_pk_fma_f32 v[22:23], v[158:159], v[22:23], v[162:163]
	s_add_u32 s98, s10, 0x90200
	s_addc_u32 s99, s11, 0
	global_store_dwordx4 v203, v[20:23], s[98:99]
	s_add_u32 s42, s10, 0xb0200
	s_addc_u32 s43, s11, 0
	global_load_dwordx4 v[156:159], v203, s[42:43]
	s_add_u32 s98, s14, 0x108200
	s_addc_u32 s99, s15, 0
	global_load_dwordx4 v[160:163], v235, s[98:99] offset:16
	s_waitcnt vmcnt(22)
	v_pk_fma_f32 v[16:17], v[164:165], v[16:17], v[168:169]
	v_pk_fma_f32 v[18:19], v[166:167], v[18:19], v[170:171]
	s_add_u32 s42, s10, 0x90200
	s_addc_u32 s43, s11, 0
	global_store_dwordx4 v203, v[16:19], s[42:43] offset:16
	s_add_u32 s98, s10, 0xb0200
	s_addc_u32 s99, s11, 0
	global_load_dwordx4 v[164:167], v203, s[98:99] offset:16
	s_waitcnt vmcnt(21)
	v_pk_fma_f32 v[44:45], v[172:173], v[44:45], v[176:177]
	v_pk_fma_f32 v[46:47], v[174:175], v[46:47], v[178:179]
	s_add_u32 s42, s10, 0xa0000
	s_addc_u32 s43, s11, 0
	global_store_dwordx4 v203, v[44:47], s[42:43]
	s_waitcnt vmcnt(19)
	v_pk_fma_f32 v[40:41], v[180:181], v[40:41], v[206:207]
	v_pk_fma_f32 v[42:43], v[182:183], v[42:43], v[208:209]
	s_add_u32 s98, s10, 0xa0000
	s_addc_u32 s99, s11, 0
	global_store_dwordx4 v203, v[40:43], s[98:99] offset:16
	s_waitcnt vmcnt(17)
	v_pk_fma_f32 v[12:13], v[210:211], v[12:13], v[236:237]
	v_pk_fma_f32 v[14:15], v[212:213], v[14:15], v[238:239]
	s_add_u32 s42, s10, 0xa0200
	s_addc_u32 s43, s11, 0
	global_store_dwordx4 v203, v[12:15], s[42:43]
	s_waitcnt vmcnt(15)
	v_pk_fma_f32 v[8:9], v[128:129], v[8:9], v[132:133]
	v_pk_fma_f32 v[10:11], v[130:131], v[10:11], v[134:135]
	s_add_u32 s98, s10, 0xa0200
	s_addc_u32 s99, s11, 0
	global_store_dwordx4 v203, v[8:11], s[98:99] offset:16
	s_waitcnt vmcnt(13)
	v_pk_fma_f32 v[36:37], v[136:137], v[36:37], v[140:141]
	v_pk_fma_f32 v[38:39], v[138:139], v[38:39], v[142:143]
	s_add_u32 s42, s10, 0xb0000
	s_addc_u32 s43, s11, 0
	global_store_dwordx4 v203, v[36:39], s[42:43]
	s_waitcnt vmcnt(11)
	v_pk_fma_f32 v[32:33], v[144:145], v[32:33], v[148:149]
	v_pk_fma_f32 v[34:35], v[146:147], v[34:35], v[150:151]
	s_add_u32 s98, s10, 0xb0000
	s_addc_u32 s99, s11, 0
	global_store_dwordx4 v203, v[32:35], s[98:99] offset:16
	s_waitcnt vmcnt(9)
	v_pk_fma_f32 v[4:5], v[152:153], v[4:5], v[156:157]
	v_pk_fma_f32 v[6:7], v[154:155], v[6:7], v[158:159]
	s_add_u32 s42, s10, 0xb0200
	s_addc_u32 s43, s11, 0
	global_store_dwordx4 v203, v[4:7], s[42:43]
	s_waitcnt vmcnt(7)
	v_pk_fma_f32 v[0:1], v[160:161], v[0:1], v[164:165]
	v_pk_fma_f32 v[2:3], v[162:163], v[2:3], v[166:167]
	s_add_u32 s98, s10, 0xb0200
	s_addc_u32 s99, s11, 0
	global_store_dwordx4 v203, v[0:3], s[98:99] offset:16
	s_branch .Lfs_predone
.Lfs_np2:
	s_add_u32 s42, s62, 0x0
	s_addc_u32 s43, s63, 0
	global_load_dwordx4 v[128:131], v205, s[42:43] sc0 sc1
	s_add_u32 s98, s62, 0x1000
	s_addc_u32 s99, s63, 0
	global_load_dwordx4 v[132:135], v205, s[98:99] sc0 sc1
	s_add_u32 s42, s62, 0x400
	s_addc_u32 s43, s63, 0
	global_load_dwordx4 v[136:139], v205, s[42:43] sc0 sc1
	s_add_u32 s98, s62, 0x1400
	s_addc_u32 s99, s63, 0
	global_load_dwordx4 v[140:143], v205, s[98:99] sc0 sc1
	s_add_u32 s42, s62, 0x800
	s_addc_u32 s43, s63, 0
	global_load_dwordx4 v[144:147], v205, s[42:43] sc0 sc1
	s_add_u32 s98, s62, 0x1800
	s_addc_u32 s99, s63, 0
	global_load_dwordx4 v[148:151], v205, s[98:99] sc0 sc1
	s_add_u32 s42, s62, 0xc00
	s_addc_u32 s43, s63, 0
	global_load_dwordx4 v[152:155], v205, s[42:43] sc0 sc1
	s_add_u32 s98, s62, 0x1c00
	s_addc_u32 s99, s63, 0
	global_load_dwordx4 v[156:159], v205, s[98:99] sc0 sc1
	s_add_u32 s42, s62, 0x2000
	s_addc_u32 s43, s63, 0
	global_load_dwordx4 v[160:163], v205, s[42:43] sc0 sc1
	s_add_u32 s98, s62, 0x3000
	s_addc_u32 s99, s63, 0
	global_load_dwordx4 v[164:167], v205, s[98:99] sc0 sc1
	s_add_u32 s42, s62, 0x2400
	s_addc_u32 s43, s63, 0
	global_load_dwordx4 v[168:171], v205, s[42:43] sc0 sc1
	s_add_u32 s98, s62, 0x3400
	s_addc_u32 s99, s63, 0
	global_load_dwordx4 v[172:175], v205, s[98:99] sc0 sc1
	s_add_u32 s42, s62, 0x2800
	s_addc_u32 s43, s63, 0
	global_load_dwordx4 v[176:179], v205, s[42:43] sc0 sc1
	s_add_u32 s98, s62, 0x3800
	s_addc_u32 s99, s63, 0
	global_load_dwordx4 v[180:183], v205, s[98:99] sc0 sc1
	s_add_u32 s42, s62, 0x2c00
	s_addc_u32 s43, s63, 0
	global_load_dwordx4 v[206:209], v205, s[42:43] sc0 sc1
	s_add_u32 s98, s62, 0x3c00
	s_addc_u32 s99, s63, 0
	global_load_dwordx4 v[210:213], v205, s[98:99] sc0 sc1
	s_add_u32 s42, s62, 0x20000
	s_addc_u32 s43, s63, 0
	global_load_dwordx4 v[236:239], v205, s[42:43] sc0 sc1
	s_waitcnt vmcnt(16)
	v_lshlrev_b32_e32 v240, 16, v128
	v_and_b32_e32 v241, 0xffff0000, v128
	v_pk_add_f32 v[124:125], v[124:125], v[240:241]
	v_lshlrev_b32_e32 v240, 16, v129
	v_and_b32_e32 v241, 0xffff0000, v129
	v_pk_add_f32 v[126:127], v[126:127], v[240:241]
	v_lshlrev_b32_e32 v240, 16, v130
	v_and_b32_e32 v241, 0xffff0000, v130
	v_pk_add_f32 v[120:121], v[120:121], v[240:241]
	v_lshlrev_b32_e32 v240, 16, v131
	v_and_b32_e32 v241, 0xffff0000, v131
	v_pk_add_f32 v[122:123], v[122:123], v[240:241]
	s_add_u32 s98, s62, 0x21000
	s_addc_u32 s99, s63, 0
	global_load_dwordx4 v[128:131], v205, s[98:99] sc0 sc1
	s_waitcnt vmcnt(16)
	v_lshlrev_b32_e32 v240, 16, v132
	v_and_b32_e32 v241, 0xffff0000, v132
	v_pk_add_f32 v[92:93], v[92:93], v[240:241]
	v_lshlrev_b32_e32 v240, 16, v133
	v_and_b32_e32 v241, 0xffff0000, v133
	v_pk_add_f32 v[94:95], v[94:95], v[240:241]
	v_lshlrev_b32_e32 v240, 16, v134
	v_and_b32_e32 v241, 0xffff0000, v134
	v_pk_add_f32 v[88:89], v[88:89], v[240:241]
	v_lshlrev_b32_e32 v240, 16, v135
	v_and_b32_e32 v241, 0xffff0000, v135
	v_pk_add_f32 v[90:91], v[90:91], v[240:241]
	s_add_u32 s42, s62, 0x20400
	s_addc_u32 s43, s63, 0
	global_load_dwordx4 v[132:135], v205, s[42:43] sc0 sc1
	s_waitcnt vmcnt(16)
	v_lshlrev_b32_e32 v240, 16, v136
	v_and_b32_e32 v241, 0xffff0000, v136
	v_pk_add_f32 v[116:117], v[116:117], v[240:241]
	v_lshlrev_b32_e32 v240, 16, v137
	v_and_b32_e32 v241, 0xffff0000, v137
	v_pk_add_f32 v[118:119], v[118:119], v[240:241]
	v_lshlrev_b32_e32 v240, 16, v138
	v_and_b32_e32 v241, 0xffff0000, v138
	v_pk_add_f32 v[112:113], v[112:113], v[240:241]
	v_lshlrev_b32_e32 v240, 16, v139
	v_and_b32_e32 v241, 0xffff0000, v139
	v_pk_add_f32 v[114:115], v[114:115], v[240:241]
	s_add_u32 s98, s62, 0x21400
	s_addc_u32 s99, s63, 0
	global_load_dwordx4 v[136:139], v205, s[98:99] sc0 sc1
	s_waitcnt vmcnt(16)
	v_lshlrev_b32_e32 v240, 16, v140
	v_and_b32_e32 v241, 0xffff0000, v140
	v_pk_add_f32 v[84:85], v[84:85], v[240:241]
	v_lshlrev_b32_e32 v240, 16, v141
	v_and_b32_e32 v241, 0xffff0000, v141
	v_pk_add_f32 v[86:87], v[86:87], v[240:241]
	v_lshlrev_b32_e32 v240, 16, v142
	v_and_b32_e32 v241, 0xffff0000, v142
	v_pk_add_f32 v[80:81], v[80:81], v[240:241]
	v_lshlrev_b32_e32 v240, 16, v143
	v_and_b32_e32 v241, 0xffff0000, v143
	v_pk_add_f32 v[82:83], v[82:83], v[240:241]
	s_add_u32 s42, s62, 0x20800
	s_addc_u32 s43, s63, 0
	global_load_dwordx4 v[140:143], v205, s[42:43] sc0 sc1
	s_waitcnt vmcnt(16)
	v_lshlrev_b32_e32 v240, 16, v144
	v_and_b32_e32 v241, 0xffff0000, v144
	v_pk_add_f32 v[108:109], v[108:109], v[240:241]
	v_lshlrev_b32_e32 v240, 16, v145
	v_and_b32_e32 v241, 0xffff0000, v145
	v_pk_add_f32 v[110:111], v[110:111], v[240:241]
	v_lshlrev_b32_e32 v240, 16, v146
	v_and_b32_e32 v241, 0xffff0000, v146
	v_pk_add_f32 v[104:105], v[104:105], v[240:241]
	v_lshlrev_b32_e32 v240, 16, v147
	v_and_b32_e32 v241, 0xffff0000, v147
	v_pk_add_f32 v[106:107], v[106:107], v[240:241]
	s_add_u32 s98, s62, 0x21800
	s_addc_u32 s99, s63, 0
	global_load_dwordx4 v[144:147], v205, s[98:99] sc0 sc1
	s_waitcnt vmcnt(16)
	v_lshlrev_b32_e32 v240, 16, v148
	v_and_b32_e32 v241, 0xffff0000, v148
	v_pk_add_f32 v[76:77], v[76:77], v[240:241]
	v_lshlrev_b32_e32 v240, 16, v149
	v_and_b32_e32 v241, 0xffff0000, v149
	v_pk_add_f32 v[78:79], v[78:79], v[240:241]
	v_lshlrev_b32_e32 v240, 16, v150
	v_and_b32_e32 v241, 0xffff0000, v150
	v_pk_add_f32 v[72:73], v[72:73], v[240:241]
	v_lshlrev_b32_e32 v240, 16, v151
	v_and_b32_e32 v241, 0xffff0000, v151
	v_pk_add_f32 v[74:75], v[74:75], v[240:241]
	s_add_u32 s42, s62, 0x20c00
	s_addc_u32 s43, s63, 0
	global_load_dwordx4 v[148:151], v205, s[42:43] sc0 sc1
	s_waitcnt vmcnt(16)
	v_lshlrev_b32_e32 v240, 16, v152
	v_and_b32_e32 v241, 0xffff0000, v152
	v_pk_add_f32 v[100:101], v[100:101], v[240:241]
	v_lshlrev_b32_e32 v240, 16, v153
	v_and_b32_e32 v241, 0xffff0000, v153
	v_pk_add_f32 v[102:103], v[102:103], v[240:241]
	v_lshlrev_b32_e32 v240, 16, v154
	v_and_b32_e32 v241, 0xffff0000, v154
	v_pk_add_f32 v[96:97], v[96:97], v[240:241]
	v_lshlrev_b32_e32 v240, 16, v155
	v_and_b32_e32 v241, 0xffff0000, v155
	v_pk_add_f32 v[98:99], v[98:99], v[240:241]
	s_add_u32 s98, s62, 0x21c00
	s_addc_u32 s99, s63, 0
	global_load_dwordx4 v[152:155], v205, s[98:99] sc0 sc1
	s_waitcnt vmcnt(16)
	v_lshlrev_b32_e32 v240, 16, v156
	v_and_b32_e32 v241, 0xffff0000, v156
	v_pk_add_f32 v[68:69], v[68:69], v[240:241]
	v_lshlrev_b32_e32 v240, 16, v157
	v_and_b32_e32 v241, 0xffff0000, v157
	v_pk_add_f32 v[70:71], v[70:71], v[240:241]
	v_lshlrev_b32_e32 v240, 16, v158
	v_and_b32_e32 v241, 0xffff0000, v158
	v_pk_add_f32 v[64:65], v[64:65], v[240:241]
	v_lshlrev_b32_e32 v240, 16, v159
	v_and_b32_e32 v241, 0xffff0000, v159
	v_pk_add_f32 v[66:67], v[66:67], v[240:241]
	s_add_u32 s42, s62, 0x22000
	s_addc_u32 s43, s63, 0
	global_load_dwordx4 v[156:159], v205, s[42:43] sc0 sc1
	s_waitcnt vmcnt(16)
	v_lshlrev_b32_e32 v240, 16, v160
	v_and_b32_e32 v241, 0xffff0000, v160
	v_pk_add_f32 v[60:61], v[60:61], v[240:241]
	v_lshlrev_b32_e32 v240, 16, v161
	v_and_b32_e32 v241, 0xffff0000, v161
	v_pk_add_f32 v[62:63], v[62:63], v[240:241]
	v_lshlrev_b32_e32 v240, 16, v162
	v_and_b32_e32 v241, 0xffff0000, v162
	v_pk_add_f32 v[56:57], v[56:57], v[240:241]
	v_lshlrev_b32_e32 v240, 16, v163
	v_and_b32_e32 v241, 0xffff0000, v163
	v_pk_add_f32 v[58:59], v[58:59], v[240:241]
	s_add_u32 s98, s62, 0x23000
	s_addc_u32 s99, s63, 0
	global_load_dwordx4 v[160:163], v205, s[98:99] sc0 sc1
	s_waitcnt vmcnt(16)
	v_lshlrev_b32_e32 v240, 16, v164
	v_and_b32_e32 v241, 0xffff0000, v164
	v_pk_add_f32 v[28:29], v[28:29], v[240:241]
	v_lshlrev_b32_e32 v240, 16, v165
	v_and_b32_e32 v241, 0xffff0000, v165
	v_pk_add_f32 v[30:31], v[30:31], v[240:241]
	v_lshlrev_b32_e32 v240, 16, v166
	v_and_b32_e32 v241, 0xffff0000, v166
	v_pk_add_f32 v[24:25], v[24:25], v[240:241]
	v_lshlrev_b32_e32 v240, 16, v167
	v_and_b32_e32 v241, 0xffff0000, v167
	v_pk_add_f32 v[26:27], v[26:27], v[240:241]
	s_add_u32 s42, s62, 0x22400
	s_addc_u32 s43, s63, 0
	global_load_dwordx4 v[164:167], v205, s[42:43] sc0 sc1
	s_waitcnt vmcnt(16)
	v_lshlrev_b32_e32 v240, 16, v168
	v_and_b32_e32 v241, 0xffff0000, v168
	v_pk_add_f32 v[52:53], v[52:53], v[240:241]
	v_lshlrev_b32_e32 v240, 16, v169
	v_and_b32_e32 v241, 0xffff0000, v169
	v_pk_add_f32 v[54:55], v[54:55], v[240:241]
	v_lshlrev_b32_e32 v240, 16, v170
	v_and_b32_e32 v241, 0xffff0000, v170
	v_pk_add_f32 v[48:49], v[48:49], v[240:241]
	v_lshlrev_b32_e32 v240, 16, v171
	v_and_b32_e32 v241, 0xffff0000, v171
	v_pk_add_f32 v[50:51], v[50:51], v[240:241]
	s_add_u32 s98, s62, 0x23400
	s_addc_u32 s99, s63, 0
	global_load_dwordx4 v[168:171], v205, s[98:99] sc0 sc1
	s_waitcnt vmcnt(16)
	v_lshlrev_b32_e32 v240, 16, v172
	v_and_b32_e32 v241, 0xffff0000, v172
	v_pk_add_f32 v[20:21], v[20:21], v[240:241]
	v_lshlrev_b32_e32 v240, 16, v173
	v_and_b32_e32 v241, 0xffff0000, v173
	v_pk_add_f32 v[22:23], v[22:23], v[240:241]
	v_lshlrev_b32_e32 v240, 16, v174
	v_and_b32_e32 v241, 0xffff0000, v174
	v_pk_add_f32 v[16:17], v[16:17], v[240:241]
	v_lshlrev_b32_e32 v240, 16, v175
	v_and_b32_e32 v241, 0xffff0000, v175
	v_pk_add_f32 v[18:19], v[18:19], v[240:241]
	s_add_u32 s42, s62, 0x22800
	s_addc_u32 s43, s63, 0
	global_load_dwordx4 v[172:175], v205, s[42:43] sc0 sc1
	s_waitcnt vmcnt(16)
	v_lshlrev_b32_e32 v240, 16, v176
	v_and_b32_e32 v241, 0xffff0000, v176
	v_pk_add_f32 v[44:45], v[44:45], v[240:241]
	v_lshlrev_b32_e32 v240, 16, v177
	v_and_b32_e32 v241, 0xffff0000, v177
	v_pk_add_f32 v[46:47], v[46:47], v[240:241]
	v_lshlrev_b32_e32 v240, 16, v178
	v_and_b32_e32 v241, 0xffff0000, v178
	v_pk_add_f32 v[40:41], v[40:41], v[240:241]
	v_lshlrev_b32_e32 v240, 16, v179
	v_and_b32_e32 v241, 0xffff0000, v179
	v_pk_add_f32 v[42:43], v[42:43], v[240:241]
	s_add_u32 s98, s62, 0x23800
	s_addc_u32 s99, s63, 0
	global_load_dwordx4 v[176:179], v205, s[98:99] sc0 sc1
	s_waitcnt vmcnt(16)
	v_lshlrev_b32_e32 v240, 16, v180
	v_and_b32_e32 v241, 0xffff0000, v180
	v_pk_add_f32 v[12:13], v[12:13], v[240:241]
	v_lshlrev_b32_e32 v240, 16, v181
	v_and_b32_e32 v241, 0xffff0000, v181
	v_pk_add_f32 v[14:15], v[14:15], v[240:241]
	v_lshlrev_b32_e32 v240, 16, v182
	v_and_b32_e32 v241, 0xffff0000, v182
	v_pk_add_f32 v[8:9], v[8:9], v[240:241]
	v_lshlrev_b32_e32 v240, 16, v183
	v_and_b32_e32 v241, 0xffff0000, v183
	v_pk_add_f32 v[10:11], v[10:11], v[240:241]
	s_add_u32 s42, s62, 0x22c00
	s_addc_u32 s43, s63, 0
	global_load_dwordx4 v[180:183], v205, s[42:43] sc0 sc1
	s_waitcnt vmcnt(16)
	v_lshlrev_b32_e32 v240, 16, v206
	v_and_b32_e32 v241, 0xffff0000, v206
	v_pk_add_f32 v[36:37], v[36:37], v[240:241]
	v_lshlrev_b32_e32 v240, 16, v207
	v_and_b32_e32 v241, 0xffff0000, v207
	v_pk_add_f32 v[38:39], v[38:39], v[240:241]
	v_lshlrev_b32_e32 v240, 16, v208
	v_and_b32_e32 v241, 0xffff0000, v208
	v_pk_add_f32 v[32:33], v[32:33], v[240:241]
	v_lshlrev_b32_e32 v240, 16, v209
	v_and_b32_e32 v241, 0xffff0000, v209
	v_pk_add_f32 v[34:35], v[34:35], v[240:241]
	s_add_u32 s98, s62, 0x23c00
	s_addc_u32 s99, s63, 0
	global_load_dwordx4 v[206:209], v205, s[98:99] sc0 sc1
	s_waitcnt vmcnt(16)
	v_lshlrev_b32_e32 v240, 16, v210
	v_and_b32_e32 v241, 0xffff0000, v210
	v_pk_add_f32 v[4:5], v[4:5], v[240:241]
	v_lshlrev_b32_e32 v240, 16, v211
	v_and_b32_e32 v241, 0xffff0000, v211
	v_pk_add_f32 v[6:7], v[6:7], v[240:241]
	v_lshlrev_b32_e32 v240, 16, v212
	v_and_b32_e32 v241, 0xffff0000, v212
	v_pk_add_f32 v[0:1], v[0:1], v[240:241]
	v_lshlrev_b32_e32 v240, 16, v213
	v_and_b32_e32 v241, 0xffff0000, v213
	v_pk_add_f32 v[2:3], v[2:3], v[240:241]
	s_add_u32 s42, s14, 0x0
	s_addc_u32 s43, s15, 0
	global_load_dwordx4 v[210:213], v235, s[42:43]
	s_waitcnt vmcnt(16)
	v_lshlrev_b32_e32 v240, 16, v236
	v_and_b32_e32 v241, 0xffff0000, v236
	v_pk_add_f32 v[124:125], v[124:125], v[240:241]
	v_lshlrev_b32_e32 v240, 16, v237
	v_and_b32_e32 v241, 0xffff0000, v237
	v_pk_add_f32 v[126:127], v[126:127], v[240:241]
	v_lshlrev_b32_e32 v240, 16, v238
	v_and_b32_e32 v241, 0xffff0000, v238
	v_pk_add_f32 v[120:121], v[120:121], v[240:241]
	v_lshlrev_b32_e32 v240, 16, v239
	v_and_b32_e32 v241, 0xffff0000, v239
	v_pk_add_f32 v[122:123], v[122:123], v[240:241]
	s_add_u32 s98, s10, 0x0
	s_addc_u32 s99, s11, 0
	global_load_dwordx4 v[236:239], v203, s[98:99]
	s_waitcnt vmcnt(16)
	v_lshlrev_b32_e32 v240, 16, v128
	v_and_b32_e32 v241, 0xffff0000, v128
	v_pk_add_f32 v[92:93], v[92:93], v[240:241]
	v_lshlrev_b32_e32 v240, 16, v129
	v_and_b32_e32 v241, 0xffff0000, v129
	v_pk_add_f32 v[94:95], v[94:95], v[240:241]
	v_lshlrev_b32_e32 v240, 16, v130
	v_and_b32_e32 v241, 0xffff0000, v130
	v_pk_add_f32 v[88:89], v[88:89], v[240:241]
	v_lshlrev_b32_e32 v240, 16, v131
	v_and_b32_e32 v241, 0xffff0000, v131
	v_pk_add_f32 v[90:91], v[90:91], v[240:241]
	s_add_u32 s42, s14, 0x0
	s_addc_u32 s43, s15, 0
	global_load_dwordx4 v[128:131], v235, s[42:43] offset:16
	s_waitcnt vmcnt(16)
	v_lshlrev_b32_e32 v240, 16, v132
	v_and_b32_e32 v241, 0xffff0000, v132
	v_pk_add_f32 v[116:117], v[116:117], v[240:241]
	v_lshlrev_b32_e32 v240, 16, v133
	v_and_b32_e32 v241, 0xffff0000, v133
	v_pk_add_f32 v[118:119], v[118:119], v[240:241]
	v_lshlrev_b32_e32 v240, 16, v134
	v_and_b32_e32 v241, 0xffff0000, v134
	v_pk_add_f32 v[112:113], v[112:113], v[240:241]
	v_lshlrev_b32_e32 v240, 16, v135
	v_and_b32_e32 v241, 0xffff0000, v135
	v_pk_add_f32 v[114:115], v[114:115], v[240:241]
	s_add_u32 s98, s10, 0x0
	s_addc_u32 s99, s11, 0
	global_load_dwordx4 v[132:135], v203, s[98:99] offset:16
	s_waitcnt vmcnt(16)
	v_lshlrev_b32_e32 v240, 16, v136
	v_and_b32_e32 v241, 0xffff0000, v136
	v_pk_add_f32 v[84:85], v[84:85], v[240:241]
	v_lshlrev_b32_e32 v240, 16, v137
	v_and_b32_e32 v241, 0xffff0000, v137
	v_pk_add_f32 v[86:87], v[86:87], v[240:241]
	v_lshlrev_b32_e32 v240, 16, v138
	v_and_b32_e32 v241, 0xffff0000, v138
	v_pk_add_f32 v[80:81], v[80:81], v[240:241]
	v_lshlrev_b32_e32 v240, 16, v139
	v_and_b32_e32 v241, 0xffff0000, v139
	v_pk_add_f32 v[82:83], v[82:83], v[240:241]
	s_add_u32 s42, s14, 0x200
	s_addc_u32 s43, s15, 0
	global_load_dwordx4 v[136:139], v235, s[42:43]
	s_waitcnt vmcnt(16)
	v_lshlrev_b32_e32 v240, 16, v140
	v_and_b32_e32 v241, 0xffff0000, v140
	v_pk_add_f32 v[108:109], v[108:109], v[240:241]
	v_lshlrev_b32_e32 v240, 16, v141
	v_and_b32_e32 v241, 0xffff0000, v141
	v_pk_add_f32 v[110:111], v[110:111], v[240:241]
	v_lshlrev_b32_e32 v240, 16, v142
	v_and_b32_e32 v241, 0xffff0000, v142
	v_pk_add_f32 v[104:105], v[104:105], v[240:241]
	v_lshlrev_b32_e32 v240, 16, v143
	v_and_b32_e32 v241, 0xffff0000, v143
	v_pk_add_f32 v[106:107], v[106:107], v[240:241]
	s_add_u32 s98, s10, 0x200
	s_addc_u32 s99, s11, 0
	global_load_dwordx4 v[140:143], v203, s[98:99]
	s_waitcnt vmcnt(16)
	v_lshlrev_b32_e32 v240, 16, v144
	v_and_b32_e32 v241, 0xffff0000, v144
	v_pk_add_f32 v[76:77], v[76:77], v[240:241]
	v_lshlrev_b32_e32 v240, 16, v145
	v_and_b32_e32 v241, 0xffff0000, v145
	v_pk_add_f32 v[78:79], v[78:79], v[240:241]
	v_lshlrev_b32_e32 v240, 16, v146
	v_and_b32_e32 v241, 0xffff0000, v146
	v_pk_add_f32 v[72:73], v[72:73], v[240:241]
	v_lshlrev_b32_e32 v240, 16, v147
	v_and_b32_e32 v241, 0xffff0000, v147
	v_pk_add_f32 v[74:75], v[74:75], v[240:241]
	s_add_u32 s42, s14, 0x200
	s_addc_u32 s43, s15, 0
	global_load_dwordx4 v[144:147], v235, s[42:43] offset:16
	s_waitcnt vmcnt(16)
	v_lshlrev_b32_e32 v240, 16, v148
	v_and_b32_e32 v241, 0xffff0000, v148
	v_pk_add_f32 v[100:101], v[100:101], v[240:241]
	v_lshlrev_b32_e32 v240, 16, v149
	v_and_b32_e32 v241, 0xffff0000, v149
	v_pk_add_f32 v[102:103], v[102:103], v[240:241]
	v_lshlrev_b32_e32 v240, 16, v150
	v_and_b32_e32 v241, 0xffff0000, v150
	v_pk_add_f32 v[96:97], v[96:97], v[240:241]
	v_lshlrev_b32_e32 v240, 16, v151
	v_and_b32_e32 v241, 0xffff0000, v151
	v_pk_add_f32 v[98:99], v[98:99], v[240:241]
	s_add_u32 s98, s10, 0x200
	s_addc_u32 s99, s11, 0
	global_load_dwordx4 v[148:151], v203, s[98:99] offset:16
	s_waitcnt vmcnt(16)
	v_lshlrev_b32_e32 v240, 16, v152
	v_and_b32_e32 v241, 0xffff0000, v152
	v_pk_add_f32 v[68:69], v[68:69], v[240:241]
	v_lshlrev_b32_e32 v240, 16, v153
	v_and_b32_e32 v241, 0xffff0000, v153
	v_pk_add_f32 v[70:71], v[70:71], v[240:241]
	v_lshlrev_b32_e32 v240, 16, v154
	v_and_b32_e32 v241, 0xffff0000, v154
	v_pk_add_f32 v[64:65], v[64:65], v[240:241]
	v_lshlrev_b32_e32 v240, 16, v155
	v_and_b32_e32 v241, 0xffff0000, v155
	v_pk_add_f32 v[66:67], v[66:67], v[240:241]
	s_add_u32 s42, s14, 0x18000
	s_addc_u32 s43, s15, 0
	global_load_dwordx4 v[152:155], v235, s[42:43]
	s_waitcnt vmcnt(16)
	v_lshlrev_b32_e32 v240, 16, v156
	v_and_b32_e32 v241, 0xffff0000, v156
	v_pk_add_f32 v[60:61], v[60:61], v[240:241]
	v_lshlrev_b32_e32 v240, 16, v157
	v_and_b32_e32 v241, 0xffff0000, v157
	v_pk_add_f32 v[62:63], v[62:63], v[240:241]
	v_lshlrev_b32_e32 v240, 16, v158
	v_and_b32_e32 v241, 0xffff0000, v158
	v_pk_add_f32 v[56:57], v[56:57], v[240:241]
	v_lshlrev_b32_e32 v240, 16, v159
	v_and_b32_e32 v241, 0xffff0000, v159
	v_pk_add_f32 v[58:59], v[58:59], v[240:241]
	s_add_u32 s98, s10, 0x10000
	s_addc_u32 s99, s11, 0
	global_load_dwordx4 v[156:159], v203, s[98:99]
	s_waitcnt vmcnt(16)
	v_lshlrev_b32_e32 v240, 16, v160
	v_and_b32_e32 v241, 0xffff0000, v160
	v_pk_add_f32 v[28:29], v[28:29], v[240:241]
	v_lshlrev_b32_e32 v240, 16, v161
	v_and_b32_e32 v241, 0xffff0000, v161
	v_pk_add_f32 v[30:31], v[30:31], v[240:241]
	v_lshlrev_b32_e32 v240, 16, v162
	v_and_b32_e32 v241, 0xffff0000, v162
	v_pk_add_f32 v[24:25], v[24:25], v[240:241]
	v_lshlrev_b32_e32 v240, 16, v163
	v_and_b32_e32 v241, 0xffff0000, v163
	v_pk_add_f32 v[26:27], v[26:27], v[240:241]
	s_add_u32 s42, s14, 0x18000
	s_addc_u32 s43, s15, 0
	global_load_dwordx4 v[160:163], v235, s[42:43] offset:16
	s_waitcnt vmcnt(16)
	v_lshlrev_b32_e32 v240, 16, v164
	v_and_b32_e32 v241, 0xffff0000, v164
	v_pk_add_f32 v[52:53], v[52:53], v[240:241]
	v_lshlrev_b32_e32 v240, 16, v165
	v_and_b32_e32 v241, 0xffff0000, v165
	v_pk_add_f32 v[54:55], v[54:55], v[240:241]
	v_lshlrev_b32_e32 v240, 16, v166
	v_and_b32_e32 v241, 0xffff0000, v166
	v_pk_add_f32 v[48:49], v[48:49], v[240:241]
	v_lshlrev_b32_e32 v240, 16, v167
	v_and_b32_e32 v241, 0xffff0000, v167
	v_pk_add_f32 v[50:51], v[50:51], v[240:241]
	s_add_u32 s98, s10, 0x10000
	s_addc_u32 s99, s11, 0
	global_load_dwordx4 v[164:167], v203, s[98:99] offset:16
	s_waitcnt vmcnt(16)
	v_lshlrev_b32_e32 v240, 16, v168
	v_and_b32_e32 v241, 0xffff0000, v168
	v_pk_add_f32 v[20:21], v[20:21], v[240:241]
	v_lshlrev_b32_e32 v240, 16, v169
	v_and_b32_e32 v241, 0xffff0000, v169
	v_pk_add_f32 v[22:23], v[22:23], v[240:241]
	v_lshlrev_b32_e32 v240, 16, v170
	v_and_b32_e32 v241, 0xffff0000, v170
	v_pk_add_f32 v[16:17], v[16:17], v[240:241]
	v_lshlrev_b32_e32 v240, 16, v171
	v_and_b32_e32 v241, 0xffff0000, v171
	v_pk_add_f32 v[18:19], v[18:19], v[240:241]
	s_add_u32 s42, s14, 0x18200
	s_addc_u32 s43, s15, 0
	global_load_dwordx4 v[168:171], v235, s[42:43]
	s_waitcnt vmcnt(16)
	v_lshlrev_b32_e32 v240, 16, v172
	v_and_b32_e32 v241, 0xffff0000, v172
	v_pk_add_f32 v[44:45], v[44:45], v[240:241]
	v_lshlrev_b32_e32 v240, 16, v173
	v_and_b32_e32 v241, 0xffff0000, v173
	v_pk_add_f32 v[46:47], v[46:47], v[240:241]
	v_lshlrev_b32_e32 v240, 16, v174
	v_and_b32_e32 v241, 0xffff0000, v174
	v_pk_add_f32 v[40:41], v[40:41], v[240:241]
	v_lshlrev_b32_e32 v240, 16, v175
	v_and_b32_e32 v241, 0xffff0000, v175
	v_pk_add_f32 v[42:43], v[42:43], v[240:241]
	s_add_u32 s98, s10, 0x10200
	s_addc_u32 s99, s11, 0
	global_load_dwordx4 v[172:175], v203, s[98:99]
	s_waitcnt vmcnt(16)
	v_lshlrev_b32_e32 v240, 16, v176
	v_and_b32_e32 v241, 0xffff0000, v176
	v_pk_add_f32 v[12:13], v[12:13], v[240:241]
	v_lshlrev_b32_e32 v240, 16, v177
	v_and_b32_e32 v241, 0xffff0000, v177
	v_pk_add_f32 v[14:15], v[14:15], v[240:241]
	v_lshlrev_b32_e32 v240, 16, v178
	v_and_b32_e32 v241, 0xffff0000, v178
	v_pk_add_f32 v[8:9], v[8:9], v[240:241]
	v_lshlrev_b32_e32 v240, 16, v179
	v_and_b32_e32 v241, 0xffff0000, v179
	v_pk_add_f32 v[10:11], v[10:11], v[240:241]
	s_add_u32 s42, s14, 0x18200
	s_addc_u32 s43, s15, 0
	global_load_dwordx4 v[176:179], v235, s[42:43] offset:16
	s_waitcnt vmcnt(16)
	v_lshlrev_b32_e32 v240, 16, v180
	v_and_b32_e32 v241, 0xffff0000, v180
	v_pk_add_f32 v[36:37], v[36:37], v[240:241]
	v_lshlrev_b32_e32 v240, 16, v181
	v_and_b32_e32 v241, 0xffff0000, v181
	v_pk_add_f32 v[38:39], v[38:39], v[240:241]
	v_lshlrev_b32_e32 v240, 16, v182
	v_and_b32_e32 v241, 0xffff0000, v182
	v_pk_add_f32 v[32:33], v[32:33], v[240:241]
	v_lshlrev_b32_e32 v240, 16, v183
	v_and_b32_e32 v241, 0xffff0000, v183
	v_pk_add_f32 v[34:35], v[34:35], v[240:241]
	s_add_u32 s98, s10, 0x10200
	s_addc_u32 s99, s11, 0
	global_load_dwordx4 v[180:183], v203, s[98:99] offset:16
	s_waitcnt vmcnt(16)
	v_lshlrev_b32_e32 v240, 16, v206
	v_and_b32_e32 v241, 0xffff0000, v206
	v_pk_add_f32 v[4:5], v[4:5], v[240:241]
	v_lshlrev_b32_e32 v240, 16, v207
	v_and_b32_e32 v241, 0xffff0000, v207
	v_pk_add_f32 v[6:7], v[6:7], v[240:241]
	v_lshlrev_b32_e32 v240, 16, v208
	v_and_b32_e32 v241, 0xffff0000, v208
	v_pk_add_f32 v[0:1], v[0:1], v[240:241]
	v_lshlrev_b32_e32 v240, 16, v209
	v_and_b32_e32 v241, 0xffff0000, v209
	v_pk_add_f32 v[2:3], v[2:3], v[240:241]
	s_add_u32 s42, s14, 0x30000
	s_addc_u32 s43, s15, 0
	global_load_dwordx4 v[206:209], v235, s[42:43]
	s_waitcnt vmcnt(15)
	v_pk_fma_f32 v[124:125], v[210:211], v[124:125], v[236:237]
	v_pk_fma_f32 v[126:127], v[212:213], v[126:127], v[238:239]
	s_add_u32 s98, s10, 0x0
	s_addc_u32 s99, s11, 0
	global_store_dwordx4 v203, v[124:127], s[98:99]
	s_add_u32 s42, s10, 0x20000
	s_addc_u32 s43, s11, 0
	global_load_dwordx4 v[210:213], v203, s[42:43]
	s_add_u32 s98, s14, 0x30000
	s_addc_u32 s99, s15, 0
	global_load_dwordx4 v[236:239], v235, s[98:99] offset:16
	s_waitcnt vmcnt(16)
	v_pk_fma_f32 v[120:121], v[128:129], v[120:121], v[132:133]
	v_pk_fma_f32 v[122:123], v[130:131], v[122:123], v[134:135]
	s_add_u32 s42, s10, 0x0
	s_addc_u32 s43, s11, 0
	global_store_dwordx4 v203, v[120:123], s[42:43] offset:16
	s_add_u32 s98, s10, 0x20000
	s_addc_u32 s99, s11, 0
	global_load_dwordx4 v[128:131], v203, s[98:99] offset:16
	s_add_u32 s42, s14, 0x30200
	s_addc_u32 s43, s15, 0
	global_load_dwordx4 v[132:135], v235, s[42:43]
	s_waitcnt vmcnt(17)
	v_pk_fma_f32 v[92:93], v[136:137], v[92:93], v[140:141]
	v_pk_fma_f32 v[94:95], v[138:139], v[94:95], v[142:143]
	s_add_u32 s98, s10, 0x200
	s_addc_u32 s99, s11, 0
	global_store_dwordx4 v203, v[92:95], s[98:99]
	s_add_u32 s42, s10, 0x20200
	s_addc_u32 s43, s11, 0
	global_load_dwordx4 v[136:139], v203, s[42:43]
	s_add_u32 s98, s14, 0x30200
	s_addc_u32 s99, s15, 0
	global_load_dwordx4 v[140:143], v235, s[98:99] offset:16
	s_waitcnt vmcnt(18)
	v_pk_fma_f32 v[88:89], v[144:145], v[88:89], v[148:149]
	v_pk_fma_f32 v[90:91], v[146:147], v[90:91], v[150:151]
	s_add_u32 s42, s10, 0x200
	s_addc_u32 s43, s11, 0
	global_store_dwordx4 v203, v[88:91], s[42:43] offset:16
	s_add_u32 s98, s10, 0x20200
	s_addc_u32 s99, s11, 0
	global_load_dwordx4 v[144:147], v203, s[98:99] offset:16
	s_add_u32 s42, s14, 0x48000
	s_addc_u32 s43, s15, 0
	global_load_dwordx4 v[148:151], v235, s[42:43]
	s_waitcnt vmcnt(19)
	v_pk_fma_f32 v[116:117], v[152:153], v[116:117], v[156:157]
	v_pk_fma_f32 v[118:119], v[154:155], v[118:119], v[158:159]
	s_add_u32 s98, s10, 0x10000
	s_addc_u32 s99, s11, 0
	global_store_dwordx4 v203, v[116:119], s[98:99]
	s_add_u32 s42, s10, 0x30000
	s_addc_u32 s43, s11, 0
	global_load_dwordx4 v[152:155], v203, s[42:43]
	s_add_u32 s98, s14, 0x48000
	s_addc_u32 s99, s15, 0
	global_load_dwordx4 v[156:159], v235, s[98:99] offset:16
	s_waitcnt vmcnt(20)
	v_pk_fma_f32 v[112:113], v[160:161], v[112:113], v[164:165]
	v_pk_fma_f32 v[114:115], v[162:163], v[114:115], v[166:167]
	s_add_u32 s42, s10, 0x10000
	s_addc_u32 s43, s11, 0
	global_store_dwordx4 v203, v[112:115], s[42:43] offset:16
	s_add_u32 s98, s10, 0x30000
	s_addc_u32 s99, s11, 0
	global_load_dwordx4 v[160:163], v203, s[98:99] offset:16
	s_add_u32 s42, s14, 0x48200
	s_addc_u32 s43, s15, 0
	global_load_dwordx4 v[164:167], v235, s[42:43]
	s_waitcnt vmcnt(21)
	v_pk_fma_f32 v[84:85], v[168:169], v[84:85], v[172:173]
	v_pk_fma_f32 v[86:87], v[170:171], v[86:87], v[174:175]
	s_add_u32 s98, s10, 0x10200
	s_addc_u32 s99, s11, 0
	global_store_dwordx4 v203, v[84:87], s[98:99]
	s_add_u32 s42, s10, 0x30200
	s_addc_u32 s43, s11, 0
	global_load_dwordx4 v[168:171], v203, s[42:43]
	s_add_u32 s98, s14, 0x48200
	s_addc_u32 s99, s15, 0
	global_load_dwordx4 v[172:175], v235, s[98:99] offset:16
	s_waitcnt vmcnt(22)
	v_pk_fma_f32 v[80:81], v[176:177], v[80:81], v[180:181]
	v_pk_fma_f32 v[82:83], v[178:179], v[82:83], v[182:183]
	s_add_u32 s42, s10, 0x10200
	s_addc_u32 s43, s11, 0
	global_store_dwordx4 v203, v[80:83], s[42:43] offset:16
	s_add_u32 s98, s10, 0x30200
	s_addc_u32 s99, s11, 0
	global_load_dwordx4 v[176:179], v203, s[98:99] offset:16
	s_add_u32 s42, s14, 0xc0000
	s_addc_u32 s43, s15, 0
	global_load_dwordx4 v[180:183], v235, s[42:43]
	s_waitcnt vmcnt(22)
	v_pk_fma_f32 v[108:109], v[206:207], v[108:109], v[210:211]
	v_pk_fma_f32 v[110:111], v[208:209], v[110:111], v[212:213]
	s_add_u32 s98, s10, 0x20000
	s_addc_u32 s99, s11, 0
	global_store_dwordx4 v203, v[108:111], s[98:99]
	s_add_u32 s42, s10, 0x80000
	s_addc_u32 s43, s11, 0
	global_load_dwordx4 v[206:209], v203, s[42:43]
	s_add_u32 s98, s14, 0xc0000
	s_addc_u32 s99, s15, 0
	global_load_dwordx4 v[210:213], v235, s[98:99] offset:16
	s_waitcnt vmcnt(22)
	v_pk_fma_f32 v[104:105], v[236:237], v[104:105], v[128:129]
	v_pk_fma_f32 v[106:107], v[238:239], v[106:107], v[130:131]
	s_add_u32 s42, s10, 0x20000
	s_addc_u32 s43, s11, 0
	global_store_dwordx4 v203, v[104:107], s[42:43] offset:16
	s_add_u32 s98, s10, 0x80000
	s_addc_u32 s99, s11, 0
	global_load_dwordx4 v[236:239], v203, s[98:99] offset:16
	s_add_u32 s42, s14, 0xc0200
	s_addc_u32 s43, s15, 0
	global_load_dwordx4 v[128:131], v235, s[42:43]
	s_waitcnt vmcnt(22)
	v_pk_fma_f32 v[76:77], v[132:133], v[76:77], v[136:137]
	v_pk_fma_f32 v[78:79], v[134:135], v[78:79], v[138:139]
	s_add_u32 s98, s10, 0x20200
	s_addc_u32 s99, s11, 0
	global_store_dwordx4 v203, v[76:79], s[98:99]
	s_add_u32 s42, s10, 0x80200
	s_addc_u32 s43, s11, 0
	global_load_dwordx4 v[132:135], v203, s[42:43]
	s_add_u32 s98, s14, 0xc0200
	s_addc_u32 s99, s15, 0
	global_load_dwordx4 v[136:139], v235, s[98:99] offset:16
	s_waitcnt vmcnt(22)
	v_pk_fma_f32 v[72:73], v[140:141], v[72:73], v[144:145]
	v_pk_fma_f32 v[74:75], v[142:143], v[74:75], v[146:147]
	s_add_u32 s42, s10, 0x20200
	s_addc_u32 s43, s11, 0
	global_store_dwordx4 v203, v[72:75], s[42:43] offset:16
	s_add_u32 s98, s10, 0x80200
	s_addc_u32 s99, s11, 0
	global_load_dwordx4 v[140:143], v203, s[98:99] offset:16
	s_add_u32 s42, s14, 0xd8000
	s_addc_u32 s43, s15, 0
	global_load_dwordx4 v[144:147], v235, s[42:43]
	s_waitcnt vmcnt(22)
	v_pk_fma_f32 v[100:101], v[148:149], v[100:101], v[152:153]
	v_pk_fma_f32 v[102:103], v[150:151], v[102:103], v[154:155]
	s_add_u32 s98, s10, 0x30000
	s_addc_u32 s99, s11, 0
	global_store_dwordx4 v203, v[100:103], s[98:99]
	s_add_u32 s42, s10, 0x90000
	s_addc_u32 s43, s11, 0
	global_load_dwordx4 v[148:151], v203, s[42:43]
	s_add_u32 s98, s14, 0xd8000
	s_addc_u32 s99, s15, 0
	global_load_dwordx4 v[152:155], v235, s[98:99] offset:16
	s_waitcnt vmcnt(22)
	v_pk_fma_f32 v[96:97], v[156:157], v[96:97], v[160:161]
	v_pk_fma_f32 v[98:99], v[158:159], v[98:99], v[162:163]
	s_add_u32 s42, s10, 0x30000
	s_addc_u32 s43, s11, 0
	global_store_dwordx4 v203, v[96:99], s[42:43] offset:16
	s_add_u32 s98, s10, 0x90000
	s_addc_u32 s99, s11, 0
	global_load_dwordx4 v[156:159], v203, s[98:99] offset:16
	s_add_u32 s42, s14, 0xd8200
	s_addc_u32 s43, s15, 0
	global_load_dwordx4 v[160:163], v235, s[42:43]
	s_waitcnt vmcnt(22)
	v_pk_fma_f32 v[68:69], v[164:165], v[68:69], v[168:169]
	v_pk_fma_f32 v[70:71], v[166:167], v[70:71], v[170:171]
	s_add_u32 s98, s10, 0x30200
	s_addc_u32 s99, s11, 0
	global_store_dwordx4 v203, v[68:71], s[98:99]
	s_add_u32 s42, s10, 0x90200
	s_addc_u32 s43, s11, 0
	global_load_dwordx4 v[164:167], v203, s[42:43]
	s_add_u32 s98, s14, 0xd8200
	s_addc_u32 s99, s15, 0
	global_load_dwordx4 v[168:171], v235, s[98:99] offset:16
	s_waitcnt vmcnt(22)
	v_pk_fma_f32 v[64:65], v[172:173], v[64:65], v[176:177]
	v_pk_fma_f32 v[66:67], v[174:175], v[66:67], v[178:179]
	s_add_u32 s42, s10, 0x30200
	s_addc_u32 s43, s11, 0
	global_store_dwordx4 v203, v[64:67], s[42:43] offset:16
	s_add_u32 s98, s10, 0x90200
	s_addc_u32 s99, s11, 0
	global_load_dwordx4 v[172:175], v203, s[98:99] offset:16
	s_add_u32 s42, s14, 0xf0000
	s_addc_u32 s43, s15, 0
	global_load_dwordx4 v[176:179], v235, s[42:43]
	s_waitcnt vmcnt(22)
	v_pk_fma_f32 v[60:61], v[180:181], v[60:61], v[206:207]
	v_pk_fma_f32 v[62:63], v[182:183], v[62:63], v[208:209]
	s_add_u32 s98, s10, 0x80000
	s_addc_u32 s99, s11, 0
	global_store_dwordx4 v203, v[60:63], s[98:99]
	s_add_u32 s42, s10, 0xa0000
	s_addc_u32 s43, s11, 0
	global_load_dwordx4 v[180:183], v203, s[42:43]
	s_add_u32 s98, s14, 0xf0000
	s_addc_u32 s99, s15, 0
	global_load_dwordx4 v[206:209], v235, s[98:99] offset:16
	s_waitcnt vmcnt(22)
	v_pk_fma_f32 v[56:57], v[210:211], v[56:57], v[236:237]
	v_pk_fma_f32 v[58:59], v[212:213], v[58:59], v[238:239]
	s_add_u32 s42, s10, 0x80000
	s_addc_u32 s43, s11, 0
	global_store_dwordx4 v203, v[56:59], s[42:43] offset:16
	s_add_u32 s98, s10, 0xa0000
	s_addc_u32 s99, s11, 0
	global_load_dwordx4 v[210:213], v203, s[98:99] offset:16
	s_add_u32 s42, s14, 0xf0200
	s_addc_u32 s43, s15, 0
	global_load_dwordx4 v[236:239], v235, s[42:43]
	s_waitcnt vmcnt(22)
	v_pk_fma_f32 v[28:29], v[128:129], v[28:29], v[132:133]
	v_pk_fma_f32 v[30:31], v[130:131], v[30:31], v[134:135]
	s_add_u32 s98, s10, 0x80200
	s_addc_u32 s99, s11, 0
	global_store_dwordx4 v203, v[28:31], s[98:99]
	s_add_u32 s42, s10, 0xa0200
	s_addc_u32 s43, s11, 0
	global_load_dwordx4 v[128:131], v203, s[42:43]
	s_add_u32 s98, s14, 0xf0200
	s_addc_u32 s99, s15, 0
	global_load_dwordx4 v[132:135], v235, s[98:99] offset:16
	s_waitcnt vmcnt(22)
	v_pk_fma_f32 v[24:25], v[136:137], v[24:25], v[140:141]
	v_pk_fma_f32 v[26:27], v[138:139], v[26:27], v[142:143]
	s_add_u32 s42, s10, 0x80200
	s_addc_u32 s43, s11, 0
	global_store_dwordx4 v203, v[24:27], s[42:43] offset:16
	s_add_u32 s98, s10, 0xa0200
	s_addc_u32 s99, s11, 0
	global_load_dwordx4 v[136:139], v203, s[98:99] offset:16
	s_add_u32 s42, s14, 0x108000
	s_addc_u32 s43, s15, 0
	global_load_dwordx4 v[140:143], v235, s[42:43]
	s_waitcnt vmcnt(22)
	v_pk_fma_f32 v[52:53], v[144:145], v[52:53], v[148:149]
	v_pk_fma_f32 v[54:55], v[146:147], v[54:55], v[150:151]
	s_add_u32 s98, s10, 0x90000
	s_addc_u32 s99, s11, 0
	global_store_dwordx4 v203, v[52:55], s[98:99]
	s_add_u32 s42, s10, 0xb0000
	s_addc_u32 s43, s11, 0
	global_load_dwordx4 v[144:147], v203, s[42:43]
	s_add_u32 s98, s14, 0x108000
	s_addc_u32 s99, s15, 0
	global_load_dwordx4 v[148:151], v235, s[98:99] offset:16
	s_waitcnt vmcnt(22)
	v_pk_fma_f32 v[48:49], v[152:153], v[48:49], v[156:157]
	v_pk_fma_f32 v[50:51], v[154:155], v[50:51], v[158:159]
	s_add_u32 s42, s10, 0x90000
	s_addc_u32 s43, s11, 0
	global_store_dwordx4 v203, v[48:51], s[42:43] offset:16
	s_add_u32 s98, s10, 0xb0000
	s_addc_u32 s99, s11, 0
	global_load_dwordx4 v[152:155], v203, s[98:99] offset:16
	s_add_u32 s42, s14, 0x108200
	s_addc_u32 s43, s15, 0
	global_load_dwordx4 v[156:159], v235, s[42:43]
	s_waitcnt vmcnt(22)
	v_pk_fma_f32 v[20:21], v[160:161], v[20:21], v[164:165]
	v_pk_fma_f32 v[22:23], v[162:163], v[22:23], v[166:167]
	s_add_u32 s98, s10, 0x90200
	s_addc_u32 s99, s11, 0
	global_store_dwordx4 v203, v[20:23], s[98:99]
	s_add_u32 s42, s10, 0xb0200
	s_addc_u32 s43, s11, 0
	global_load_dwordx4 v[160:163], v203, s[42:43]
	s_add_u32 s98, s14, 0x108200
	s_addc_u32 s99, s15, 0
	global_load_dwordx4 v[164:167], v235, s[98:99] offset:16
	s_waitcnt vmcnt(22)
	v_pk_fma_f32 v[16:17], v[168:169], v[16:17], v[172:173]
	v_pk_fma_f32 v[18:19], v[170:171], v[18:19], v[174:175]
	s_add_u32 s42, s10, 0x90200
	s_addc_u32 s43, s11, 0
	global_store_dwordx4 v203, v[16:19], s[42:43] offset:16
	s_add_u32 s98, s10, 0xb0200
	s_addc_u32 s99, s11, 0
	global_load_dwordx4 v[168:171], v203, s[98:99] offset:16
	s_waitcnt vmcnt(21)
	v_pk_fma_f32 v[44:45], v[176:177], v[44:45], v[180:181]
	v_pk_fma_f32 v[46:47], v[178:179], v[46:47], v[182:183]
	s_add_u32 s42, s10, 0xa0000
	s_addc_u32 s43, s11, 0
	global_store_dwordx4 v203, v[44:47], s[42:43]
	s_waitcnt vmcnt(19)
	v_pk_fma_f32 v[40:41], v[206:207], v[40:41], v[210:211]
	v_pk_fma_f32 v[42:43], v[208:209], v[42:43], v[212:213]
	s_add_u32 s98, s10, 0xa0000
	s_addc_u32 s99, s11, 0
	global_store_dwordx4 v203, v[40:43], s[98:99] offset:16
	s_waitcnt vmcnt(17)
	v_pk_fma_f32 v[12:13], v[236:237], v[12:13], v[128:129]
	v_pk_fma_f32 v[14:15], v[238:239], v[14:15], v[130:131]
	s_add_u32 s42, s10, 0xa0200
	s_addc_u32 s43, s11, 0
	global_store_dwordx4 v203, v[12:15], s[42:43]
	s_waitcnt vmcnt(15)
	v_pk_fma_f32 v[8:9], v[132:133], v[8:9], v[136:137]
	v_pk_fma_f32 v[10:11], v[134:135], v[10:11], v[138:139]
	s_add_u32 s98, s10, 0xa0200
	s_addc_u32 s99, s11, 0
	global_store_dwordx4 v203, v[8:11], s[98:99] offset:16
	s_waitcnt vmcnt(13)
	v_pk_fma_f32 v[36:37], v[140:141], v[36:37], v[144:145]
	v_pk_fma_f32 v[38:39], v[142:143], v[38:39], v[146:147]
	s_add_u32 s42, s10, 0xb0000
	s_addc_u32 s43, s11, 0
	global_store_dwordx4 v203, v[36:39], s[42:43]
	s_waitcnt vmcnt(11)
	v_pk_fma_f32 v[32:33], v[148:149], v[32:33], v[152:153]
	v_pk_fma_f32 v[34:35], v[150:151], v[34:35], v[154:155]
	s_add_u32 s98, s10, 0xb0000
	s_addc_u32 s99, s11, 0
	global_store_dwordx4 v203, v[32:35], s[98:99] offset:16
	s_waitcnt vmcnt(9)
	v_pk_fma_f32 v[4:5], v[156:157], v[4:5], v[160:161]
	v_pk_fma_f32 v[6:7], v[158:159], v[6:7], v[162:163]
	s_add_u32 s42, s10, 0xb0200
	s_addc_u32 s43, s11, 0
	global_store_dwordx4 v203, v[4:7], s[42:43]
	s_waitcnt vmcnt(7)
	v_pk_fma_f32 v[0:1], v[164:165], v[0:1], v[168:169]
	v_pk_fma_f32 v[2:3], v[166:167], v[2:3], v[170:171]
	s_add_u32 s98, s10, 0xb0200
	s_addc_u32 s99, s11, 0
	global_store_dwordx4 v203, v[0:3], s[98:99] offset:16
	s_branch .Lfs_predone
.Lfs_np1:
	s_add_u32 s42, s62, 0x0
	s_addc_u32 s43, s63, 0
	global_load_dwordx4 v[128:131], v205, s[42:43] sc0 sc1
	s_add_u32 s98, s62, 0x1000
	s_addc_u32 s99, s63, 0
	global_load_dwordx4 v[132:135], v205, s[98:99] sc0 sc1
	s_add_u32 s42, s62, 0x400
	s_addc_u32 s43, s63, 0
	global_load_dwordx4 v[136:139], v205, s[42:43] sc0 sc1
	s_add_u32 s98, s62, 0x1400
	s_addc_u32 s99, s63, 0
	global_load_dwordx4 v[140:143], v205, s[98:99] sc0 sc1
	s_add_u32 s42, s62, 0x800
	s_addc_u32 s43, s63, 0
	global_load_dwordx4 v[144:147], v205, s[42:43] sc0 sc1
	s_add_u32 s98, s62, 0x1800
	s_addc_u32 s99, s63, 0
	global_load_dwordx4 v[148:151], v205, s[98:99] sc0 sc1
	s_add_u32 s42, s62, 0xc00
	s_addc_u32 s43, s63, 0
	global_load_dwordx4 v[152:155], v205, s[42:43] sc0 sc1
	s_add_u32 s98, s62, 0x1c00
	s_addc_u32 s99, s63, 0
	global_load_dwordx4 v[156:159], v205, s[98:99] sc0 sc1
	s_add_u32 s42, s62, 0x2000
	s_addc_u32 s43, s63, 0
	global_load_dwordx4 v[160:163], v205, s[42:43] sc0 sc1
	s_add_u32 s98, s62, 0x3000
	s_addc_u32 s99, s63, 0
	global_load_dwordx4 v[164:167], v205, s[98:99] sc0 sc1
	s_add_u32 s42, s62, 0x2400
	s_addc_u32 s43, s63, 0
	global_load_dwordx4 v[168:171], v205, s[42:43] sc0 sc1
	s_add_u32 s98, s62, 0x3400
	s_addc_u32 s99, s63, 0
	global_load_dwordx4 v[172:175], v205, s[98:99] sc0 sc1
	s_add_u32 s42, s62, 0x2800
	s_addc_u32 s43, s63, 0
	global_load_dwordx4 v[176:179], v205, s[42:43] sc0 sc1
	s_add_u32 s98, s62, 0x3800
	s_addc_u32 s99, s63, 0
	global_load_dwordx4 v[180:183], v205, s[98:99] sc0 sc1
	s_add_u32 s42, s62, 0x2c00
	s_addc_u32 s43, s63, 0
	global_load_dwordx4 v[206:209], v205, s[42:43] sc0 sc1
	s_add_u32 s98, s62, 0x3c00
	s_addc_u32 s99, s63, 0
	global_load_dwordx4 v[210:213], v205, s[98:99] sc0 sc1
	s_add_u32 s42, s14, 0x0
	s_addc_u32 s43, s15, 0
	global_load_dwordx4 v[236:239], v235, s[42:43]
	s_waitcnt vmcnt(16)
	v_lshlrev_b32_e32 v240, 16, v128
	v_and_b32_e32 v241, 0xffff0000, v128
	v_pk_add_f32 v[124:125], v[124:125], v[240:241]
	v_lshlrev_b32_e32 v240, 16, v129
	v_and_b32_e32 v241, 0xffff0000, v129
	v_pk_add_f32 v[126:127], v[126:127], v[240:241]
	v_lshlrev_b32_e32 v240, 16, v130
	v_and_b32_e32 v241, 0xffff0000, v130
	v_pk_add_f32 v[120:121], v[120:121], v[240:241]
	v_lshlrev_b32_e32 v240, 16, v131
	v_and_b32_e32 v241, 0xffff0000, v131
	v_pk_add_f32 v[122:123], v[122:123], v[240:241]
	s_add_u32 s98, s10, 0x0
	s_addc_u32 s99, s11, 0
	global_load_dwordx4 v[128:131], v203, s[98:99]
	s_waitcnt vmcnt(16)
	v_lshlrev_b32_e32 v240, 16, v132
	v_and_b32_e32 v241, 0xffff0000, v132
	v_pk_add_f32 v[92:93], v[92:93], v[240:241]
	v_lshlrev_b32_e32 v240, 16, v133
	v_and_b32_e32 v241, 0xffff0000, v133
	v_pk_add_f32 v[94:95], v[94:95], v[240:241]
	v_lshlrev_b32_e32 v240, 16, v134
	v_and_b32_e32 v241, 0xffff0000, v134
	v_pk_add_f32 v[88:89], v[88:89], v[240:241]
	v_lshlrev_b32_e32 v240, 16, v135
	v_and_b32_e32 v241, 0xffff0000, v135
	v_pk_add_f32 v[90:91], v[90:91], v[240:241]
	s_add_u32 s42, s14, 0x0
	s_addc_u32 s43, s15, 0
	global_load_dwordx4 v[132:135], v235, s[42:43] offset:16
	s_waitcnt vmcnt(16)
	v_lshlrev_b32_e32 v240, 16, v136
	v_and_b32_e32 v241, 0xffff0000, v136
	v_pk_add_f32 v[116:117], v[116:117], v[240:241]
	v_lshlrev_b32_e32 v240, 16, v137
	v_and_b32_e32 v241, 0xffff0000, v137
	v_pk_add_f32 v[118:119], v[118:119], v[240:241]
	v_lshlrev_b32_e32 v240, 16, v138
	v_and_b32_e32 v241, 0xffff0000, v138
	v_pk_add_f32 v[112:113], v[112:113], v[240:241]
	v_lshlrev_b32_e32 v240, 16, v139
	v_and_b32_e32 v241, 0xffff0000, v139
	v_pk_add_f32 v[114:115], v[114:115], v[240:241]
	s_add_u32 s98, s10, 0x0
	s_addc_u32 s99, s11, 0
	global_load_dwordx4 v[136:139], v203, s[98:99] offset:16
	s_waitcnt vmcnt(16)
	v_lshlrev_b32_e32 v240, 16, v140
	v_and_b32_e32 v241, 0xffff0000, v140
	v_pk_add_f32 v[84:85], v[84:85], v[240:241]
	v_lshlrev_b32_e32 v240, 16, v141
	v_and_b32_e32 v241, 0xffff0000, v141
	v_pk_add_f32 v[86:87], v[86:87], v[240:241]
	v_lshlrev_b32_e32 v240, 16, v142
	v_and_b32_e32 v241, 0xffff0000, v142
	v_pk_add_f32 v[80:81], v[80:81], v[240:241]
	v_lshlrev_b32_e32 v240, 16, v143
	v_and_b32_e32 v241, 0xffff0000, v143
	v_pk_add_f32 v[82:83], v[82:83], v[240:241]
	s_add_u32 s42, s14, 0x200
	s_addc_u32 s43, s15, 0
	global_load_dwordx4 v[140:143], v235, s[42:43]
	s_waitcnt vmcnt(16)
	v_lshlrev_b32_e32 v240, 16, v144
	v_and_b32_e32 v241, 0xffff0000, v144
	v_pk_add_f32 v[108:109], v[108:109], v[240:241]
	v_lshlrev_b32_e32 v240, 16, v145
	v_and_b32_e32 v241, 0xffff0000, v145
	v_pk_add_f32 v[110:111], v[110:111], v[240:241]
	v_lshlrev_b32_e32 v240, 16, v146
	v_and_b32_e32 v241, 0xffff0000, v146
	v_pk_add_f32 v[104:105], v[104:105], v[240:241]
	v_lshlrev_b32_e32 v240, 16, v147
	v_and_b32_e32 v241, 0xffff0000, v147
	v_pk_add_f32 v[106:107], v[106:107], v[240:241]
	s_add_u32 s98, s10, 0x200
	s_addc_u32 s99, s11, 0
	global_load_dwordx4 v[144:147], v203, s[98:99]
	s_waitcnt vmcnt(16)
	v_lshlrev_b32_e32 v240, 16, v148
	v_and_b32_e32 v241, 0xffff0000, v148
	v_pk_add_f32 v[76:77], v[76:77], v[240:241]
	v_lshlrev_b32_e32 v240, 16, v149
	v_and_b32_e32 v241, 0xffff0000, v149
	v_pk_add_f32 v[78:79], v[78:79], v[240:241]
	v_lshlrev_b32_e32 v240, 16, v150
	v_and_b32_e32 v241, 0xffff0000, v150
	v_pk_add_f32 v[72:73], v[72:73], v[240:241]
	v_lshlrev_b32_e32 v240, 16, v151
	v_and_b32_e32 v241, 0xffff0000, v151
	v_pk_add_f32 v[74:75], v[74:75], v[240:241]
	s_add_u32 s42, s14, 0x200
	s_addc_u32 s43, s15, 0
	global_load_dwordx4 v[148:151], v235, s[42:43] offset:16
	s_waitcnt vmcnt(16)
	v_lshlrev_b32_e32 v240, 16, v152
	v_and_b32_e32 v241, 0xffff0000, v152
	v_pk_add_f32 v[100:101], v[100:101], v[240:241]
	v_lshlrev_b32_e32 v240, 16, v153
	v_and_b32_e32 v241, 0xffff0000, v153
	v_pk_add_f32 v[102:103], v[102:103], v[240:241]
	v_lshlrev_b32_e32 v240, 16, v154
	v_and_b32_e32 v241, 0xffff0000, v154
	v_pk_add_f32 v[96:97], v[96:97], v[240:241]
	v_lshlrev_b32_e32 v240, 16, v155
	v_and_b32_e32 v241, 0xffff0000, v155
	v_pk_add_f32 v[98:99], v[98:99], v[240:241]
	s_add_u32 s98, s10, 0x200
	s_addc_u32 s99, s11, 0
	global_load_dwordx4 v[152:155], v203, s[98:99] offset:16
	s_waitcnt vmcnt(16)
	v_lshlrev_b32_e32 v240, 16, v156
	v_and_b32_e32 v241, 0xffff0000, v156
	v_pk_add_f32 v[68:69], v[68:69], v[240:241]
	v_lshlrev_b32_e32 v240, 16, v157
	v_and_b32_e32 v241, 0xffff0000, v157
	v_pk_add_f32 v[70:71], v[70:71], v[240:241]
	v_lshlrev_b32_e32 v240, 16, v158
	v_and_b32_e32 v241, 0xffff0000, v158
	v_pk_add_f32 v[64:65], v[64:65], v[240:241]
	v_lshlrev_b32_e32 v240, 16, v159
	v_and_b32_e32 v241, 0xffff0000, v159
	v_pk_add_f32 v[66:67], v[66:67], v[240:241]
	s_add_u32 s42, s14, 0x18000
	s_addc_u32 s43, s15, 0
	global_load_dwordx4 v[156:159], v235, s[42:43]
	s_waitcnt vmcnt(16)
	v_lshlrev_b32_e32 v240, 16, v160
	v_and_b32_e32 v241, 0xffff0000, v160
	v_pk_add_f32 v[60:61], v[60:61], v[240:241]
	v_lshlrev_b32_e32 v240, 16, v161
	v_and_b32_e32 v241, 0xffff0000, v161
	v_pk_add_f32 v[62:63], v[62:63], v[240:241]
	v_lshlrev_b32_e32 v240, 16, v162
	v_and_b32_e32 v241, 0xffff0000, v162
	v_pk_add_f32 v[56:57], v[56:57], v[240:241]
	v_lshlrev_b32_e32 v240, 16, v163
	v_and_b32_e32 v241, 0xffff0000, v163
	v_pk_add_f32 v[58:59], v[58:59], v[240:241]
	s_add_u32 s98, s10, 0x10000
	s_addc_u32 s99, s11, 0
	global_load_dwordx4 v[160:163], v203, s[98:99]
	s_waitcnt vmcnt(16)
	v_lshlrev_b32_e32 v240, 16, v164
	v_and_b32_e32 v241, 0xffff0000, v164
	v_pk_add_f32 v[28:29], v[28:29], v[240:241]
	v_lshlrev_b32_e32 v240, 16, v165
	v_and_b32_e32 v241, 0xffff0000, v165
	v_pk_add_f32 v[30:31], v[30:31], v[240:241]
	v_lshlrev_b32_e32 v240, 16, v166
	v_and_b32_e32 v241, 0xffff0000, v166
	v_pk_add_f32 v[24:25], v[24:25], v[240:241]
	v_lshlrev_b32_e32 v240, 16, v167
	v_and_b32_e32 v241, 0xffff0000, v167
	v_pk_add_f32 v[26:27], v[26:27], v[240:241]
	s_add_u32 s42, s14, 0x18000
	s_addc_u32 s43, s15, 0
	global_load_dwordx4 v[164:167], v235, s[42:43] offset:16
	s_waitcnt vmcnt(16)
	v_lshlrev_b32_e32 v240, 16, v168
	v_and_b32_e32 v241, 0xffff0000, v168
	v_pk_add_f32 v[52:53], v[52:53], v[240:241]
	v_lshlrev_b32_e32 v240, 16, v169
	v_and_b32_e32 v241, 0xffff0000, v169
	v_pk_add_f32 v[54:55], v[54:55], v[240:241]
	v_lshlrev_b32_e32 v240, 16, v170
	v_and_b32_e32 v241, 0xffff0000, v170
	v_pk_add_f32 v[48:49], v[48:49], v[240:241]
	v_lshlrev_b32_e32 v240, 16, v171
	v_and_b32_e32 v241, 0xffff0000, v171
	v_pk_add_f32 v[50:51], v[50:51], v[240:241]
	s_add_u32 s98, s10, 0x10000
	s_addc_u32 s99, s11, 0
	global_load_dwordx4 v[168:171], v203, s[98:99] offset:16
	s_waitcnt vmcnt(16)
	v_lshlrev_b32_e32 v240, 16, v172
	v_and_b32_e32 v241, 0xffff0000, v172
	v_pk_add_f32 v[20:21], v[20:21], v[240:241]
	v_lshlrev_b32_e32 v240, 16, v173
	v_and_b32_e32 v241, 0xffff0000, v173
	v_pk_add_f32 v[22:23], v[22:23], v[240:241]
	v_lshlrev_b32_e32 v240, 16, v174
	v_and_b32_e32 v241, 0xffff0000, v174
	v_pk_add_f32 v[16:17], v[16:17], v[240:241]
	v_lshlrev_b32_e32 v240, 16, v175
	v_and_b32_e32 v241, 0xffff0000, v175
	v_pk_add_f32 v[18:19], v[18:19], v[240:241]
	s_add_u32 s42, s14, 0x18200
	s_addc_u32 s43, s15, 0
	global_load_dwordx4 v[172:175], v235, s[42:43]
	s_waitcnt vmcnt(16)
	v_lshlrev_b32_e32 v240, 16, v176
	v_and_b32_e32 v241, 0xffff0000, v176
	v_pk_add_f32 v[44:45], v[44:45], v[240:241]
	v_lshlrev_b32_e32 v240, 16, v177
	v_and_b32_e32 v241, 0xffff0000, v177
	v_pk_add_f32 v[46:47], v[46:47], v[240:241]
	v_lshlrev_b32_e32 v240, 16, v178
	v_and_b32_e32 v241, 0xffff0000, v178
	v_pk_add_f32 v[40:41], v[40:41], v[240:241]
	v_lshlrev_b32_e32 v240, 16, v179
	v_and_b32_e32 v241, 0xffff0000, v179
	v_pk_add_f32 v[42:43], v[42:43], v[240:241]
	s_add_u32 s98, s10, 0x10200
	s_addc_u32 s99, s11, 0
	global_load_dwordx4 v[176:179], v203, s[98:99]
	s_waitcnt vmcnt(16)
	v_lshlrev_b32_e32 v240, 16, v180
	v_and_b32_e32 v241, 0xffff0000, v180
	v_pk_add_f32 v[12:13], v[12:13], v[240:241]
	v_lshlrev_b32_e32 v240, 16, v181
	v_and_b32_e32 v241, 0xffff0000, v181
	v_pk_add_f32 v[14:15], v[14:15], v[240:241]
	v_lshlrev_b32_e32 v240, 16, v182
	v_and_b32_e32 v241, 0xffff0000, v182
	v_pk_add_f32 v[8:9], v[8:9], v[240:241]
	v_lshlrev_b32_e32 v240, 16, v183
	v_and_b32_e32 v241, 0xffff0000, v183
	v_pk_add_f32 v[10:11], v[10:11], v[240:241]
	s_add_u32 s42, s14, 0x18200
	s_addc_u32 s43, s15, 0
	global_load_dwordx4 v[180:183], v235, s[42:43] offset:16
	s_waitcnt vmcnt(16)
	v_lshlrev_b32_e32 v240, 16, v206
	v_and_b32_e32 v241, 0xffff0000, v206
	v_pk_add_f32 v[36:37], v[36:37], v[240:241]
	v_lshlrev_b32_e32 v240, 16, v207
	v_and_b32_e32 v241, 0xffff0000, v207
	v_pk_add_f32 v[38:39], v[38:39], v[240:241]
	v_lshlrev_b32_e32 v240, 16, v208
	v_and_b32_e32 v241, 0xffff0000, v208
	v_pk_add_f32 v[32:33], v[32:33], v[240:241]
	v_lshlrev_b32_e32 v240, 16, v209
	v_and_b32_e32 v241, 0xffff0000, v209
	v_pk_add_f32 v[34:35], v[34:35], v[240:241]
	s_add_u32 s98, s10, 0x10200
	s_addc_u32 s99, s11, 0
	global_load_dwordx4 v[206:209], v203, s[98:99] offset:16
	s_waitcnt vmcnt(16)
	v_lshlrev_b32_e32 v240, 16, v210
	v_and_b32_e32 v241, 0xffff0000, v210
	v_pk_add_f32 v[4:5], v[4:5], v[240:241]
	v_lshlrev_b32_e32 v240, 16, v211
	v_and_b32_e32 v241, 0xffff0000, v211
	v_pk_add_f32 v[6:7], v[6:7], v[240:241]
	v_lshlrev_b32_e32 v240, 16, v212
	v_and_b32_e32 v241, 0xffff0000, v212
	v_pk_add_f32 v[0:1], v[0:1], v[240:241]
	v_lshlrev_b32_e32 v240, 16, v213
	v_and_b32_e32 v241, 0xffff0000, v213
	v_pk_add_f32 v[2:3], v[2:3], v[240:241]
	s_add_u32 s42, s14, 0x30000
	s_addc_u32 s43, s15, 0
	global_load_dwordx4 v[210:213], v235, s[42:43]
	s_waitcnt vmcnt(15)
	v_pk_fma_f32 v[124:125], v[236:237], v[124:125], v[128:129]
	v_pk_fma_f32 v[126:127], v[238:239], v[126:127], v[130:131]
	s_add_u32 s98, s10, 0x0
	s_addc_u32 s99, s11, 0
	global_store_dwordx4 v203, v[124:127], s[98:99]
	s_add_u32 s42, s10, 0x20000
	s_addc_u32 s43, s11, 0
	global_load_dwordx4 v[236:239], v203, s[42:43]
	s_add_u32 s98, s14, 0x30000
	s_addc_u32 s99, s15, 0
	global_load_dwordx4 v[128:131], v235, s[98:99] offset:16
	s_waitcnt vmcnt(16)
	v_pk_fma_f32 v[120:121], v[132:133], v[120:121], v[136:137]
	v_pk_fma_f32 v[122:123], v[134:135], v[122:123], v[138:139]
	s_add_u32 s42, s10, 0x0
	s_addc_u32 s43, s11, 0
	global_store_dwordx4 v203, v[120:123], s[42:43] offset:16
	s_add_u32 s98, s10, 0x20000
	s_addc_u32 s99, s11, 0
	global_load_dwordx4 v[132:135], v203, s[98:99] offset:16
	s_add_u32 s42, s14, 0x30200
	s_addc_u32 s43, s15, 0
	global_load_dwordx4 v[136:139], v235, s[42:43]
	s_waitcnt vmcnt(17)
	v_pk_fma_f32 v[92:93], v[140:141], v[92:93], v[144:145]
	v_pk_fma_f32 v[94:95], v[142:143], v[94:95], v[146:147]
	s_add_u32 s98, s10, 0x200
	s_addc_u32 s99, s11, 0
	global_store_dwordx4 v203, v[92:95], s[98:99]
	s_add_u32 s42, s10, 0x20200
	s_addc_u32 s43, s11, 0
	global_load_dwordx4 v[140:143], v203, s[42:43]
	s_add_u32 s98, s14, 0x30200
	s_addc_u32 s99, s15, 0
	global_load_dwordx4 v[144:147], v235, s[98:99] offset:16
	s_waitcnt vmcnt(18)
	v_pk_fma_f32 v[88:89], v[148:149], v[88:89], v[152:153]
	v_pk_fma_f32 v[90:91], v[150:151], v[90:91], v[154:155]
	s_add_u32 s42, s10, 0x200
	s_addc_u32 s43, s11, 0
	global_store_dwordx4 v203, v[88:91], s[42:43] offset:16
	s_add_u32 s98, s10, 0x20200
	s_addc_u32 s99, s11, 0
	global_load_dwordx4 v[148:151], v203, s[98:99] offset:16
	s_add_u32 s42, s14, 0x48000
	s_addc_u32 s43, s15, 0
	global_load_dwordx4 v[152:155], v235, s[42:43]
	s_waitcnt vmcnt(19)
	v_pk_fma_f32 v[116:117], v[156:157], v[116:117], v[160:161]
	v_pk_fma_f32 v[118:119], v[158:159], v[118:119], v[162:163]
	s_add_u32 s98, s10, 0x10000
	s_addc_u32 s99, s11, 0
	global_store_dwordx4 v203, v[116:119], s[98:99]
	s_add_u32 s42, s10, 0x30000
	s_addc_u32 s43, s11, 0
	global_load_dwordx4 v[156:159], v203, s[42:43]
	s_add_u32 s98, s14, 0x48000
	s_addc_u32 s99, s15, 0
	global_load_dwordx4 v[160:163], v235, s[98:99] offset:16
	s_waitcnt vmcnt(20)
	v_pk_fma_f32 v[112:113], v[164:165], v[112:113], v[168:169]
	v_pk_fma_f32 v[114:115], v[166:167], v[114:115], v[170:171]
	s_add_u32 s42, s10, 0x10000
	s_addc_u32 s43, s11, 0
	global_store_dwordx4 v203, v[112:115], s[42:43] offset:16
	s_add_u32 s98, s10, 0x30000
	s_addc_u32 s99, s11, 0
	global_load_dwordx4 v[164:167], v203, s[98:99] offset:16
	s_add_u32 s42, s14, 0x48200
	s_addc_u32 s43, s15, 0
	global_load_dwordx4 v[168:171], v235, s[42:43]
	s_waitcnt vmcnt(21)
	v_pk_fma_f32 v[84:85], v[172:173], v[84:85], v[176:177]
	v_pk_fma_f32 v[86:87], v[174:175], v[86:87], v[178:179]
	s_add_u32 s98, s10, 0x10200
	s_addc_u32 s99, s11, 0
	global_store_dwordx4 v203, v[84:87], s[98:99]
	s_add_u32 s42, s10, 0x30200
	s_addc_u32 s43, s11, 0
	global_load_dwordx4 v[172:175], v203, s[42:43]
	s_add_u32 s98, s14, 0x48200
	s_addc_u32 s99, s15, 0
	global_load_dwordx4 v[176:179], v235, s[98:99] offset:16
	s_waitcnt vmcnt(22)
	v_pk_fma_f32 v[80:81], v[180:181], v[80:81], v[206:207]
	v_pk_fma_f32 v[82:83], v[182:183], v[82:83], v[208:209]
	s_add_u32 s42, s10, 0x10200
	s_addc_u32 s43, s11, 0
	global_store_dwordx4 v203, v[80:83], s[42:43] offset:16
	s_add_u32 s98, s10, 0x30200
	s_addc_u32 s99, s11, 0
	global_load_dwordx4 v[180:183], v203, s[98:99] offset:16
	s_add_u32 s42, s14, 0xc0000
	s_addc_u32 s43, s15, 0
	global_load_dwordx4 v[206:209], v235, s[42:43]
	s_waitcnt vmcnt(22)
	v_pk_fma_f32 v[108:109], v[210:211], v[108:109], v[236:237]
	v_pk_fma_f32 v[110:111], v[212:213], v[110:111], v[238:239]
	s_add_u32 s98, s10, 0x20000
	s_addc_u32 s99, s11, 0
	global_store_dwordx4 v203, v[108:111], s[98:99]
	s_add_u32 s42, s10, 0x80000
	s_addc_u32 s43, s11, 0
	global_load_dwordx4 v[210:213], v203, s[42:43]
	s_add_u32 s98, s14, 0xc0000
	s_addc_u32 s99, s15, 0
	global_load_dwordx4 v[236:239], v235, s[98:99] offset:16
	s_waitcnt vmcnt(22)
	v_pk_fma_f32 v[104:105], v[128:129], v[104:105], v[132:133]
	v_pk_fma_f32 v[106:107], v[130:131], v[106:107], v[134:135]
	s_add_u32 s42, s10, 0x20000
	s_addc_u32 s43, s11, 0
	global_store_dwordx4 v203, v[104:107], s[42:43] offset:16
	s_add_u32 s98, s10, 0x80000
	s_addc_u32 s99, s11, 0
	global_load_dwordx4 v[128:131], v203, s[98:99] offset:16
	s_add_u32 s42, s14, 0xc0200
	s_addc_u32 s43, s15, 0
	global_load_dwordx4 v[132:135], v235, s[42:43]
	s_waitcnt vmcnt(22)
	v_pk_fma_f32 v[76:77], v[136:137], v[76:77], v[140:141]
	v_pk_fma_f32 v[78:79], v[138:139], v[78:79], v[142:143]
	s_add_u32 s98, s10, 0x20200
	s_addc_u32 s99, s11, 0
	global_store_dwordx4 v203, v[76:79], s[98:99]
	s_add_u32 s42, s10, 0x80200
	s_addc_u32 s43, s11, 0
	global_load_dwordx4 v[136:139], v203, s[42:43]
	s_add_u32 s98, s14, 0xc0200
	s_addc_u32 s99, s15, 0
	global_load_dwordx4 v[140:143], v235, s[98:99] offset:16
	s_waitcnt vmcnt(22)
	v_pk_fma_f32 v[72:73], v[144:145], v[72:73], v[148:149]
	v_pk_fma_f32 v[74:75], v[146:147], v[74:75], v[150:151]
	s_add_u32 s42, s10, 0x20200
	s_addc_u32 s43, s11, 0
	global_store_dwordx4 v203, v[72:75], s[42:43] offset:16
	s_add_u32 s98, s10, 0x80200
	s_addc_u32 s99, s11, 0
	global_load_dwordx4 v[144:147], v203, s[98:99] offset:16
	s_add_u32 s42, s14, 0xd8000
	s_addc_u32 s43, s15, 0
	global_load_dwordx4 v[148:151], v235, s[42:43]
	s_waitcnt vmcnt(22)
	v_pk_fma_f32 v[100:101], v[152:153], v[100:101], v[156:157]
	v_pk_fma_f32 v[102:103], v[154:155], v[102:103], v[158:159]
	s_add_u32 s98, s10, 0x30000
	s_addc_u32 s99, s11, 0
	global_store_dwordx4 v203, v[100:103], s[98:99]
	s_add_u32 s42, s10, 0x90000
	s_addc_u32 s43, s11, 0
	global_load_dwordx4 v[152:155], v203, s[42:43]
	s_add_u32 s98, s14, 0xd8000
	s_addc_u32 s99, s15, 0
	global_load_dwordx4 v[156:159], v235, s[98:99] offset:16
	s_waitcnt vmcnt(22)
	v_pk_fma_f32 v[96:97], v[160:161], v[96:97], v[164:165]
	v_pk_fma_f32 v[98:99], v[162:163], v[98:99], v[166:167]
	s_add_u32 s42, s10, 0x30000
	s_addc_u32 s43, s11, 0
	global_store_dwordx4 v203, v[96:99], s[42:43] offset:16
	s_add_u32 s98, s10, 0x90000
	s_addc_u32 s99, s11, 0
	global_load_dwordx4 v[160:163], v203, s[98:99] offset:16
	s_add_u32 s42, s14, 0xd8200
	s_addc_u32 s43, s15, 0
	global_load_dwordx4 v[164:167], v235, s[42:43]
	s_waitcnt vmcnt(22)
	v_pk_fma_f32 v[68:69], v[168:169], v[68:69], v[172:173]
	v_pk_fma_f32 v[70:71], v[170:171], v[70:71], v[174:175]
	s_add_u32 s98, s10, 0x30200
	s_addc_u32 s99, s11, 0
	global_store_dwordx4 v203, v[68:71], s[98:99]
	s_add_u32 s42, s10, 0x90200
	s_addc_u32 s43, s11, 0
	global_load_dwordx4 v[168:171], v203, s[42:43]
	s_add_u32 s98, s14, 0xd8200
	s_addc_u32 s99, s15, 0
	global_load_dwordx4 v[172:175], v235, s[98:99] offset:16
	s_waitcnt vmcnt(22)
	v_pk_fma_f32 v[64:65], v[176:177], v[64:65], v[180:181]
	v_pk_fma_f32 v[66:67], v[178:179], v[66:67], v[182:183]
	s_add_u32 s42, s10, 0x30200
	s_addc_u32 s43, s11, 0
	global_store_dwordx4 v203, v[64:67], s[42:43] offset:16
	s_add_u32 s98, s10, 0x90200
	s_addc_u32 s99, s11, 0
	global_load_dwordx4 v[176:179], v203, s[98:99] offset:16
	s_add_u32 s42, s14, 0xf0000
	s_addc_u32 s43, s15, 0
	global_load_dwordx4 v[180:183], v235, s[42:43]
	s_waitcnt vmcnt(22)
	v_pk_fma_f32 v[60:61], v[206:207], v[60:61], v[210:211]
	v_pk_fma_f32 v[62:63], v[208:209], v[62:63], v[212:213]
	s_add_u32 s98, s10, 0x80000
	s_addc_u32 s99, s11, 0
	global_store_dwordx4 v203, v[60:63], s[98:99]
	s_add_u32 s42, s10, 0xa0000
	s_addc_u32 s43, s11, 0
	global_load_dwordx4 v[206:209], v203, s[42:43]
	s_add_u32 s98, s14, 0xf0000
	s_addc_u32 s99, s15, 0
	global_load_dwordx4 v[210:213], v235, s[98:99] offset:16
	s_waitcnt vmcnt(22)
	v_pk_fma_f32 v[56:57], v[236:237], v[56:57], v[128:129]
	v_pk_fma_f32 v[58:59], v[238:239], v[58:59], v[130:131]
	s_add_u32 s42, s10, 0x80000
	s_addc_u32 s43, s11, 0
	global_store_dwordx4 v203, v[56:59], s[42:43] offset:16
	s_add_u32 s98, s10, 0xa0000
	s_addc_u32 s99, s11, 0
	global_load_dwordx4 v[236:239], v203, s[98:99] offset:16
	s_add_u32 s42, s14, 0xf0200
	s_addc_u32 s43, s15, 0
	global_load_dwordx4 v[128:131], v235, s[42:43]
	s_waitcnt vmcnt(22)
	v_pk_fma_f32 v[28:29], v[132:133], v[28:29], v[136:137]
	v_pk_fma_f32 v[30:31], v[134:135], v[30:31], v[138:139]
	s_add_u32 s98, s10, 0x80200
	s_addc_u32 s99, s11, 0
	global_store_dwordx4 v203, v[28:31], s[98:99]
	s_add_u32 s42, s10, 0xa0200
	s_addc_u32 s43, s11, 0
	global_load_dwordx4 v[132:135], v203, s[42:43]
	s_add_u32 s98, s14, 0xf0200
	s_addc_u32 s99, s15, 0
	global_load_dwordx4 v[136:139], v235, s[98:99] offset:16
	s_waitcnt vmcnt(22)
	v_pk_fma_f32 v[24:25], v[140:141], v[24:25], v[144:145]
	v_pk_fma_f32 v[26:27], v[142:143], v[26:27], v[146:147]
	s_add_u32 s42, s10, 0x80200
	s_addc_u32 s43, s11, 0
	global_store_dwordx4 v203, v[24:27], s[42:43] offset:16
	s_add_u32 s98, s10, 0xa0200
	s_addc_u32 s99, s11, 0
	global_load_dwordx4 v[140:143], v203, s[98:99] offset:16
	s_add_u32 s42, s14, 0x108000
	s_addc_u32 s43, s15, 0
	global_load_dwordx4 v[144:147], v235, s[42:43]
	s_waitcnt vmcnt(22)
	v_pk_fma_f32 v[52:53], v[148:149], v[52:53], v[152:153]
	v_pk_fma_f32 v[54:55], v[150:151], v[54:55], v[154:155]
	s_add_u32 s98, s10, 0x90000
	s_addc_u32 s99, s11, 0
	global_store_dwordx4 v203, v[52:55], s[98:99]
	s_add_u32 s42, s10, 0xb0000
	s_addc_u32 s43, s11, 0
	global_load_dwordx4 v[148:151], v203, s[42:43]
	s_add_u32 s98, s14, 0x108000
	s_addc_u32 s99, s15, 0
	global_load_dwordx4 v[152:155], v235, s[98:99] offset:16
	s_waitcnt vmcnt(22)
	v_pk_fma_f32 v[48:49], v[156:157], v[48:49], v[160:161]
	v_pk_fma_f32 v[50:51], v[158:159], v[50:51], v[162:163]
	s_add_u32 s42, s10, 0x90000
	s_addc_u32 s43, s11, 0
	global_store_dwordx4 v203, v[48:51], s[42:43] offset:16
	s_add_u32 s98, s10, 0xb0000
	s_addc_u32 s99, s11, 0
	global_load_dwordx4 v[156:159], v203, s[98:99] offset:16
	s_add_u32 s42, s14, 0x108200
	s_addc_u32 s43, s15, 0
	global_load_dwordx4 v[160:163], v235, s[42:43]
	s_waitcnt vmcnt(22)
	v_pk_fma_f32 v[20:21], v[164:165], v[20:21], v[168:169]
	v_pk_fma_f32 v[22:23], v[166:167], v[22:23], v[170:171]
	s_add_u32 s98, s10, 0x90200
	s_addc_u32 s99, s11, 0
	global_store_dwordx4 v203, v[20:23], s[98:99]
	s_add_u32 s42, s10, 0xb0200
	s_addc_u32 s43, s11, 0
	global_load_dwordx4 v[164:167], v203, s[42:43]
	s_add_u32 s98, s14, 0x108200
	s_addc_u32 s99, s15, 0
	global_load_dwordx4 v[168:171], v235, s[98:99] offset:16
	s_waitcnt vmcnt(22)
	v_pk_fma_f32 v[16:17], v[172:173], v[16:17], v[176:177]
	v_pk_fma_f32 v[18:19], v[174:175], v[18:19], v[178:179]
	s_add_u32 s42, s10, 0x90200
	s_addc_u32 s43, s11, 0
	global_store_dwordx4 v203, v[16:19], s[42:43] offset:16
	s_add_u32 s98, s10, 0xb0200
	s_addc_u32 s99, s11, 0
	global_load_dwordx4 v[172:175], v203, s[98:99] offset:16
	s_waitcnt vmcnt(21)
	v_pk_fma_f32 v[44:45], v[180:181], v[44:45], v[206:207]
	v_pk_fma_f32 v[46:47], v[182:183], v[46:47], v[208:209]
	s_add_u32 s42, s10, 0xa0000
	s_addc_u32 s43, s11, 0
	global_store_dwordx4 v203, v[44:47], s[42:43]
	s_waitcnt vmcnt(19)
	v_pk_fma_f32 v[40:41], v[210:211], v[40:41], v[236:237]
	v_pk_fma_f32 v[42:43], v[212:213], v[42:43], v[238:239]
	s_add_u32 s98, s10, 0xa0000
	s_addc_u32 s99, s11, 0
	global_store_dwordx4 v203, v[40:43], s[98:99] offset:16
	s_waitcnt vmcnt(17)
	v_pk_fma_f32 v[12:13], v[128:129], v[12:13], v[132:133]
	v_pk_fma_f32 v[14:15], v[130:131], v[14:15], v[134:135]
	s_add_u32 s42, s10, 0xa0200
	s_addc_u32 s43, s11, 0
	global_store_dwordx4 v203, v[12:15], s[42:43]
	s_waitcnt vmcnt(15)
	v_pk_fma_f32 v[8:9], v[136:137], v[8:9], v[140:141]
	v_pk_fma_f32 v[10:11], v[138:139], v[10:11], v[142:143]
	s_add_u32 s98, s10, 0xa0200
	s_addc_u32 s99, s11, 0
	global_store_dwordx4 v203, v[8:11], s[98:99] offset:16
	s_waitcnt vmcnt(13)
	v_pk_fma_f32 v[36:37], v[144:145], v[36:37], v[148:149]
	v_pk_fma_f32 v[38:39], v[146:147], v[38:39], v[150:151]
	s_add_u32 s42, s10, 0xb0000
	s_addc_u32 s43, s11, 0
	global_store_dwordx4 v203, v[36:39], s[42:43]
	s_waitcnt vmcnt(11)
	v_pk_fma_f32 v[32:33], v[152:153], v[32:33], v[156:157]
	v_pk_fma_f32 v[34:35], v[154:155], v[34:35], v[158:159]
	s_add_u32 s98, s10, 0xb0000
	s_addc_u32 s99, s11, 0
	global_store_dwordx4 v203, v[32:35], s[98:99] offset:16
	s_waitcnt vmcnt(9)
	v_pk_fma_f32 v[4:5], v[160:161], v[4:5], v[164:165]
	v_pk_fma_f32 v[6:7], v[162:163], v[6:7], v[166:167]
	s_add_u32 s42, s10, 0xb0200
	s_addc_u32 s43, s11, 0
	global_store_dwordx4 v203, v[4:7], s[42:43]
	s_waitcnt vmcnt(7)
	v_pk_fma_f32 v[0:1], v[168:169], v[0:1], v[172:173]
	v_pk_fma_f32 v[2:3], v[170:171], v[2:3], v[174:175]
	s_add_u32 s98, s10, 0xb0200
	s_addc_u32 s99, s11, 0
	global_store_dwordx4 v203, v[0:3], s[98:99] offset:16

.Lfs_LBB0_1561:
	v_ashrrev_i32_e32 v177, 31, v176
	v_lshlrev_b64 v[180:181], 10, v[176:177]
	s_waitcnt vmcnt(0)
	v_mov_b64_e32 v[150:151], v[38:39]
	v_mov_b64_e32 v[148:149], v[36:37]
	v_mov_b64_e32 v[146:147], v[34:35]
	v_mov_b64_e32 v[144:145], v[32:33]
	s_and_b64 vcc, exec, s[80:81]
	s_cbranch_vccnz .Lfs_LBB0_1563
	v_mul_f32_e32 v160, v140, v148
	v_mul_f32_e32 v161, v141, v149
	v_mul_f32_e32 v164, v136, v144
	v_mul_f32_e32 v165, v137, v145
	v_mov_b32_e32 v136, v185
	v_mov_b32_e32 v137, v185
	v_cvt_pk_fp8_f32 v136, v160, v161
	v_cvt_pk_fp8_f32 v137, v164, v165
	v_mul_f32_e32 v162, v142, v150
	v_mul_f32_e32 v163, v143, v151
	v_mul_f32_e32 v166, v138, v146
	v_mul_f32_e32 v167, v139, v147
	v_lshl_add_u64 v[138:139], v[180:181], 1, s[18:19]
	v_cvt_pk_fp8_f32 v136, v162, v163 op_sel:[0,0,1]
	v_cvt_pk_fp8_f32 v137, v166, v167 op_sel:[0,0,1]
	v_lshl_add_u64 v[138:139], v[200:201], 1, v[138:139]
	v_cvt_pk_bf16_f32 v140, v160, v161
	v_cvt_pk_bf16_f32 v141, v162, v163
	v_cvt_pk_bf16_f32 v142, v164, v165
	v_cvt_pk_bf16_f32 v143, v166, v167
	global_store_dwordx4 v[138:139], v[140:143], off
	v_lshl_add_u64 v[138:139], s[70:71], 0, v[180:181]
	v_lshl_add_u64 v[138:139], v[138:139], 0, v[200:201]
	global_store_dwordx2 v[138:139], v[136:137], off
